# LRU-out (EpiRes) tail round in quadrant mode: residual preload, K-loop and stores per quadrant
# speedup vs baseline: 1.1027x; 1.0198x over previous
.LBB0_384:
	s_add_u32 s26, s84, 0x7d00000
	s_addc_u32 s27, s12, 0
	s_add_u32 s28, s84, 0xc500000
	s_addc_u32 s29, s12, 0
	s_add_u32 s30, s84, 0xbd00000
	s_addc_u32 s31, s12, 0
	s_mul_i32 s66, s90, 0x2400
	s_add_u32 s34, s0, 0x2000
	s_addc_u32 s35, s1, 0
	s_lshl_b64 s[0:1], s[66:67], 2
	s_add_u32 s0, s84, s0
	s_addc_u32 s1, s12, s1
	v_bfe_u32 v16, v9, 4, 2
	s_add_u32 s40, s0, 0x10000
	v_and_b32_e32 v15, 15, v9
	v_lshlrev_b32_e32 v17, 4, v16
	v_lshlrev_b32_e32 v9, 2, v9
	s_addc_u32 s41, s1, 0
	v_lshl_or_b32 v146, s2, 6, v15
	v_lshl_or_b32 v15, v15, 6, v17
	s_lshl_b32 s0, s2, 13
	v_and_b32_e32 v9, 32, v9
	v_bitop3_b32 v17, v15, s0, v9 bitop3:0xde
	s_lshl_b32 s0, s3, 5
	s_and_b32 s5, s0, 0x60
	s_lshl_b32 s0, s5, 7
	s_add_i32 m0, s9, 0x18000
	v_lshl_add_u64 v[6:7], v[6:7], 0, s[94:95]
	v_bitop3_b32 v178, v15, s0, v9 bitop3:0xde
	s_waitcnt vmcnt(2)
	s_barrier
	global_load_lds_dwordx4 v[6:7], off
	v_lshl_add_u64 v[4:5], v[4:5], 0, s[94:95]
	s_add_i32 m0, s9, 0x1a000
	s_add_i32 s66, s9, 0x8000
	s_add_i32 s0, s9, 0xa000
	global_load_lds_dwordx4 v[4:5], off
	v_lshl_add_u64 v[0:1], v[0:1], 0, s[94:95]
	s_mov_b32 m0, s66
	s_add_u32 s2, s82, 0x80080
	global_load_lds_dwordx4 v[0:1], off
	v_lshl_add_u64 v[0:1], v[2:3], 0, s[94:95]
	s_mov_b32 m0, s0
	s_addc_u32 s3, s83, 0
	global_load_lds_dwordx4 v[0:1], off
	s_add_i32 m0, s9, 0x1c000
	v_lshl_add_u64 v[0:1], s[2:3], 0, v[160:161]
	global_load_lds_dwordx4 v[0:1], off
	v_lshl_add_u64 v[0:1], s[2:3], 0, v[162:163]
	s_add_i32 m0, s9, 0x1e000
	s_cmpk_lt_u32 s6, 0x100
	global_load_lds_dwordx4 v[0:1], off
	v_lshlrev_b32_e32 v0, 15, v12
	v_and_b32_e32 v0, 0xffff0000, v0
	v_lshl_add_u32 v0, v13, 12, v0
	v_and_b32_e32 v1, 1, v12
	v_lshl_or_b32 v0, v1, 6, v0
	v_lshl_add_u32 v164, v14, 1, v0
	v_lshlrev_b32_e32 v0, 15, v8
	v_and_b32_e32 v0, 0xffff0000, v0
	s_waitcnt vmcnt(6)
	v_lshl_add_u32 v0, v10, 12, v0
	v_and_b32_e32 v1, 1, v8
	v_lshl_or_b32 v0, v1, 6, v0
	s_cselect_b64 s[52:53], -1, 0
	s_mov_b32 s1, 0
	v_cmp_eq_u32_e64 s[36:37], 0, v16
	s_ashr_i32 s64, s13, 31
	v_lshl_or_b32 v179, v16, 2, s5
	v_mov_b32_e32 v165, v145
	v_lshl_add_u32 v166, v11, 1, v0
	v_mov_b32_e32 v167, v145
	v_add_u32_e32 v190, 0, v17
	s_barrier
	s_mov_b32 s98, 15
	s_branch .LBB0_387

.LBB0_386:
	s_mov_b32 s98, s99
	s_andn2_b64 vcc, exec, s[4:5]
	s_mov_b32 s4, s54
	s_mov_b32 s72, s68
	s_mov_b64 s[82:83], s[74:75]
	s_mov_b64 s[88:89], s[2:3]
	s_cbranch_vccz .LBB0_478
.LBB0_387:
	s_add_i32 s1, s1, 1
	v_readlane_b32 s2, v246, 8
	s_mul_i32 s2, s1, s2
	s_mul_hi_u32 s3, s1, s48
	s_add_i32 s3, s3, s2
	s_mul_i32 s2, s1, s48
	s_add_u32 s2, s2, s13
	s_addc_u32 s3, s3, s64
	s_mov_b32 s99, 15
	s_cmp_eq_u32 s1, 1
	s_cbranch_scc0 .Lq_lout_sd
	s_cmp_lt_u32 s13, 128
	s_cbranch_scc0 .Lq_lout_sd
	s_lshr_b32 s99, s13, 5
	s_and_b32 s2, s13, 31
	s_add_u32 s2, s2, 0x100
	s_mov_b32 s3, 0
	s_lshl_b32 s99, 1, s99
.Lq_lout_sd:
	v_cmp_gt_i64_e32 vcc, s[2:3], v[154:155]
	v_cmp_lt_i64_e64 s[38:39], s[2:3], v[152:153]
	s_cbranch_vccnz .LBB0_389
	s_ashr_i32 s3, s2, 31
	s_lshr_b32 s3, s3, 29
	s_add_i32 s3, s2, s3
	s_ashr_i32 s5, s3, 3
	s_and_b32 s3, s3, -8
	s_sub_i32 s2, s2, s3
	s_cmp_lt_i32 s2, 0
	s_cselect_b32 s3, 37, 36
	s_mul_i32 s2, s2, s3
	s_add_i32 s2, s2, s5
	s_ashr_i32 s3, s2, 31
	s_lshr_b32 s3, s3, 26
	s_add_i32 s3, s2, s3
	s_ashr_i32 s5, s3, 6
	s_lshl_b32 s5, s5, 3
	s_sub_i32 s6, 36, s5
	s_min_i32 s6, s6, 8
	s_abs_i32 s7, s6
	v_cvt_f32_u32_e32 v0, s7
	s_sub_i32 s49, 0, s7
	s_andn2_b32 s3, s3, 63
	s_sub_i32 s2, s2, s3
	v_rcp_iflag_f32_e32 v0, v0
	s_abs_i32 s3, s2
	s_xor_b32 s33, s2, s6
	s_ashr_i32 s33, s33, 31
	v_mul_f32_e32 v0, 0x4f7ffffe, v0
	v_cvt_u32_f32_e32 v0, v0
	s_nop 0
	v_readfirstlane_b32 s51, v0
	s_mul_i32 s49, s49, s51
	s_mul_hi_u32 s49, s51, s49
	s_add_i32 s51, s51, s49
	s_mul_hi_u32 s49, s3, s51
	s_mul_i32 s51, s49, s7
	s_sub_i32 s3, s3, s51
	s_add_i32 s54, s49, 1
	s_sub_i32 s51, s3, s7
	s_cmp_ge_u32 s3, s7
	s_cselect_b32 s49, s54, s49
	s_cselect_b32 s3, s51, s3
	s_add_i32 s51, s49, 1
	s_cmp_ge_u32 s3, s7
	s_cselect_b32 s3, s51, s49
	s_xor_b32 s3, s3, s33
	s_sub_i32 s54, s3, s33
	s_mul_i32 s3, s54, s6
	s_sub_i32 s2, s2, s3
	s_add_i32 s68, s5, s2
.LBB0_389:
	s_ashr_i32 s69, s68, 31
	s_lshl_b64 s[2:3], s[68:69], 20
	s_add_u32 s2, s22, s2
	s_addc_u32 s3, s23, s3
	s_and_b64 s[6:7], s[38:39], exec
	s_cselect_b32 s5, s3, s89
	s_cselect_b32 s6, s2, s88
	s_ashr_i32 s55, s54, 31
	s_lshl_b64 s[62:63], s[54:55], 20
	s_add_u32 s74, s14, s62
	s_addc_u32 s75, s15, s63
	s_and_b64 s[62:63], s[38:39], exec
	s_cselect_b32 s7, s75, s83
	s_cselect_b32 s33, s74, s82
	s_add_u32 s49, s82, 0x100
	s_addc_u32 s51, s83, 0
	s_add_u32 vcc_lo, s88, 0x80080
	v_mov_b32_e32 v0, 0
	s_addc_u32 vcc_hi, s89, 0
	s_mov_b32 s55, -2
	s_waitcnt lgkmcnt(0)
	v_lshrrev_b32_e32 v176, 8, v180
	v_and_b32_e32 v176, 1, v176
	v_lshlrev_b32_e32 v176, 6, v176
	v_and_b32_e32 v177, 15, v180
	v_or_b32_e32 v176, v176, v177
	v_lshlrev_b32_e32 v176, 13, v176
	v_lshrrev_b32_e32 v177, 6, v180
	v_and_b32_e32 v177, 3, v177
	v_lshl_or_b32 v176, v177, 7, v176
	v_lshrrev_b32_e32 v177, 4, v180
	v_and_b32_e32 v177, 3, v177
	v_lshl_or_b32 v176, v177, 4, v176
	s_cmp_gt_u32 s72, 31
	s_cbranch_scc1 .Lpre_lru_s
	s_lshl_b32 s32, s72, 21
	s_add_u32 s100, s26, s32
	s_addc_u32 s101, s27, 0
	s_branch .Lpre_lru_go

.Lpre_lru_go:
	s_lshl_b32 s32, s4, 10
	s_add_u32 s100, s100, s32
	s_addc_u32 s101, s101, 0
	s_cmp_eq_u32 s98, 15
	s_cbranch_scc1 .Lqp_lout_full
	v_mov_b32_e32 v0, 0
	v_mov_b32_e32 v1, 0
	v_mov_b32_e32 v2, 0
	v_mov_b32_e32 v3, 0
	v_mov_b32_e32 v4, 0
	v_mov_b32_e32 v5, 0
	v_mov_b32_e32 v6, 0
	v_mov_b32_e32 v7, 0
	v_mov_b32_e32 v8, 0
	v_mov_b32_e32 v9, 0
	v_mov_b32_e32 v10, 0
	v_mov_b32_e32 v11, 0
	v_mov_b32_e32 v12, 0
	v_mov_b32_e32 v13, 0
	v_mov_b32_e32 v14, 0
	v_mov_b32_e32 v15, 0
	v_mov_b32_e32 v16, 0
	v_mov_b32_e32 v17, 0
	v_mov_b32_e32 v18, 0
	v_mov_b32_e32 v19, 0
	v_mov_b32_e32 v20, 0
	v_mov_b32_e32 v21, 0
	v_mov_b32_e32 v22, 0
	v_mov_b32_e32 v23, 0
	v_mov_b32_e32 v24, 0
	v_mov_b32_e32 v25, 0
	v_mov_b32_e32 v26, 0
	v_mov_b32_e32 v27, 0
	v_mov_b32_e32 v36, 0
	v_mov_b32_e32 v37, 0
	v_mov_b32_e32 v38, 0
	v_mov_b32_e32 v39, 0
	v_mov_b32_e32 v48, 0
	v_mov_b32_e32 v49, 0
	v_mov_b32_e32 v50, 0
	v_mov_b32_e32 v51, 0
	v_mov_b32_e32 v52, 0
	v_mov_b32_e32 v53, 0
	v_mov_b32_e32 v54, 0
	v_mov_b32_e32 v55, 0
	v_mov_b32_e32 v56, 0
	v_mov_b32_e32 v57, 0
	v_mov_b32_e32 v58, 0
	v_mov_b32_e32 v59, 0
	v_mov_b32_e32 v60, 0
	v_mov_b32_e32 v61, 0
	v_mov_b32_e32 v62, 0
	v_mov_b32_e32 v63, 0
	v_mov_b32_e32 v64, 0
	v_mov_b32_e32 v65, 0
	v_mov_b32_e32 v66, 0
	v_mov_b32_e32 v67, 0
	v_mov_b32_e32 v68, 0
	v_mov_b32_e32 v69, 0
	v_mov_b32_e32 v70, 0
	v_mov_b32_e32 v71, 0
	v_mov_b32_e32 v72, 0
	v_mov_b32_e32 v73, 0
	v_mov_b32_e32 v74, 0
	v_mov_b32_e32 v75, 0
	v_mov_b32_e32 v76, 0
	v_mov_b32_e32 v77, 0
	v_mov_b32_e32 v78, 0
	v_mov_b32_e32 v79, 0
	v_mov_b32_e32 v80, 0
	v_mov_b32_e32 v81, 0
	v_mov_b32_e32 v82, 0
	v_mov_b32_e32 v83, 0
	v_mov_b32_e32 v84, 0
	v_mov_b32_e32 v85, 0
	v_mov_b32_e32 v86, 0
	v_mov_b32_e32 v87, 0
	v_mov_b32_e32 v88, 0
	v_mov_b32_e32 v89, 0
	v_mov_b32_e32 v90, 0
	v_mov_b32_e32 v91, 0
	v_mov_b32_e32 v92, 0
	v_mov_b32_e32 v93, 0
	v_mov_b32_e32 v94, 0
	v_mov_b32_e32 v95, 0
	v_mov_b32_e32 v96, 0
	v_mov_b32_e32 v97, 0
	v_mov_b32_e32 v98, 0
	v_mov_b32_e32 v99, 0
	v_mov_b32_e32 v100, 0
	v_mov_b32_e32 v101, 0
	v_mov_b32_e32 v102, 0
	v_mov_b32_e32 v103, 0
	v_mov_b32_e32 v104, 0
	v_mov_b32_e32 v105, 0
	v_mov_b32_e32 v106, 0
	v_mov_b32_e32 v107, 0
	v_mov_b32_e32 v108, 0
	v_mov_b32_e32 v109, 0
	v_mov_b32_e32 v110, 0
	v_mov_b32_e32 v111, 0
	v_mov_b32_e32 v112, 0
	v_mov_b32_e32 v113, 0
	v_mov_b32_e32 v114, 0
	v_mov_b32_e32 v115, 0
	v_mov_b32_e32 v116, 0
	v_mov_b32_e32 v117, 0
	v_mov_b32_e32 v118, 0
	v_mov_b32_e32 v119, 0
	v_mov_b32_e32 v120, 0
	v_mov_b32_e32 v121, 0
	v_mov_b32_e32 v122, 0
	v_mov_b32_e32 v123, 0
	v_mov_b32_e32 v124, 0
	v_mov_b32_e32 v125, 0
	v_mov_b32_e32 v126, 0
	v_mov_b32_e32 v127, 0
	v_mov_b32_e32 v128, 0
	v_mov_b32_e32 v129, 0
	v_mov_b32_e32 v130, 0
	v_mov_b32_e32 v131, 0
	v_mov_b32_e32 v132, 0
	v_mov_b32_e32 v133, 0
	v_mov_b32_e32 v134, 0
	v_mov_b32_e32 v135, 0
	v_mov_b32_e32 v136, 0
	v_mov_b32_e32 v137, 0
	v_mov_b32_e32 v138, 0
	v_mov_b32_e32 v139, 0
	v_mov_b32_e32 v140, 0
	v_mov_b32_e32 v141, 0
	v_mov_b32_e32 v142, 0
	v_mov_b32_e32 v143, 0
.Lqp_lout_full:
	s_bitcmp1_b32 s98, 0
	s_cbranch_scc0 .Lqp_lout_0
	global_load_dwordx4 v[140:143], v176, s[100:101]
.Lqp_lout_0:
	s_bitcmp1_b32 s98, 0
	s_cbranch_scc0 .Lqp_lout_1
	global_load_dwordx4 v[136:139], v176, s[100:101] offset:64
.Lqp_lout_1:
	s_bitcmp1_b32 s98, 1
	s_cbranch_scc0 .Lqp_lout_2
	global_load_dwordx4 v[132:135], v176, s[100:101] offset:512
.Lqp_lout_2:
	s_bitcmp1_b32 s98, 1
	s_cbranch_scc0 .Lqp_lout_3
	global_load_dwordx4 v[128:131], v176, s[100:101] offset:576
.Lqp_lout_3:
	s_add_u32 s100, s100, 0x20000
	s_addc_u32 s101, s101, 0
	s_bitcmp1_b32 s98, 0
	s_cbranch_scc0 .Lqp_lout_4
	global_load_dwordx4 v[124:127], v176, s[100:101]
.Lqp_lout_4:
	s_bitcmp1_b32 s98, 0
	s_cbranch_scc0 .Lqp_lout_5
	global_load_dwordx4 v[120:123], v176, s[100:101] offset:64
.Lqp_lout_5:
	s_bitcmp1_b32 s98, 1
	s_cbranch_scc0 .Lqp_lout_6
	global_load_dwordx4 v[116:119], v176, s[100:101] offset:512
.Lqp_lout_6:
	s_bitcmp1_b32 s98, 1
	s_cbranch_scc0 .Lqp_lout_7
	global_load_dwordx4 v[112:115], v176, s[100:101] offset:576
.Lqp_lout_7:
	s_add_u32 s100, s100, 0x20000
	s_addc_u32 s101, s101, 0
	s_bitcmp1_b32 s98, 0
	s_cbranch_scc0 .Lqp_lout_8
	global_load_dwordx4 v[108:111], v176, s[100:101]
.Lqp_lout_8:
	s_bitcmp1_b32 s98, 0
	s_cbranch_scc0 .Lqp_lout_9
	global_load_dwordx4 v[104:107], v176, s[100:101] offset:64
.Lqp_lout_9:
	s_bitcmp1_b32 s98, 1
	s_cbranch_scc0 .Lqp_lout_10
	global_load_dwordx4 v[100:103], v176, s[100:101] offset:512
.Lqp_lout_10:
	s_bitcmp1_b32 s98, 1
	s_cbranch_scc0 .Lqp_lout_11
	global_load_dwordx4 v[96:99], v176, s[100:101] offset:576
.Lqp_lout_11:
	s_add_u32 s100, s100, 0x20000
	s_addc_u32 s101, s101, 0
	s_bitcmp1_b32 s98, 0
	s_cbranch_scc0 .Lqp_lout_12
	global_load_dwordx4 v[92:95], v176, s[100:101]
.Lqp_lout_12:
	s_bitcmp1_b32 s98, 0
	s_cbranch_scc0 .Lqp_lout_13
	global_load_dwordx4 v[88:91], v176, s[100:101] offset:64
.Lqp_lout_13:
	s_bitcmp1_b32 s98, 1
	s_cbranch_scc0 .Lqp_lout_14
	global_load_dwordx4 v[84:87], v176, s[100:101] offset:512
.Lqp_lout_14:
	s_bitcmp1_b32 s98, 1
	s_cbranch_scc0 .Lqp_lout_15
	global_load_dwordx4 v[80:83], v176, s[100:101] offset:576
.Lqp_lout_15:
	s_add_u32 s100, s100, 0xa0000
	s_addc_u32 s101, s101, 0
	s_bitcmp1_b32 s98, 2
	s_cbranch_scc0 .Lqp_lout_16
	global_load_dwordx4 v[76:79], v176, s[100:101]
.Lqp_lout_16:
	s_bitcmp1_b32 s98, 2
	s_cbranch_scc0 .Lqp_lout_17
	global_load_dwordx4 v[72:75], v176, s[100:101] offset:64
.Lqp_lout_17:
	s_bitcmp1_b32 s98, 3
	s_cbranch_scc0 .Lqp_lout_18
	global_load_dwordx4 v[68:71], v176, s[100:101] offset:512
.Lqp_lout_18:
	s_bitcmp1_b32 s98, 3
	s_cbranch_scc0 .Lqp_lout_19
	global_load_dwordx4 v[64:67], v176, s[100:101] offset:576
.Lqp_lout_19:
	s_add_u32 s100, s100, 0x20000
	s_addc_u32 s101, s101, 0
	s_bitcmp1_b32 s98, 2
	s_cbranch_scc0 .Lqp_lout_20
	global_load_dwordx4 v[60:63], v176, s[100:101]
.Lqp_lout_20:
	s_bitcmp1_b32 s98, 2
	s_cbranch_scc0 .Lqp_lout_21
	global_load_dwordx4 v[56:59], v176, s[100:101] offset:64
.Lqp_lout_21:
	s_bitcmp1_b32 s98, 3
	s_cbranch_scc0 .Lqp_lout_22
	global_load_dwordx4 v[52:55], v176, s[100:101] offset:512
.Lqp_lout_22:
	s_bitcmp1_b32 s98, 3
	s_cbranch_scc0 .Lqp_lout_23
	global_load_dwordx4 v[48:51], v176, s[100:101] offset:576
.Lqp_lout_23:
	s_add_u32 s100, s100, 0x20000
	s_addc_u32 s101, s101, 0
	s_bitcmp1_b32 s98, 2
	s_cbranch_scc0 .Lqp_lout_24
	global_load_dwordx4 v[36:39], v176, s[100:101]
.Lqp_lout_24:
	s_bitcmp1_b32 s98, 2
	s_cbranch_scc0 .Lqp_lout_25
	global_load_dwordx4 v[24:27], v176, s[100:101] offset:64
.Lqp_lout_25:
	s_bitcmp1_b32 s98, 3
	s_cbranch_scc0 .Lqp_lout_26
	global_load_dwordx4 v[20:23], v176, s[100:101] offset:512
.Lqp_lout_26:
	s_bitcmp1_b32 s98, 3
	s_cbranch_scc0 .Lqp_lout_27
	global_load_dwordx4 v[16:19], v176, s[100:101] offset:576
.Lqp_lout_27:
	s_add_u32 s100, s100, 0x20000
	s_addc_u32 s101, s101, 0
	s_bitcmp1_b32 s98, 2
	s_cbranch_scc0 .Lqp_lout_28
	global_load_dwordx4 v[12:15], v176, s[100:101]
.Lqp_lout_28:
	s_bitcmp1_b32 s98, 2
	s_cbranch_scc0 .Lqp_lout_29
	global_load_dwordx4 v[8:11], v176, s[100:101] offset:64
.Lqp_lout_29:
	s_bitcmp1_b32 s98, 3
	s_cbranch_scc0 .Lqp_lout_30
	global_load_dwordx4 v[4:7], v176, s[100:101] offset:512
.Lqp_lout_30:
	s_bitcmp1_b32 s98, 3
	s_cbranch_scc0 .Lqp_lout_31
	global_load_dwordx4 v[0:3], v176, s[100:101] offset:576
.Lqp_lout_31:
	s_waitcnt vmcnt(0)
	s_cmp_eq_u32 s98, 15
	s_cbranch_scc0 .Lq_lout_disp
.LBB0_390:
	s_add_u32 s61, vcc_lo, 0xfff80080
	s_addc_u32 s62, vcc_hi, -1
	s_add_i32 s63, 0, 0x10000
	s_cmp_eq_u32 s55, 28
	s_cselect_b32 s89, s5, s62
	s_cselect_b32 s88, s6, s61
	s_cselect_b32 s83, s7, s51
	s_cselect_b32 s82, s33, s49
	s_add_i32 s61, 0, 0x14000
	v_add_u32_e32 v44, s63, v178
	v_add_u32_e32 v144, s61, v178
	ds_read_b128 v[28:31], v44
	ds_read_b128 v[32:35], v44 offset:1024
	ds_read_b128 v[40:43], v44 offset:2048
	ds_read_b128 v[44:47], v44 offset:3072
	ds_read_b128 v[168:171], v144
	ds_read_b128 v[172:175], v144 offset:1024
	ds_read_b128 v[192:195], v144 offset:2048
	ds_read_b128 v[196:199], v144 offset:3072
	v_lshl_add_u64 v[176:177], vcc, 0, v[166:167]
	s_add_i32 m0, s9, 0xc000
	ds_read_b128 v[200:203], v190
	ds_read_b128 v[204:207], v190 offset:1024
	ds_read_b128 v[208:211], v190 offset:2048
	ds_read_b128 v[212:215], v190 offset:3072
	ds_read_b128 v[216:219], v190 offset:4096
	ds_read_b128 v[220:223], v190 offset:5120
	ds_read_b128 v[224:227], v190 offset:6144
	ds_read_b128 v[228:231], v190 offset:7168
	global_load_lds_dwordx4 v[176:177], off
	v_lshl_add_u64 v[176:177], vcc, 0, v[164:165]
	s_add_i32 m0, s9, 0xe000
	s_nop 0
	global_load_lds_dwordx4 v[176:177], off
	s_waitcnt vmcnt(8)
	s_waitcnt lgkmcnt(0)
	s_barrier
	s_setprio 1
	s_waitcnt lgkmcnt(0)
	v_mfma_f32_16x16x32_bf16 v[140:143], v[28:31], v[200:203], v[140:143]
	v_mfma_f32_16x16x32_bf16 v[136:139], v[40:43], v[200:203], v[136:139]
	v_mfma_f32_16x16x32_bf16 v[124:127], v[28:31], v[208:211], v[124:127]
	v_mfma_f32_16x16x32_bf16 v[120:123], v[40:43], v[208:211], v[120:123]
	v_mfma_f32_16x16x32_bf16 v[108:111], v[28:31], v[216:219], v[108:111]
	v_mfma_f32_16x16x32_bf16 v[104:107], v[40:43], v[216:219], v[104:107]
	v_mfma_f32_16x16x32_bf16 v[92:95], v[28:31], v[224:227], v[92:95]
	v_mfma_f32_16x16x32_bf16 v[88:91], v[40:43], v[224:227], v[88:91]
	v_mfma_f32_16x16x32_bf16 v[140:143], v[32:35], v[204:207], v[140:143]
	v_mfma_f32_16x16x32_bf16 v[136:139], v[44:47], v[204:207], v[136:139]
	v_mfma_f32_16x16x32_bf16 v[124:127], v[32:35], v[212:215], v[124:127]
	v_mfma_f32_16x16x32_bf16 v[120:123], v[44:47], v[212:215], v[120:123]
	v_mfma_f32_16x16x32_bf16 v[108:111], v[32:35], v[220:223], v[108:111]
	v_mfma_f32_16x16x32_bf16 v[104:107], v[44:47], v[220:223], v[104:107]
	v_mfma_f32_16x16x32_bf16 v[92:95], v[32:35], v[228:231], v[92:95]
	v_mfma_f32_16x16x32_bf16 v[88:91], v[44:47], v[228:231], v[88:91]
	s_setprio 0
	s_setprio 1
	v_mfma_f32_16x16x32_bf16 v[132:135], v[168:171], v[200:203], v[132:135]
	v_mfma_f32_16x16x32_bf16 v[128:131], v[192:195], v[200:203], v[128:131]
	v_mfma_f32_16x16x32_bf16 v[116:119], v[168:171], v[208:211], v[116:119]
	v_mfma_f32_16x16x32_bf16 v[112:115], v[192:195], v[208:211], v[112:115]
	v_mfma_f32_16x16x32_bf16 v[100:103], v[168:171], v[216:219], v[100:103]
	v_mfma_f32_16x16x32_bf16 v[96:99], v[192:195], v[216:219], v[96:99]
	v_mfma_f32_16x16x32_bf16 v[84:87], v[168:171], v[224:227], v[84:87]
	v_mfma_f32_16x16x32_bf16 v[80:83], v[192:195], v[224:227], v[80:83]
	v_mfma_f32_16x16x32_bf16 v[132:135], v[172:175], v[204:207], v[132:135]
	v_mfma_f32_16x16x32_bf16 v[128:131], v[196:199], v[204:207], v[128:131]
	v_mfma_f32_16x16x32_bf16 v[116:119], v[172:175], v[212:215], v[116:119]
	v_mfma_f32_16x16x32_bf16 v[112:115], v[196:199], v[212:215], v[112:115]
	v_mfma_f32_16x16x32_bf16 v[100:103], v[172:175], v[220:223], v[100:103]
	v_mfma_f32_16x16x32_bf16 v[96:99], v[196:199], v[220:223], v[96:99]
	v_mfma_f32_16x16x32_bf16 v[84:87], v[172:175], v[228:231], v[84:87]
	v_mfma_f32_16x16x32_bf16 v[80:83], v[196:199], v[228:231], v[80:83]
	s_setprio 0
	s_barrier
	s_add_i32 s62, s63, s8
	v_lshl_add_u64 v[176:177], s[82:83], 0, v[160:161]
	s_mov_b32 m0, s62
	ds_read_b128 v[200:203], v190 offset:16384
	ds_read_b128 v[204:207], v190 offset:17408
	ds_read_b128 v[208:211], v190 offset:18432
	ds_read_b128 v[212:215], v190 offset:19456
	ds_read_b128 v[216:219], v190 offset:20480
	ds_read_b128 v[220:223], v190 offset:21504
	ds_read_b128 v[224:227], v190 offset:22528
	ds_read_b128 v[228:231], v190 offset:23552
	global_load_lds_dwordx4 v[176:177], off
	s_add_i32 m0, s62, 0x2000
	s_add_u32 s62, s82, 0x80000
	v_lshl_add_u64 v[232:233], s[82:83], 0, v[162:163]
	s_addc_u32 s63, s83, 0
	s_add_i32 s61, s61, s8
	global_load_lds_dwordx4 v[232:233], off
	v_lshl_add_u64 v[234:235], s[62:63], 0, v[160:161]
	s_mov_b32 m0, s61
	v_lshl_add_u64 v[236:237], s[88:89], 0, v[162:163]
	global_load_lds_dwordx4 v[234:235], off
	v_lshl_add_u64 v[234:235], s[62:63], 0, v[162:163]
	s_add_i32 m0, s61, 0x2000
	s_nop 0
	global_load_lds_dwordx4 v[234:235], off
	v_lshl_add_u64 v[234:235], s[88:89], 0, v[160:161]
	s_mov_b32 m0, s9
	s_nop 0
	global_load_lds_dwordx4 v[234:235], off
	s_mov_b32 m0, s73
	s_nop 0
	global_load_lds_dwordx4 v[236:237], off
	s_waitcnt vmcnt(8)
	s_waitcnt lgkmcnt(0)
	s_barrier
	s_setprio 1
	s_waitcnt lgkmcnt(0)
	v_mfma_f32_16x16x32_bf16 v[76:79], v[28:31], v[200:203], v[76:79]
	v_mfma_f32_16x16x32_bf16 v[72:75], v[40:43], v[200:203], v[72:75]
	v_mfma_f32_16x16x32_bf16 v[60:63], v[28:31], v[208:211], v[60:63]
	v_mfma_f32_16x16x32_bf16 v[56:59], v[40:43], v[208:211], v[56:59]
	v_mfma_f32_16x16x32_bf16 v[36:39], v[28:31], v[216:219], v[36:39]
	v_mfma_f32_16x16x32_bf16 v[24:27], v[40:43], v[216:219], v[24:27]
	v_mfma_f32_16x16x32_bf16 v[12:15], v[28:31], v[224:227], v[12:15]
	v_mfma_f32_16x16x32_bf16 v[8:11], v[40:43], v[224:227], v[8:11]
	v_mfma_f32_16x16x32_bf16 v[76:79], v[32:35], v[204:207], v[76:79]
	v_mfma_f32_16x16x32_bf16 v[72:75], v[44:47], v[204:207], v[72:75]
	v_mfma_f32_16x16x32_bf16 v[60:63], v[32:35], v[212:215], v[60:63]
	v_mfma_f32_16x16x32_bf16 v[56:59], v[44:47], v[212:215], v[56:59]
	v_mfma_f32_16x16x32_bf16 v[36:39], v[32:35], v[220:223], v[36:39]
	v_mfma_f32_16x16x32_bf16 v[24:27], v[44:47], v[220:223], v[24:27]
	v_mfma_f32_16x16x32_bf16 v[12:15], v[32:35], v[228:231], v[12:15]
	v_mfma_f32_16x16x32_bf16 v[8:11], v[44:47], v[228:231], v[8:11]
	s_setprio 0
	s_setprio 1
	v_mfma_f32_16x16x32_bf16 v[20:23], v[168:171], v[216:219], v[20:23]
	v_mfma_f32_16x16x32_bf16 v[16:19], v[192:195], v[216:219], v[16:19]
	v_mfma_f32_16x16x32_bf16 v[4:7], v[168:171], v[224:227], v[4:7]
	v_mfma_f32_16x16x32_bf16 v[0:3], v[192:195], v[224:227], v[0:3]
	v_mfma_f32_16x16x32_bf16 v[28:31], v[168:171], v[200:203], v[68:71]
	v_mfma_f32_16x16x32_bf16 v[32:35], v[192:195], v[200:203], v[64:67]
	v_mfma_f32_16x16x32_bf16 v[40:43], v[168:171], v[208:211], v[52:55]
	v_mfma_f32_16x16x32_bf16 v[44:47], v[192:195], v[208:211], v[48:51]
	v_mfma_f32_16x16x32_bf16 v[20:23], v[172:175], v[220:223], v[20:23]
	v_mfma_f32_16x16x32_bf16 v[16:19], v[196:199], v[220:223], v[16:19]
	v_mfma_f32_16x16x32_bf16 v[4:7], v[172:175], v[228:231], v[4:7]
	v_mfma_f32_16x16x32_bf16 v[0:3], v[196:199], v[228:231], v[0:3]
	v_mfma_f32_16x16x32_bf16 v[28:31], v[172:175], v[204:207], v[28:31]
	v_mfma_f32_16x16x32_bf16 v[32:35], v[196:199], v[204:207], v[32:35]
	v_mfma_f32_16x16x32_bf16 v[40:43], v[172:175], v[212:215], v[40:43]
	v_mfma_f32_16x16x32_bf16 v[44:47], v[196:199], v[212:215], v[44:47]
	s_setprio 0
	s_barrier
	s_add_i32 s61, 0, 0x18000
	s_add_i32 s65, 0, 0x1c000
	v_add_u32_e32 v68, s61, v178
	v_add_u32_e32 v144, s65, v178
	ds_read_b128 v[48:51], v68
	ds_read_b128 v[52:55], v68 offset:1024
	ds_read_b128 v[64:67], v68 offset:2048
	ds_read_b128 v[68:71], v68 offset:3072
	ds_read_b128 v[168:171], v144
	ds_read_b128 v[172:175], v144 offset:1024
	ds_read_b128 v[192:195], v144 offset:2048
	ds_read_b128 v[196:199], v144 offset:3072
	s_add_u32 s62, s88, 0x80000
	s_addc_u32 s63, s89, 0
	s_mov_b32 m0, s16
	v_lshl_add_u64 v[238:239], s[62:63], 0, v[160:161]
	ds_read_b128 v[200:203], v190 offset:32768
	ds_read_b128 v[204:207], v190 offset:33792
	ds_read_b128 v[208:211], v190 offset:34816
	ds_read_b128 v[212:215], v190 offset:35840
	ds_read_b128 v[216:219], v190 offset:36864
	ds_read_b128 v[220:223], v190 offset:37888
	ds_read_b128 v[224:227], v190 offset:38912
	ds_read_b128 v[228:231], v190 offset:39936
	global_load_lds_dwordx4 v[238:239], off
	v_lshl_add_u64 v[238:239], s[62:63], 0, v[162:163]
	s_mov_b32 m0, s17
	s_nop 0
	global_load_lds_dwordx4 v[238:239], off
	s_waitcnt vmcnt(8)
	s_waitcnt lgkmcnt(0)
	s_barrier
	s_setprio 1
	s_waitcnt lgkmcnt(0)
	v_mfma_f32_16x16x32_bf16 v[140:143], v[48:51], v[200:203], v[140:143]
	v_mfma_f32_16x16x32_bf16 v[136:139], v[64:67], v[200:203], v[136:139]
	v_mfma_f32_16x16x32_bf16 v[124:127], v[48:51], v[208:211], v[124:127]
	v_mfma_f32_16x16x32_bf16 v[120:123], v[64:67], v[208:211], v[120:123]
	v_mfma_f32_16x16x32_bf16 v[108:111], v[48:51], v[216:219], v[108:111]
	v_mfma_f32_16x16x32_bf16 v[104:107], v[64:67], v[216:219], v[104:107]
	v_mfma_f32_16x16x32_bf16 v[92:95], v[48:51], v[224:227], v[92:95]
	v_mfma_f32_16x16x32_bf16 v[88:91], v[64:67], v[224:227], v[88:91]
	v_mfma_f32_16x16x32_bf16 v[140:143], v[52:55], v[204:207], v[140:143]
	v_mfma_f32_16x16x32_bf16 v[136:139], v[68:71], v[204:207], v[136:139]
	v_mfma_f32_16x16x32_bf16 v[124:127], v[52:55], v[212:215], v[124:127]
	v_mfma_f32_16x16x32_bf16 v[120:123], v[68:71], v[212:215], v[120:123]
	v_mfma_f32_16x16x32_bf16 v[108:111], v[52:55], v[220:223], v[108:111]
	v_mfma_f32_16x16x32_bf16 v[104:107], v[68:71], v[220:223], v[104:107]
	v_mfma_f32_16x16x32_bf16 v[92:95], v[52:55], v[228:231], v[92:95]
	v_mfma_f32_16x16x32_bf16 v[88:91], v[68:71], v[228:231], v[88:91]
	s_setprio 0
	s_setprio 1
	v_mfma_f32_16x16x32_bf16 v[132:135], v[168:171], v[200:203], v[132:135]
	v_mfma_f32_16x16x32_bf16 v[128:131], v[192:195], v[200:203], v[128:131]
	v_mfma_f32_16x16x32_bf16 v[116:119], v[168:171], v[208:211], v[116:119]
	v_mfma_f32_16x16x32_bf16 v[112:115], v[192:195], v[208:211], v[112:115]
	v_mfma_f32_16x16x32_bf16 v[100:103], v[168:171], v[216:219], v[100:103]
	v_mfma_f32_16x16x32_bf16 v[96:99], v[192:195], v[216:219], v[96:99]
	v_mfma_f32_16x16x32_bf16 v[84:87], v[168:171], v[224:227], v[84:87]
	v_mfma_f32_16x16x32_bf16 v[80:83], v[192:195], v[224:227], v[80:83]
	v_mfma_f32_16x16x32_bf16 v[132:135], v[172:175], v[204:207], v[132:135]
	v_mfma_f32_16x16x32_bf16 v[128:131], v[196:199], v[204:207], v[128:131]
	v_mfma_f32_16x16x32_bf16 v[116:119], v[172:175], v[212:215], v[116:119]
	v_mfma_f32_16x16x32_bf16 v[112:115], v[196:199], v[212:215], v[112:115]
	v_mfma_f32_16x16x32_bf16 v[100:103], v[172:175], v[220:223], v[100:103]
	v_mfma_f32_16x16x32_bf16 v[96:99], v[196:199], v[220:223], v[96:99]
	v_mfma_f32_16x16x32_bf16 v[84:87], v[172:175], v[228:231], v[84:87]
	v_mfma_f32_16x16x32_bf16 v[80:83], v[196:199], v[228:231], v[80:83]
	s_setprio 0
	s_barrier
	s_add_i32 s61, s61, s8
	v_lshl_add_u64 v[176:177], v[176:177], 0, s[94:95]
	s_mov_b32 m0, s61
	ds_read_b128 v[200:203], v190 offset:49152
	ds_read_b128 v[204:207], v190 offset:50176
	ds_read_b128 v[208:211], v190 offset:51200
	ds_read_b128 v[212:215], v190 offset:52224
	ds_read_b128 v[216:219], v190 offset:53248
	ds_read_b128 v[220:223], v190 offset:54272
	ds_read_b128 v[224:227], v190 offset:55296
	ds_read_b128 v[228:231], v190 offset:56320
	global_load_lds_dwordx4 v[176:177], off
	s_add_i32 m0, s61, 0x2000
	s_add_u32 s62, s82, 0x80080
	v_lshl_add_u64 v[176:177], v[232:233], 0, s[94:95]
	s_addc_u32 s63, s83, 0
	s_add_i32 s61, s65, s8
	global_load_lds_dwordx4 v[176:177], off
	v_lshl_add_u64 v[176:177], s[62:63], 0, v[160:161]
	s_mov_b32 m0, s61
	s_nop 0
	global_load_lds_dwordx4 v[176:177], off
	v_lshl_add_u64 v[176:177], s[62:63], 0, v[162:163]
	s_add_i32 m0, s61, 0x2000
	s_nop 0
	global_load_lds_dwordx4 v[176:177], off
	v_lshl_add_u64 v[176:177], v[234:235], 0, s[94:95]
	s_mov_b32 m0, s66
	s_nop 0
	global_load_lds_dwordx4 v[176:177], off
	v_lshl_add_u64 v[176:177], v[236:237], 0, s[94:95]
	s_mov_b32 m0, s0
	s_nop 0
	global_load_lds_dwordx4 v[176:177], off
	s_waitcnt vmcnt(8)
	s_waitcnt lgkmcnt(0)
	s_barrier
	s_setprio 1
	s_waitcnt lgkmcnt(0)
	v_mfma_f32_16x16x32_bf16 v[76:79], v[48:51], v[200:203], v[76:79]
	v_mfma_f32_16x16x32_bf16 v[72:75], v[64:67], v[200:203], v[72:75]
	v_mfma_f32_16x16x32_bf16 v[60:63], v[48:51], v[208:211], v[60:63]
	v_mfma_f32_16x16x32_bf16 v[56:59], v[64:67], v[208:211], v[56:59]
	v_mfma_f32_16x16x32_bf16 v[36:39], v[48:51], v[216:219], v[36:39]
	v_mfma_f32_16x16x32_bf16 v[24:27], v[64:67], v[216:219], v[24:27]
	v_mfma_f32_16x16x32_bf16 v[12:15], v[48:51], v[224:227], v[12:15]
	v_mfma_f32_16x16x32_bf16 v[8:11], v[64:67], v[224:227], v[8:11]
	v_mfma_f32_16x16x32_bf16 v[76:79], v[52:55], v[204:207], v[76:79]
	v_mfma_f32_16x16x32_bf16 v[72:75], v[68:71], v[204:207], v[72:75]
	v_mfma_f32_16x16x32_bf16 v[60:63], v[52:55], v[212:215], v[60:63]
	v_mfma_f32_16x16x32_bf16 v[56:59], v[68:71], v[212:215], v[56:59]
	v_mfma_f32_16x16x32_bf16 v[36:39], v[52:55], v[220:223], v[36:39]
	v_mfma_f32_16x16x32_bf16 v[24:27], v[68:71], v[220:223], v[24:27]
	v_mfma_f32_16x16x32_bf16 v[12:15], v[52:55], v[228:231], v[12:15]
	v_mfma_f32_16x16x32_bf16 v[8:11], v[68:71], v[228:231], v[8:11]
	s_setprio 0
	s_setprio 1
	v_mfma_f32_16x16x32_bf16 v[28:31], v[168:171], v[200:203], v[28:31]
	v_mfma_f32_16x16x32_bf16 v[68:71], v[172:175], v[204:207], v[28:31]
	v_mfma_f32_16x16x32_bf16 v[28:31], v[192:195], v[200:203], v[32:35]
	v_mfma_f32_16x16x32_bf16 v[64:67], v[196:199], v[204:207], v[28:31]
	v_mfma_f32_16x16x32_bf16 v[28:31], v[168:171], v[208:211], v[40:43]
	v_mfma_f32_16x16x32_bf16 v[52:55], v[172:175], v[212:215], v[28:31]
	v_mfma_f32_16x16x32_bf16 v[28:31], v[192:195], v[208:211], v[44:47]
	v_mfma_f32_16x16x32_bf16 v[20:23], v[168:171], v[216:219], v[20:23]
	v_mfma_f32_16x16x32_bf16 v[16:19], v[192:195], v[216:219], v[16:19]
	v_mfma_f32_16x16x32_bf16 v[4:7], v[168:171], v[224:227], v[4:7]
	v_mfma_f32_16x16x32_bf16 v[0:3], v[192:195], v[224:227], v[0:3]
	v_mfma_f32_16x16x32_bf16 v[48:51], v[196:199], v[212:215], v[28:31]
	v_mfma_f32_16x16x32_bf16 v[20:23], v[172:175], v[220:223], v[20:23]
	v_mfma_f32_16x16x32_bf16 v[16:19], v[196:199], v[220:223], v[16:19]
	v_mfma_f32_16x16x32_bf16 v[4:7], v[172:175], v[228:231], v[4:7]
	v_mfma_f32_16x16x32_bf16 v[0:3], v[196:199], v[228:231], v[0:3]
	s_setprio 0
	s_barrier
	s_add_i32 s55, s55, 2
	s_add_u32 s49, s49, 0x100
	s_addc_u32 s51, s51, 0
	s_add_u32 vcc_lo, vcc_lo, 0x100
	s_addc_u32 vcc_hi, vcc_hi, 0
	s_cmp_gt_u32 s55, 29
	s_cbranch_scc0 .LBB0_390
	s_branch .Lq_lout_exit
.Lq_lout_disp:
	s_cmp_eq_u32 s98, 1
	s_cbranch_scc1 .Lq_lout_0_loop
	s_cmp_eq_u32 s98, 2
	s_cbranch_scc1 .Lq_lout_1_loop
	s_cmp_eq_u32 s98, 4
	s_cbranch_scc1 .Lq_lout_2_loop
	s_branch .Lq_lout_3_loop
.Lq_lout_0_loop:
	s_add_u32 s88, s88, 0x100
	s_addc_u32 s89, s89, 0
	s_add_u32 s82, s82, 0x100
	s_addc_u32 s83, s83, 0
	s_waitcnt vmcnt(0)
	s_barrier
	s_barrier
	v_lshl_add_u64 v[176:177], s[88:89], 0, v[160:161]
	s_add_i32 m0, s9, 0x4000
	v_lshl_add_u64 v[232:233], s[88:89], 0, v[162:163]
	global_load_lds_dwordx4 v[176:177], off
	s_add_i32 m0, s9, 0x6000
	v_lshl_add_u64 v[234:235], s[82:83], 0, v[160:161]
	global_load_lds_dwordx4 v[232:233], off
	s_add_i32 m0, s9, 0x14000
	v_lshl_add_u64 v[236:237], s[82:83], 0, v[162:163]
	global_load_lds_dwordx4 v[234:235], off
	s_add_i32 m0, s9, 0x16000
	s_add_u32 s88, s88, 0x80
	s_addc_u32 s89, s89, 0
	global_load_lds_dwordx4 v[236:237], off
	s_add_u32 s82, s82, 0x80
	s_addc_u32 s83, s83, 0
	s_mov_b32 s55, 0
.Lq_lout_0_k:
	v_lshl_add_u64 v[176:177], s[88:89], 0, v[160:161]
	s_add_i32 m0, s9, 0xc000
	v_lshl_add_u64 v[232:233], s[88:89], 0, v[162:163]
	global_load_lds_dwordx4 v[176:177], off
	s_add_i32 m0, s9, 0xe000
	v_lshl_add_u64 v[234:235], s[82:83], 0, v[160:161]
	global_load_lds_dwordx4 v[232:233], off
	s_add_i32 m0, s9, 0x1c000
	v_lshl_add_u64 v[236:237], s[82:83], 0, v[162:163]
	global_load_lds_dwordx4 v[234:235], off
	s_add_i32 m0, s9, 0x1e000
	s_add_u32 s88, s88, 0x80
	s_addc_u32 s89, s89, 0
	global_load_lds_dwordx4 v[236:237], off
	s_add_u32 s82, s82, 0x80
	s_addc_u32 s83, s83, 0
	v_add_u32_e32 v144, 0x10000, v178
	ds_read_b128 v[200:203], v190 offset:0
	ds_read_b128 v[204:207], v190 offset:1024
	ds_read_b128 v[208:211], v190 offset:2048
	ds_read_b128 v[212:215], v190 offset:3072
	ds_read_b128 v[216:219], v190 offset:4096
	ds_read_b128 v[220:223], v190 offset:5120
	ds_read_b128 v[224:227], v190 offset:6144
	ds_read_b128 v[228:231], v190 offset:7168
	ds_read_b128 v[28:31], v144
	ds_read_b128 v[32:35], v144 offset:1024
	ds_read_b128 v[40:43], v144 offset:2048
	ds_read_b128 v[44:47], v144 offset:3072
	s_waitcnt vmcnt(8)
	s_waitcnt lgkmcnt(0)
	s_barrier
	s_setprio 1
	v_mfma_f32_16x16x32_bf16 v[140:143], v[28:31], v[200:203], v[140:143]
	v_mfma_f32_16x16x32_bf16 v[136:139], v[40:43], v[200:203], v[136:139]
	v_mfma_f32_16x16x32_bf16 v[124:127], v[28:31], v[208:211], v[124:127]
	v_mfma_f32_16x16x32_bf16 v[120:123], v[40:43], v[208:211], v[120:123]
	v_mfma_f32_16x16x32_bf16 v[108:111], v[28:31], v[216:219], v[108:111]
	v_mfma_f32_16x16x32_bf16 v[104:107], v[40:43], v[216:219], v[104:107]
	v_mfma_f32_16x16x32_bf16 v[92:95], v[28:31], v[224:227], v[92:95]
	v_mfma_f32_16x16x32_bf16 v[88:91], v[40:43], v[224:227], v[88:91]
	v_mfma_f32_16x16x32_bf16 v[140:143], v[32:35], v[204:207], v[140:143]
	v_mfma_f32_16x16x32_bf16 v[136:139], v[44:47], v[204:207], v[136:139]
	v_mfma_f32_16x16x32_bf16 v[124:127], v[32:35], v[212:215], v[124:127]
	v_mfma_f32_16x16x32_bf16 v[120:123], v[44:47], v[212:215], v[120:123]
	v_mfma_f32_16x16x32_bf16 v[108:111], v[32:35], v[220:223], v[108:111]
	v_mfma_f32_16x16x32_bf16 v[104:107], v[44:47], v[220:223], v[104:107]
	v_mfma_f32_16x16x32_bf16 v[92:95], v[32:35], v[228:231], v[92:95]
	v_mfma_f32_16x16x32_bf16 v[88:91], v[44:47], v[228:231], v[88:91]
	s_setprio 0
	s_barrier
	v_lshl_add_u64 v[176:177], s[88:89], 0, v[160:161]
	s_add_i32 m0, s9, 0x0
	v_lshl_add_u64 v[232:233], s[88:89], 0, v[162:163]
	global_load_lds_dwordx4 v[176:177], off
	s_add_i32 m0, s9, 0x2000
	v_lshl_add_u64 v[234:235], s[82:83], 0, v[160:161]
	global_load_lds_dwordx4 v[232:233], off
	s_add_i32 m0, s9, 0x10000
	v_lshl_add_u64 v[236:237], s[82:83], 0, v[162:163]
	global_load_lds_dwordx4 v[234:235], off
	s_add_i32 m0, s9, 0x12000
	s_add_u32 s88, s88, 0x80
	s_addc_u32 s89, s89, 0
	global_load_lds_dwordx4 v[236:237], off
	s_add_u32 s82, s82, 0x80
	s_addc_u32 s83, s83, 0
	v_add_u32_e32 v144, 0x18000, v178
	ds_read_b128 v[200:203], v190 offset:32768
	ds_read_b128 v[204:207], v190 offset:33792
	ds_read_b128 v[208:211], v190 offset:34816
	ds_read_b128 v[212:215], v190 offset:35840
	ds_read_b128 v[216:219], v190 offset:36864
	ds_read_b128 v[220:223], v190 offset:37888
	ds_read_b128 v[224:227], v190 offset:38912
	ds_read_b128 v[228:231], v190 offset:39936
	ds_read_b128 v[28:31], v144
	ds_read_b128 v[32:35], v144 offset:1024
	ds_read_b128 v[40:43], v144 offset:2048
	ds_read_b128 v[44:47], v144 offset:3072
	s_waitcnt vmcnt(8)
	s_waitcnt lgkmcnt(0)
	s_barrier
	s_setprio 1
	v_mfma_f32_16x16x32_bf16 v[140:143], v[28:31], v[200:203], v[140:143]
	v_mfma_f32_16x16x32_bf16 v[136:139], v[40:43], v[200:203], v[136:139]
	v_mfma_f32_16x16x32_bf16 v[124:127], v[28:31], v[208:211], v[124:127]
	v_mfma_f32_16x16x32_bf16 v[120:123], v[40:43], v[208:211], v[120:123]
	v_mfma_f32_16x16x32_bf16 v[108:111], v[28:31], v[216:219], v[108:111]
	v_mfma_f32_16x16x32_bf16 v[104:107], v[40:43], v[216:219], v[104:107]
	v_mfma_f32_16x16x32_bf16 v[92:95], v[28:31], v[224:227], v[92:95]
	v_mfma_f32_16x16x32_bf16 v[88:91], v[40:43], v[224:227], v[88:91]
	v_mfma_f32_16x16x32_bf16 v[140:143], v[32:35], v[204:207], v[140:143]
	v_mfma_f32_16x16x32_bf16 v[136:139], v[44:47], v[204:207], v[136:139]
	v_mfma_f32_16x16x32_bf16 v[124:127], v[32:35], v[212:215], v[124:127]
	v_mfma_f32_16x16x32_bf16 v[120:123], v[44:47], v[212:215], v[120:123]
	v_mfma_f32_16x16x32_bf16 v[108:111], v[32:35], v[220:223], v[108:111]
	v_mfma_f32_16x16x32_bf16 v[104:107], v[44:47], v[220:223], v[104:107]
	v_mfma_f32_16x16x32_bf16 v[92:95], v[32:35], v[228:231], v[92:95]
	v_mfma_f32_16x16x32_bf16 v[88:91], v[44:47], v[228:231], v[88:91]
	s_setprio 0
	s_barrier
	v_lshl_add_u64 v[176:177], s[88:89], 0, v[160:161]
	s_add_i32 m0, s9, 0x8000
	v_lshl_add_u64 v[232:233], s[88:89], 0, v[162:163]
	global_load_lds_dwordx4 v[176:177], off
	s_add_i32 m0, s9, 0xa000
	v_lshl_add_u64 v[234:235], s[82:83], 0, v[160:161]
	global_load_lds_dwordx4 v[232:233], off
	s_add_i32 m0, s9, 0x18000
	v_lshl_add_u64 v[236:237], s[82:83], 0, v[162:163]
	global_load_lds_dwordx4 v[234:235], off
	s_add_i32 m0, s9, 0x1a000
	s_add_u32 s88, s88, 0x80
	s_addc_u32 s89, s89, 0
	global_load_lds_dwordx4 v[236:237], off
	s_add_u32 s82, s82, 0x80
	s_addc_u32 s83, s83, 0
	v_add_u32_e32 v144, 0x14000, v178
	ds_read_b128 v[200:203], v190 offset:16384
	ds_read_b128 v[204:207], v190 offset:17408
	ds_read_b128 v[208:211], v190 offset:18432
	ds_read_b128 v[212:215], v190 offset:19456
	ds_read_b128 v[216:219], v190 offset:20480
	ds_read_b128 v[220:223], v190 offset:21504
	ds_read_b128 v[224:227], v190 offset:22528
	ds_read_b128 v[228:231], v190 offset:23552
	ds_read_b128 v[28:31], v144
	ds_read_b128 v[32:35], v144 offset:1024
	ds_read_b128 v[40:43], v144 offset:2048
	ds_read_b128 v[44:47], v144 offset:3072
	s_waitcnt vmcnt(8)
	s_waitcnt lgkmcnt(0)
	s_barrier
	s_setprio 1
	v_mfma_f32_16x16x32_bf16 v[140:143], v[28:31], v[200:203], v[140:143]
	v_mfma_f32_16x16x32_bf16 v[136:139], v[40:43], v[200:203], v[136:139]
	v_mfma_f32_16x16x32_bf16 v[124:127], v[28:31], v[208:211], v[124:127]
	v_mfma_f32_16x16x32_bf16 v[120:123], v[40:43], v[208:211], v[120:123]
	v_mfma_f32_16x16x32_bf16 v[108:111], v[28:31], v[216:219], v[108:111]
	v_mfma_f32_16x16x32_bf16 v[104:107], v[40:43], v[216:219], v[104:107]
	v_mfma_f32_16x16x32_bf16 v[92:95], v[28:31], v[224:227], v[92:95]
	v_mfma_f32_16x16x32_bf16 v[88:91], v[40:43], v[224:227], v[88:91]
	v_mfma_f32_16x16x32_bf16 v[140:143], v[32:35], v[204:207], v[140:143]
	v_mfma_f32_16x16x32_bf16 v[136:139], v[44:47], v[204:207], v[136:139]
	v_mfma_f32_16x16x32_bf16 v[124:127], v[32:35], v[212:215], v[124:127]
	v_mfma_f32_16x16x32_bf16 v[120:123], v[44:47], v[212:215], v[120:123]
	v_mfma_f32_16x16x32_bf16 v[108:111], v[32:35], v[220:223], v[108:111]
	v_mfma_f32_16x16x32_bf16 v[104:107], v[44:47], v[220:223], v[104:107]
	v_mfma_f32_16x16x32_bf16 v[92:95], v[32:35], v[228:231], v[92:95]
	v_mfma_f32_16x16x32_bf16 v[88:91], v[44:47], v[228:231], v[88:91]
	s_setprio 0
	s_barrier
	v_lshl_add_u64 v[176:177], s[88:89], 0, v[160:161]
	s_add_i32 m0, s9, 0x4000
	v_lshl_add_u64 v[232:233], s[88:89], 0, v[162:163]
	global_load_lds_dwordx4 v[176:177], off
	s_add_i32 m0, s9, 0x6000
	v_lshl_add_u64 v[234:235], s[82:83], 0, v[160:161]
	global_load_lds_dwordx4 v[232:233], off
	s_add_i32 m0, s9, 0x14000
	v_lshl_add_u64 v[236:237], s[82:83], 0, v[162:163]
	global_load_lds_dwordx4 v[234:235], off
	s_add_i32 m0, s9, 0x16000
	s_add_u32 s88, s88, 0x80
	s_addc_u32 s89, s89, 0
	global_load_lds_dwordx4 v[236:237], off
	s_add_u32 s82, s82, 0x80
	s_addc_u32 s83, s83, 0
	v_add_u32_e32 v144, 0x1c000, v178
	ds_read_b128 v[200:203], v190 offset:49152
	ds_read_b128 v[204:207], v190 offset:50176
	ds_read_b128 v[208:211], v190 offset:51200
	ds_read_b128 v[212:215], v190 offset:52224
	ds_read_b128 v[216:219], v190 offset:53248
	ds_read_b128 v[220:223], v190 offset:54272
	ds_read_b128 v[224:227], v190 offset:55296
	ds_read_b128 v[228:231], v190 offset:56320
	ds_read_b128 v[28:31], v144
	ds_read_b128 v[32:35], v144 offset:1024
	ds_read_b128 v[40:43], v144 offset:2048
	ds_read_b128 v[44:47], v144 offset:3072
	s_waitcnt vmcnt(8)
	s_waitcnt lgkmcnt(0)
	s_barrier
	s_setprio 1
	v_mfma_f32_16x16x32_bf16 v[140:143], v[28:31], v[200:203], v[140:143]
	v_mfma_f32_16x16x32_bf16 v[136:139], v[40:43], v[200:203], v[136:139]
	v_mfma_f32_16x16x32_bf16 v[124:127], v[28:31], v[208:211], v[124:127]
	v_mfma_f32_16x16x32_bf16 v[120:123], v[40:43], v[208:211], v[120:123]
	v_mfma_f32_16x16x32_bf16 v[108:111], v[28:31], v[216:219], v[108:111]
	v_mfma_f32_16x16x32_bf16 v[104:107], v[40:43], v[216:219], v[104:107]
	v_mfma_f32_16x16x32_bf16 v[92:95], v[28:31], v[224:227], v[92:95]
	v_mfma_f32_16x16x32_bf16 v[88:91], v[40:43], v[224:227], v[88:91]
	v_mfma_f32_16x16x32_bf16 v[140:143], v[32:35], v[204:207], v[140:143]
	v_mfma_f32_16x16x32_bf16 v[136:139], v[44:47], v[204:207], v[136:139]
	v_mfma_f32_16x16x32_bf16 v[124:127], v[32:35], v[212:215], v[124:127]
	v_mfma_f32_16x16x32_bf16 v[120:123], v[44:47], v[212:215], v[120:123]
	v_mfma_f32_16x16x32_bf16 v[108:111], v[32:35], v[220:223], v[108:111]
	v_mfma_f32_16x16x32_bf16 v[104:107], v[44:47], v[220:223], v[104:107]
	v_mfma_f32_16x16x32_bf16 v[92:95], v[32:35], v[228:231], v[92:95]
	v_mfma_f32_16x16x32_bf16 v[88:91], v[44:47], v[228:231], v[88:91]
	s_setprio 0
	s_barrier
	s_add_i32 s55, s55, 1
	s_cmp_lt_u32 s55, 7
	s_cbranch_scc1 .Lq_lout_0_k
	v_lshl_add_u64 v[176:177], s[88:89], 0, v[160:161]
	s_add_i32 m0, s9, 0xc000
	v_lshl_add_u64 v[232:233], s[88:89], 0, v[162:163]
	global_load_lds_dwordx4 v[176:177], off
	s_add_i32 m0, s9, 0xe000
	v_lshl_add_u64 v[234:235], s[82:83], 0, v[160:161]
	global_load_lds_dwordx4 v[232:233], off
	s_add_i32 m0, s9, 0x1c000
	v_lshl_add_u64 v[236:237], s[82:83], 0, v[162:163]
	global_load_lds_dwordx4 v[234:235], off
	s_add_i32 m0, s9, 0x1e000
	s_add_u32 s88, s88, 0x80
	s_addc_u32 s89, s89, 0
	global_load_lds_dwordx4 v[236:237], off
	s_add_u32 s82, s82, 0x80
	s_addc_u32 s83, s83, 0
	v_add_u32_e32 v144, 0x10000, v178
	ds_read_b128 v[200:203], v190 offset:0
	ds_read_b128 v[204:207], v190 offset:1024
	ds_read_b128 v[208:211], v190 offset:2048
	ds_read_b128 v[212:215], v190 offset:3072
	ds_read_b128 v[216:219], v190 offset:4096
	ds_read_b128 v[220:223], v190 offset:5120
	ds_read_b128 v[224:227], v190 offset:6144
	ds_read_b128 v[228:231], v190 offset:7168
	ds_read_b128 v[28:31], v144
	ds_read_b128 v[32:35], v144 offset:1024
	ds_read_b128 v[40:43], v144 offset:2048
	ds_read_b128 v[44:47], v144 offset:3072
	s_waitcnt vmcnt(8)
	s_waitcnt lgkmcnt(0)
	s_barrier
	s_setprio 1
	v_mfma_f32_16x16x32_bf16 v[140:143], v[28:31], v[200:203], v[140:143]
	v_mfma_f32_16x16x32_bf16 v[136:139], v[40:43], v[200:203], v[136:139]
	v_mfma_f32_16x16x32_bf16 v[124:127], v[28:31], v[208:211], v[124:127]
	v_mfma_f32_16x16x32_bf16 v[120:123], v[40:43], v[208:211], v[120:123]
	v_mfma_f32_16x16x32_bf16 v[108:111], v[28:31], v[216:219], v[108:111]
	v_mfma_f32_16x16x32_bf16 v[104:107], v[40:43], v[216:219], v[104:107]
	v_mfma_f32_16x16x32_bf16 v[92:95], v[28:31], v[224:227], v[92:95]
	v_mfma_f32_16x16x32_bf16 v[88:91], v[40:43], v[224:227], v[88:91]
	v_mfma_f32_16x16x32_bf16 v[140:143], v[32:35], v[204:207], v[140:143]
	v_mfma_f32_16x16x32_bf16 v[136:139], v[44:47], v[204:207], v[136:139]
	v_mfma_f32_16x16x32_bf16 v[124:127], v[32:35], v[212:215], v[124:127]
	v_mfma_f32_16x16x32_bf16 v[120:123], v[44:47], v[212:215], v[120:123]
	v_mfma_f32_16x16x32_bf16 v[108:111], v[32:35], v[220:223], v[108:111]
	v_mfma_f32_16x16x32_bf16 v[104:107], v[44:47], v[220:223], v[104:107]
	v_mfma_f32_16x16x32_bf16 v[92:95], v[32:35], v[228:231], v[92:95]
	v_mfma_f32_16x16x32_bf16 v[88:91], v[44:47], v[228:231], v[88:91]
	s_setprio 0
	s_barrier
	v_add_u32_e32 v144, 0x18000, v178
	ds_read_b128 v[200:203], v190 offset:32768
	ds_read_b128 v[204:207], v190 offset:33792
	ds_read_b128 v[208:211], v190 offset:34816
	ds_read_b128 v[212:215], v190 offset:35840
	ds_read_b128 v[216:219], v190 offset:36864
	ds_read_b128 v[220:223], v190 offset:37888
	ds_read_b128 v[224:227], v190 offset:38912
	ds_read_b128 v[228:231], v190 offset:39936
	ds_read_b128 v[28:31], v144
	ds_read_b128 v[32:35], v144 offset:1024
	ds_read_b128 v[40:43], v144 offset:2048
	ds_read_b128 v[44:47], v144 offset:3072
	s_waitcnt vmcnt(4)
	s_waitcnt lgkmcnt(0)
	s_barrier
	s_setprio 1
	v_mfma_f32_16x16x32_bf16 v[140:143], v[28:31], v[200:203], v[140:143]
	v_mfma_f32_16x16x32_bf16 v[136:139], v[40:43], v[200:203], v[136:139]
	v_mfma_f32_16x16x32_bf16 v[124:127], v[28:31], v[208:211], v[124:127]
	v_mfma_f32_16x16x32_bf16 v[120:123], v[40:43], v[208:211], v[120:123]
	v_mfma_f32_16x16x32_bf16 v[108:111], v[28:31], v[216:219], v[108:111]
	v_mfma_f32_16x16x32_bf16 v[104:107], v[40:43], v[216:219], v[104:107]
	v_mfma_f32_16x16x32_bf16 v[92:95], v[28:31], v[224:227], v[92:95]
	v_mfma_f32_16x16x32_bf16 v[88:91], v[40:43], v[224:227], v[88:91]
	v_mfma_f32_16x16x32_bf16 v[140:143], v[32:35], v[204:207], v[140:143]
	v_mfma_f32_16x16x32_bf16 v[136:139], v[44:47], v[204:207], v[136:139]
	v_mfma_f32_16x16x32_bf16 v[124:127], v[32:35], v[212:215], v[124:127]
	v_mfma_f32_16x16x32_bf16 v[120:123], v[44:47], v[212:215], v[120:123]
	v_mfma_f32_16x16x32_bf16 v[108:111], v[32:35], v[220:223], v[108:111]
	v_mfma_f32_16x16x32_bf16 v[104:107], v[44:47], v[220:223], v[104:107]
	v_mfma_f32_16x16x32_bf16 v[92:95], v[32:35], v[228:231], v[92:95]
	v_mfma_f32_16x16x32_bf16 v[88:91], v[44:47], v[228:231], v[88:91]
	s_setprio 0
	s_barrier
	v_add_u32_e32 v144, 0x14000, v178
	ds_read_b128 v[200:203], v190 offset:16384
	ds_read_b128 v[204:207], v190 offset:17408
	ds_read_b128 v[208:211], v190 offset:18432
	ds_read_b128 v[212:215], v190 offset:19456
	ds_read_b128 v[216:219], v190 offset:20480
	ds_read_b128 v[220:223], v190 offset:21504
	ds_read_b128 v[224:227], v190 offset:22528
	ds_read_b128 v[228:231], v190 offset:23552
	ds_read_b128 v[28:31], v144
	ds_read_b128 v[32:35], v144 offset:1024
	ds_read_b128 v[40:43], v144 offset:2048
	ds_read_b128 v[44:47], v144 offset:3072
	s_waitcnt vmcnt(0)
	s_waitcnt lgkmcnt(0)
	s_barrier
	s_setprio 1
	v_mfma_f32_16x16x32_bf16 v[140:143], v[28:31], v[200:203], v[140:143]
	v_mfma_f32_16x16x32_bf16 v[136:139], v[40:43], v[200:203], v[136:139]
	v_mfma_f32_16x16x32_bf16 v[124:127], v[28:31], v[208:211], v[124:127]
	v_mfma_f32_16x16x32_bf16 v[120:123], v[40:43], v[208:211], v[120:123]
	v_mfma_f32_16x16x32_bf16 v[108:111], v[28:31], v[216:219], v[108:111]
	v_mfma_f32_16x16x32_bf16 v[104:107], v[40:43], v[216:219], v[104:107]
	v_mfma_f32_16x16x32_bf16 v[92:95], v[28:31], v[224:227], v[92:95]
	v_mfma_f32_16x16x32_bf16 v[88:91], v[40:43], v[224:227], v[88:91]
	v_mfma_f32_16x16x32_bf16 v[140:143], v[32:35], v[204:207], v[140:143]
	v_mfma_f32_16x16x32_bf16 v[136:139], v[44:47], v[204:207], v[136:139]
	v_mfma_f32_16x16x32_bf16 v[124:127], v[32:35], v[212:215], v[124:127]
	v_mfma_f32_16x16x32_bf16 v[120:123], v[44:47], v[212:215], v[120:123]
	v_mfma_f32_16x16x32_bf16 v[108:111], v[32:35], v[220:223], v[108:111]
	v_mfma_f32_16x16x32_bf16 v[104:107], v[44:47], v[220:223], v[104:107]
	v_mfma_f32_16x16x32_bf16 v[92:95], v[32:35], v[228:231], v[92:95]
	v_mfma_f32_16x16x32_bf16 v[88:91], v[44:47], v[228:231], v[88:91]
	s_setprio 0
	s_barrier
	v_add_u32_e32 v144, 0x1c000, v178
	ds_read_b128 v[200:203], v190 offset:49152
	ds_read_b128 v[204:207], v190 offset:50176
	ds_read_b128 v[208:211], v190 offset:51200
	ds_read_b128 v[212:215], v190 offset:52224
	ds_read_b128 v[216:219], v190 offset:53248
	ds_read_b128 v[220:223], v190 offset:54272
	ds_read_b128 v[224:227], v190 offset:55296
	ds_read_b128 v[228:231], v190 offset:56320
	ds_read_b128 v[28:31], v144
	ds_read_b128 v[32:35], v144 offset:1024
	ds_read_b128 v[40:43], v144 offset:2048
	ds_read_b128 v[44:47], v144 offset:3072
	s_waitcnt lgkmcnt(0)
	s_barrier
	s_setprio 1
	v_mfma_f32_16x16x32_bf16 v[140:143], v[28:31], v[200:203], v[140:143]
	v_mfma_f32_16x16x32_bf16 v[136:139], v[40:43], v[200:203], v[136:139]
	v_mfma_f32_16x16x32_bf16 v[124:127], v[28:31], v[208:211], v[124:127]
	v_mfma_f32_16x16x32_bf16 v[120:123], v[40:43], v[208:211], v[120:123]
	v_mfma_f32_16x16x32_bf16 v[108:111], v[28:31], v[216:219], v[108:111]
	v_mfma_f32_16x16x32_bf16 v[104:107], v[40:43], v[216:219], v[104:107]
	v_mfma_f32_16x16x32_bf16 v[92:95], v[28:31], v[224:227], v[92:95]
	v_mfma_f32_16x16x32_bf16 v[88:91], v[40:43], v[224:227], v[88:91]
	v_mfma_f32_16x16x32_bf16 v[140:143], v[32:35], v[204:207], v[140:143]
	v_mfma_f32_16x16x32_bf16 v[136:139], v[44:47], v[204:207], v[136:139]
	v_mfma_f32_16x16x32_bf16 v[124:127], v[32:35], v[212:215], v[124:127]
	v_mfma_f32_16x16x32_bf16 v[120:123], v[44:47], v[212:215], v[120:123]
	v_mfma_f32_16x16x32_bf16 v[108:111], v[32:35], v[220:223], v[108:111]
	v_mfma_f32_16x16x32_bf16 v[104:107], v[44:47], v[220:223], v[104:107]
	v_mfma_f32_16x16x32_bf16 v[92:95], v[32:35], v[228:231], v[92:95]
	v_mfma_f32_16x16x32_bf16 v[88:91], v[44:47], v[228:231], v[88:91]
	s_setprio 0
	s_barrier
	s_branch .Lq_lout_exit
.Lq_lout_1_loop:
	s_add_u32 s88, s88, 0x100
	s_addc_u32 s89, s89, 0
	s_add_u32 s82, s82, 0x80100
	s_addc_u32 s83, s83, 0
	s_waitcnt vmcnt(0)
	s_barrier
	s_barrier
	v_lshl_add_u64 v[176:177], s[88:89], 0, v[160:161]
	s_add_i32 m0, s9, 0x4000
	v_lshl_add_u64 v[232:233], s[88:89], 0, v[162:163]
	global_load_lds_dwordx4 v[176:177], off
	s_add_i32 m0, s9, 0x6000
	v_lshl_add_u64 v[234:235], s[82:83], 0, v[160:161]
	global_load_lds_dwordx4 v[232:233], off
	s_add_i32 m0, s9, 0x10000
	v_lshl_add_u64 v[236:237], s[82:83], 0, v[162:163]
	global_load_lds_dwordx4 v[234:235], off
	s_add_i32 m0, s9, 0x12000
	s_add_u32 s88, s88, 0x80
	s_addc_u32 s89, s89, 0
	global_load_lds_dwordx4 v[236:237], off
	s_add_u32 s82, s82, 0x80
	s_addc_u32 s83, s83, 0
	s_mov_b32 s55, 0
.Lq_lout_1_k:
	v_lshl_add_u64 v[176:177], s[88:89], 0, v[160:161]
	s_add_i32 m0, s9, 0xc000
	v_lshl_add_u64 v[232:233], s[88:89], 0, v[162:163]
	global_load_lds_dwordx4 v[176:177], off
	s_add_i32 m0, s9, 0xe000
	v_lshl_add_u64 v[234:235], s[82:83], 0, v[160:161]
	global_load_lds_dwordx4 v[232:233], off
	s_add_i32 m0, s9, 0x18000
	v_lshl_add_u64 v[236:237], s[82:83], 0, v[162:163]
	global_load_lds_dwordx4 v[234:235], off
	s_add_i32 m0, s9, 0x1a000
	s_add_u32 s88, s88, 0x80
	s_addc_u32 s89, s89, 0
	global_load_lds_dwordx4 v[236:237], off
	s_add_u32 s82, s82, 0x80
	s_addc_u32 s83, s83, 0
	v_add_u32_e32 v144, 0x14000, v178
	ds_read_b128 v[200:203], v190 offset:0
	ds_read_b128 v[204:207], v190 offset:1024
	ds_read_b128 v[208:211], v190 offset:2048
	ds_read_b128 v[212:215], v190 offset:3072
	ds_read_b128 v[216:219], v190 offset:4096
	ds_read_b128 v[220:223], v190 offset:5120
	ds_read_b128 v[224:227], v190 offset:6144
	ds_read_b128 v[228:231], v190 offset:7168
	ds_read_b128 v[168:171], v144
	ds_read_b128 v[172:175], v144 offset:1024
	ds_read_b128 v[192:195], v144 offset:2048
	ds_read_b128 v[196:199], v144 offset:3072
	s_waitcnt vmcnt(8)
	s_waitcnt lgkmcnt(0)
	s_barrier
	s_setprio 1
	v_mfma_f32_16x16x32_bf16 v[132:135], v[168:171], v[200:203], v[132:135]
	v_mfma_f32_16x16x32_bf16 v[128:131], v[192:195], v[200:203], v[128:131]
	v_mfma_f32_16x16x32_bf16 v[116:119], v[168:171], v[208:211], v[116:119]
	v_mfma_f32_16x16x32_bf16 v[112:115], v[192:195], v[208:211], v[112:115]
	v_mfma_f32_16x16x32_bf16 v[100:103], v[168:171], v[216:219], v[100:103]
	v_mfma_f32_16x16x32_bf16 v[96:99], v[192:195], v[216:219], v[96:99]
	v_mfma_f32_16x16x32_bf16 v[84:87], v[168:171], v[224:227], v[84:87]
	v_mfma_f32_16x16x32_bf16 v[80:83], v[192:195], v[224:227], v[80:83]
	v_mfma_f32_16x16x32_bf16 v[132:135], v[172:175], v[204:207], v[132:135]
	v_mfma_f32_16x16x32_bf16 v[128:131], v[196:199], v[204:207], v[128:131]
	v_mfma_f32_16x16x32_bf16 v[116:119], v[172:175], v[212:215], v[116:119]
	v_mfma_f32_16x16x32_bf16 v[112:115], v[196:199], v[212:215], v[112:115]
	v_mfma_f32_16x16x32_bf16 v[100:103], v[172:175], v[220:223], v[100:103]
	v_mfma_f32_16x16x32_bf16 v[96:99], v[196:199], v[220:223], v[96:99]
	v_mfma_f32_16x16x32_bf16 v[84:87], v[172:175], v[228:231], v[84:87]
	v_mfma_f32_16x16x32_bf16 v[80:83], v[196:199], v[228:231], v[80:83]
	s_setprio 0
	s_barrier
	v_lshl_add_u64 v[176:177], s[88:89], 0, v[160:161]
	s_add_i32 m0, s9, 0x0
	v_lshl_add_u64 v[232:233], s[88:89], 0, v[162:163]
	global_load_lds_dwordx4 v[176:177], off
	s_add_i32 m0, s9, 0x2000
	v_lshl_add_u64 v[234:235], s[82:83], 0, v[160:161]
	global_load_lds_dwordx4 v[232:233], off
	s_add_i32 m0, s9, 0x14000
	v_lshl_add_u64 v[236:237], s[82:83], 0, v[162:163]
	global_load_lds_dwordx4 v[234:235], off
	s_add_i32 m0, s9, 0x16000
	s_add_u32 s88, s88, 0x80
	s_addc_u32 s89, s89, 0
	global_load_lds_dwordx4 v[236:237], off
	s_add_u32 s82, s82, 0x80
	s_addc_u32 s83, s83, 0
	v_add_u32_e32 v144, 0x1c000, v178
	ds_read_b128 v[200:203], v190 offset:32768
	ds_read_b128 v[204:207], v190 offset:33792
	ds_read_b128 v[208:211], v190 offset:34816
	ds_read_b128 v[212:215], v190 offset:35840
	ds_read_b128 v[216:219], v190 offset:36864
	ds_read_b128 v[220:223], v190 offset:37888
	ds_read_b128 v[224:227], v190 offset:38912
	ds_read_b128 v[228:231], v190 offset:39936
	ds_read_b128 v[168:171], v144
	ds_read_b128 v[172:175], v144 offset:1024
	ds_read_b128 v[192:195], v144 offset:2048
	ds_read_b128 v[196:199], v144 offset:3072
	s_waitcnt vmcnt(8)
	s_waitcnt lgkmcnt(0)
	s_barrier
	s_setprio 1
	v_mfma_f32_16x16x32_bf16 v[132:135], v[168:171], v[200:203], v[132:135]
	v_mfma_f32_16x16x32_bf16 v[128:131], v[192:195], v[200:203], v[128:131]
	v_mfma_f32_16x16x32_bf16 v[116:119], v[168:171], v[208:211], v[116:119]
	v_mfma_f32_16x16x32_bf16 v[112:115], v[192:195], v[208:211], v[112:115]
	v_mfma_f32_16x16x32_bf16 v[100:103], v[168:171], v[216:219], v[100:103]
	v_mfma_f32_16x16x32_bf16 v[96:99], v[192:195], v[216:219], v[96:99]
	v_mfma_f32_16x16x32_bf16 v[84:87], v[168:171], v[224:227], v[84:87]
	v_mfma_f32_16x16x32_bf16 v[80:83], v[192:195], v[224:227], v[80:83]
	v_mfma_f32_16x16x32_bf16 v[132:135], v[172:175], v[204:207], v[132:135]
	v_mfma_f32_16x16x32_bf16 v[128:131], v[196:199], v[204:207], v[128:131]
	v_mfma_f32_16x16x32_bf16 v[116:119], v[172:175], v[212:215], v[116:119]
	v_mfma_f32_16x16x32_bf16 v[112:115], v[196:199], v[212:215], v[112:115]
	v_mfma_f32_16x16x32_bf16 v[100:103], v[172:175], v[220:223], v[100:103]
	v_mfma_f32_16x16x32_bf16 v[96:99], v[196:199], v[220:223], v[96:99]
	v_mfma_f32_16x16x32_bf16 v[84:87], v[172:175], v[228:231], v[84:87]
	v_mfma_f32_16x16x32_bf16 v[80:83], v[196:199], v[228:231], v[80:83]
	s_setprio 0
	s_barrier
	v_lshl_add_u64 v[176:177], s[88:89], 0, v[160:161]
	s_add_i32 m0, s9, 0x8000
	v_lshl_add_u64 v[232:233], s[88:89], 0, v[162:163]
	global_load_lds_dwordx4 v[176:177], off
	s_add_i32 m0, s9, 0xa000
	v_lshl_add_u64 v[234:235], s[82:83], 0, v[160:161]
	global_load_lds_dwordx4 v[232:233], off
	s_add_i32 m0, s9, 0x1c000
	v_lshl_add_u64 v[236:237], s[82:83], 0, v[162:163]
	global_load_lds_dwordx4 v[234:235], off
	s_add_i32 m0, s9, 0x1e000
	s_add_u32 s88, s88, 0x80
	s_addc_u32 s89, s89, 0
	global_load_lds_dwordx4 v[236:237], off
	s_add_u32 s82, s82, 0x80
	s_addc_u32 s83, s83, 0
	v_add_u32_e32 v144, 0x10000, v178
	ds_read_b128 v[200:203], v190 offset:16384
	ds_read_b128 v[204:207], v190 offset:17408
	ds_read_b128 v[208:211], v190 offset:18432
	ds_read_b128 v[212:215], v190 offset:19456
	ds_read_b128 v[216:219], v190 offset:20480
	ds_read_b128 v[220:223], v190 offset:21504
	ds_read_b128 v[224:227], v190 offset:22528
	ds_read_b128 v[228:231], v190 offset:23552
	ds_read_b128 v[168:171], v144
	ds_read_b128 v[172:175], v144 offset:1024
	ds_read_b128 v[192:195], v144 offset:2048
	ds_read_b128 v[196:199], v144 offset:3072
	s_waitcnt vmcnt(8)
	s_waitcnt lgkmcnt(0)
	s_barrier
	s_setprio 1
	v_mfma_f32_16x16x32_bf16 v[132:135], v[168:171], v[200:203], v[132:135]
	v_mfma_f32_16x16x32_bf16 v[128:131], v[192:195], v[200:203], v[128:131]
	v_mfma_f32_16x16x32_bf16 v[116:119], v[168:171], v[208:211], v[116:119]
	v_mfma_f32_16x16x32_bf16 v[112:115], v[192:195], v[208:211], v[112:115]
	v_mfma_f32_16x16x32_bf16 v[100:103], v[168:171], v[216:219], v[100:103]
	v_mfma_f32_16x16x32_bf16 v[96:99], v[192:195], v[216:219], v[96:99]
	v_mfma_f32_16x16x32_bf16 v[84:87], v[168:171], v[224:227], v[84:87]
	v_mfma_f32_16x16x32_bf16 v[80:83], v[192:195], v[224:227], v[80:83]
	v_mfma_f32_16x16x32_bf16 v[132:135], v[172:175], v[204:207], v[132:135]
	v_mfma_f32_16x16x32_bf16 v[128:131], v[196:199], v[204:207], v[128:131]
	v_mfma_f32_16x16x32_bf16 v[116:119], v[172:175], v[212:215], v[116:119]
	v_mfma_f32_16x16x32_bf16 v[112:115], v[196:199], v[212:215], v[112:115]
	v_mfma_f32_16x16x32_bf16 v[100:103], v[172:175], v[220:223], v[100:103]
	v_mfma_f32_16x16x32_bf16 v[96:99], v[196:199], v[220:223], v[96:99]
	v_mfma_f32_16x16x32_bf16 v[84:87], v[172:175], v[228:231], v[84:87]
	v_mfma_f32_16x16x32_bf16 v[80:83], v[196:199], v[228:231], v[80:83]
	s_setprio 0
	s_barrier
	v_lshl_add_u64 v[176:177], s[88:89], 0, v[160:161]
	s_add_i32 m0, s9, 0x4000
	v_lshl_add_u64 v[232:233], s[88:89], 0, v[162:163]
	global_load_lds_dwordx4 v[176:177], off
	s_add_i32 m0, s9, 0x6000
	v_lshl_add_u64 v[234:235], s[82:83], 0, v[160:161]
	global_load_lds_dwordx4 v[232:233], off
	s_add_i32 m0, s9, 0x10000
	v_lshl_add_u64 v[236:237], s[82:83], 0, v[162:163]
	global_load_lds_dwordx4 v[234:235], off
	s_add_i32 m0, s9, 0x12000
	s_add_u32 s88, s88, 0x80
	s_addc_u32 s89, s89, 0
	global_load_lds_dwordx4 v[236:237], off
	s_add_u32 s82, s82, 0x80
	s_addc_u32 s83, s83, 0
	v_add_u32_e32 v144, 0x18000, v178
	ds_read_b128 v[200:203], v190 offset:49152
	ds_read_b128 v[204:207], v190 offset:50176
	ds_read_b128 v[208:211], v190 offset:51200
	ds_read_b128 v[212:215], v190 offset:52224
	ds_read_b128 v[216:219], v190 offset:53248
	ds_read_b128 v[220:223], v190 offset:54272
	ds_read_b128 v[224:227], v190 offset:55296
	ds_read_b128 v[228:231], v190 offset:56320
	ds_read_b128 v[168:171], v144
	ds_read_b128 v[172:175], v144 offset:1024
	ds_read_b128 v[192:195], v144 offset:2048
	ds_read_b128 v[196:199], v144 offset:3072
	s_waitcnt vmcnt(8)
	s_waitcnt lgkmcnt(0)
	s_barrier
	s_setprio 1
	v_mfma_f32_16x16x32_bf16 v[132:135], v[168:171], v[200:203], v[132:135]
	v_mfma_f32_16x16x32_bf16 v[128:131], v[192:195], v[200:203], v[128:131]
	v_mfma_f32_16x16x32_bf16 v[116:119], v[168:171], v[208:211], v[116:119]
	v_mfma_f32_16x16x32_bf16 v[112:115], v[192:195], v[208:211], v[112:115]
	v_mfma_f32_16x16x32_bf16 v[100:103], v[168:171], v[216:219], v[100:103]
	v_mfma_f32_16x16x32_bf16 v[96:99], v[192:195], v[216:219], v[96:99]
	v_mfma_f32_16x16x32_bf16 v[84:87], v[168:171], v[224:227], v[84:87]
	v_mfma_f32_16x16x32_bf16 v[80:83], v[192:195], v[224:227], v[80:83]
	v_mfma_f32_16x16x32_bf16 v[132:135], v[172:175], v[204:207], v[132:135]
	v_mfma_f32_16x16x32_bf16 v[128:131], v[196:199], v[204:207], v[128:131]
	v_mfma_f32_16x16x32_bf16 v[116:119], v[172:175], v[212:215], v[116:119]
	v_mfma_f32_16x16x32_bf16 v[112:115], v[196:199], v[212:215], v[112:115]
	v_mfma_f32_16x16x32_bf16 v[100:103], v[172:175], v[220:223], v[100:103]
	v_mfma_f32_16x16x32_bf16 v[96:99], v[196:199], v[220:223], v[96:99]
	v_mfma_f32_16x16x32_bf16 v[84:87], v[172:175], v[228:231], v[84:87]
	v_mfma_f32_16x16x32_bf16 v[80:83], v[196:199], v[228:231], v[80:83]
	s_setprio 0
	s_barrier
	s_add_i32 s55, s55, 1
	s_cmp_lt_u32 s55, 7
	s_cbranch_scc1 .Lq_lout_1_k
	v_lshl_add_u64 v[176:177], s[88:89], 0, v[160:161]
	s_add_i32 m0, s9, 0xc000
	v_lshl_add_u64 v[232:233], s[88:89], 0, v[162:163]
	global_load_lds_dwordx4 v[176:177], off
	s_add_i32 m0, s9, 0xe000
	v_lshl_add_u64 v[234:235], s[82:83], 0, v[160:161]
	global_load_lds_dwordx4 v[232:233], off
	s_add_i32 m0, s9, 0x18000
	v_lshl_add_u64 v[236:237], s[82:83], 0, v[162:163]
	global_load_lds_dwordx4 v[234:235], off
	s_add_i32 m0, s9, 0x1a000
	s_add_u32 s88, s88, 0x80
	s_addc_u32 s89, s89, 0
	global_load_lds_dwordx4 v[236:237], off
	s_add_u32 s82, s82, 0x80
	s_addc_u32 s83, s83, 0
	v_add_u32_e32 v144, 0x14000, v178
	ds_read_b128 v[200:203], v190 offset:0
	ds_read_b128 v[204:207], v190 offset:1024
	ds_read_b128 v[208:211], v190 offset:2048
	ds_read_b128 v[212:215], v190 offset:3072
	ds_read_b128 v[216:219], v190 offset:4096
	ds_read_b128 v[220:223], v190 offset:5120
	ds_read_b128 v[224:227], v190 offset:6144
	ds_read_b128 v[228:231], v190 offset:7168
	ds_read_b128 v[168:171], v144
	ds_read_b128 v[172:175], v144 offset:1024
	ds_read_b128 v[192:195], v144 offset:2048
	ds_read_b128 v[196:199], v144 offset:3072
	s_waitcnt vmcnt(8)
	s_waitcnt lgkmcnt(0)
	s_barrier
	s_setprio 1
	v_mfma_f32_16x16x32_bf16 v[132:135], v[168:171], v[200:203], v[132:135]
	v_mfma_f32_16x16x32_bf16 v[128:131], v[192:195], v[200:203], v[128:131]
	v_mfma_f32_16x16x32_bf16 v[116:119], v[168:171], v[208:211], v[116:119]
	v_mfma_f32_16x16x32_bf16 v[112:115], v[192:195], v[208:211], v[112:115]
	v_mfma_f32_16x16x32_bf16 v[100:103], v[168:171], v[216:219], v[100:103]
	v_mfma_f32_16x16x32_bf16 v[96:99], v[192:195], v[216:219], v[96:99]
	v_mfma_f32_16x16x32_bf16 v[84:87], v[168:171], v[224:227], v[84:87]
	v_mfma_f32_16x16x32_bf16 v[80:83], v[192:195], v[224:227], v[80:83]
	v_mfma_f32_16x16x32_bf16 v[132:135], v[172:175], v[204:207], v[132:135]
	v_mfma_f32_16x16x32_bf16 v[128:131], v[196:199], v[204:207], v[128:131]
	v_mfma_f32_16x16x32_bf16 v[116:119], v[172:175], v[212:215], v[116:119]
	v_mfma_f32_16x16x32_bf16 v[112:115], v[196:199], v[212:215], v[112:115]
	v_mfma_f32_16x16x32_bf16 v[100:103], v[172:175], v[220:223], v[100:103]
	v_mfma_f32_16x16x32_bf16 v[96:99], v[196:199], v[220:223], v[96:99]
	v_mfma_f32_16x16x32_bf16 v[84:87], v[172:175], v[228:231], v[84:87]
	v_mfma_f32_16x16x32_bf16 v[80:83], v[196:199], v[228:231], v[80:83]
	s_setprio 0
	s_barrier
	v_add_u32_e32 v144, 0x1c000, v178
	ds_read_b128 v[200:203], v190 offset:32768
	ds_read_b128 v[204:207], v190 offset:33792
	ds_read_b128 v[208:211], v190 offset:34816
	ds_read_b128 v[212:215], v190 offset:35840
	ds_read_b128 v[216:219], v190 offset:36864
	ds_read_b128 v[220:223], v190 offset:37888
	ds_read_b128 v[224:227], v190 offset:38912
	ds_read_b128 v[228:231], v190 offset:39936
	ds_read_b128 v[168:171], v144
	ds_read_b128 v[172:175], v144 offset:1024
	ds_read_b128 v[192:195], v144 offset:2048
	ds_read_b128 v[196:199], v144 offset:3072
	s_waitcnt vmcnt(4)
	s_waitcnt lgkmcnt(0)
	s_barrier
	s_setprio 1
	v_mfma_f32_16x16x32_bf16 v[132:135], v[168:171], v[200:203], v[132:135]
	v_mfma_f32_16x16x32_bf16 v[128:131], v[192:195], v[200:203], v[128:131]
	v_mfma_f32_16x16x32_bf16 v[116:119], v[168:171], v[208:211], v[116:119]
	v_mfma_f32_16x16x32_bf16 v[112:115], v[192:195], v[208:211], v[112:115]
	v_mfma_f32_16x16x32_bf16 v[100:103], v[168:171], v[216:219], v[100:103]
	v_mfma_f32_16x16x32_bf16 v[96:99], v[192:195], v[216:219], v[96:99]
	v_mfma_f32_16x16x32_bf16 v[84:87], v[168:171], v[224:227], v[84:87]
	v_mfma_f32_16x16x32_bf16 v[80:83], v[192:195], v[224:227], v[80:83]
	v_mfma_f32_16x16x32_bf16 v[132:135], v[172:175], v[204:207], v[132:135]
	v_mfma_f32_16x16x32_bf16 v[128:131], v[196:199], v[204:207], v[128:131]
	v_mfma_f32_16x16x32_bf16 v[116:119], v[172:175], v[212:215], v[116:119]
	v_mfma_f32_16x16x32_bf16 v[112:115], v[196:199], v[212:215], v[112:115]
	v_mfma_f32_16x16x32_bf16 v[100:103], v[172:175], v[220:223], v[100:103]
	v_mfma_f32_16x16x32_bf16 v[96:99], v[196:199], v[220:223], v[96:99]
	v_mfma_f32_16x16x32_bf16 v[84:87], v[172:175], v[228:231], v[84:87]
	v_mfma_f32_16x16x32_bf16 v[80:83], v[196:199], v[228:231], v[80:83]
	s_setprio 0
	s_barrier
	v_add_u32_e32 v144, 0x10000, v178
	ds_read_b128 v[200:203], v190 offset:16384
	ds_read_b128 v[204:207], v190 offset:17408
	ds_read_b128 v[208:211], v190 offset:18432
	ds_read_b128 v[212:215], v190 offset:19456
	ds_read_b128 v[216:219], v190 offset:20480
	ds_read_b128 v[220:223], v190 offset:21504
	ds_read_b128 v[224:227], v190 offset:22528
	ds_read_b128 v[228:231], v190 offset:23552
	ds_read_b128 v[168:171], v144
	ds_read_b128 v[172:175], v144 offset:1024
	ds_read_b128 v[192:195], v144 offset:2048
	ds_read_b128 v[196:199], v144 offset:3072
	s_waitcnt vmcnt(0)
	s_waitcnt lgkmcnt(0)
	s_barrier
	s_setprio 1
	v_mfma_f32_16x16x32_bf16 v[132:135], v[168:171], v[200:203], v[132:135]
	v_mfma_f32_16x16x32_bf16 v[128:131], v[192:195], v[200:203], v[128:131]
	v_mfma_f32_16x16x32_bf16 v[116:119], v[168:171], v[208:211], v[116:119]
	v_mfma_f32_16x16x32_bf16 v[112:115], v[192:195], v[208:211], v[112:115]
	v_mfma_f32_16x16x32_bf16 v[100:103], v[168:171], v[216:219], v[100:103]
	v_mfma_f32_16x16x32_bf16 v[96:99], v[192:195], v[216:219], v[96:99]
	v_mfma_f32_16x16x32_bf16 v[84:87], v[168:171], v[224:227], v[84:87]
	v_mfma_f32_16x16x32_bf16 v[80:83], v[192:195], v[224:227], v[80:83]
	v_mfma_f32_16x16x32_bf16 v[132:135], v[172:175], v[204:207], v[132:135]
	v_mfma_f32_16x16x32_bf16 v[128:131], v[196:199], v[204:207], v[128:131]
	v_mfma_f32_16x16x32_bf16 v[116:119], v[172:175], v[212:215], v[116:119]
	v_mfma_f32_16x16x32_bf16 v[112:115], v[196:199], v[212:215], v[112:115]
	v_mfma_f32_16x16x32_bf16 v[100:103], v[172:175], v[220:223], v[100:103]
	v_mfma_f32_16x16x32_bf16 v[96:99], v[196:199], v[220:223], v[96:99]
	v_mfma_f32_16x16x32_bf16 v[84:87], v[172:175], v[228:231], v[84:87]
	v_mfma_f32_16x16x32_bf16 v[80:83], v[196:199], v[228:231], v[80:83]
	s_setprio 0
	s_barrier
	v_add_u32_e32 v144, 0x18000, v178
	ds_read_b128 v[200:203], v190 offset:49152
	ds_read_b128 v[204:207], v190 offset:50176
	ds_read_b128 v[208:211], v190 offset:51200
	ds_read_b128 v[212:215], v190 offset:52224
	ds_read_b128 v[216:219], v190 offset:53248
	ds_read_b128 v[220:223], v190 offset:54272
	ds_read_b128 v[224:227], v190 offset:55296
	ds_read_b128 v[228:231], v190 offset:56320
	ds_read_b128 v[168:171], v144
	ds_read_b128 v[172:175], v144 offset:1024
	ds_read_b128 v[192:195], v144 offset:2048
	ds_read_b128 v[196:199], v144 offset:3072
	s_waitcnt lgkmcnt(0)
	s_barrier
	s_setprio 1
	v_mfma_f32_16x16x32_bf16 v[132:135], v[168:171], v[200:203], v[132:135]
	v_mfma_f32_16x16x32_bf16 v[128:131], v[192:195], v[200:203], v[128:131]
	v_mfma_f32_16x16x32_bf16 v[116:119], v[168:171], v[208:211], v[116:119]
	v_mfma_f32_16x16x32_bf16 v[112:115], v[192:195], v[208:211], v[112:115]
	v_mfma_f32_16x16x32_bf16 v[100:103], v[168:171], v[216:219], v[100:103]
	v_mfma_f32_16x16x32_bf16 v[96:99], v[192:195], v[216:219], v[96:99]
	v_mfma_f32_16x16x32_bf16 v[84:87], v[168:171], v[224:227], v[84:87]
	v_mfma_f32_16x16x32_bf16 v[80:83], v[192:195], v[224:227], v[80:83]
	v_mfma_f32_16x16x32_bf16 v[132:135], v[172:175], v[204:207], v[132:135]
	v_mfma_f32_16x16x32_bf16 v[128:131], v[196:199], v[204:207], v[128:131]
	v_mfma_f32_16x16x32_bf16 v[116:119], v[172:175], v[212:215], v[116:119]
	v_mfma_f32_16x16x32_bf16 v[112:115], v[196:199], v[212:215], v[112:115]
	v_mfma_f32_16x16x32_bf16 v[100:103], v[172:175], v[220:223], v[100:103]
	v_mfma_f32_16x16x32_bf16 v[96:99], v[196:199], v[220:223], v[96:99]
	v_mfma_f32_16x16x32_bf16 v[84:87], v[172:175], v[228:231], v[84:87]
	v_mfma_f32_16x16x32_bf16 v[80:83], v[196:199], v[228:231], v[80:83]
	s_setprio 0
	s_barrier
	s_branch .Lq_lout_exit
.Lq_lout_2_loop:
	s_add_u32 s88, s88, 0x80080
	s_addc_u32 s89, s89, 0
	s_add_u32 s82, s82, 0x100
	s_addc_u32 s83, s83, 0
	s_waitcnt vmcnt(0)
	s_barrier
	s_barrier
	v_lshl_add_u64 v[176:177], s[88:89], 0, v[160:161]
	s_add_i32 m0, s9, 0xc000
	v_lshl_add_u64 v[232:233], s[88:89], 0, v[162:163]
	global_load_lds_dwordx4 v[176:177], off
	s_add_i32 m0, s9, 0xe000
	s_add_u32 s88, s88, 0x80
	s_addc_u32 s89, s89, 0
	global_load_lds_dwordx4 v[232:233], off
	v_lshl_add_u64 v[176:177], s[88:89], 0, v[160:161]
	s_add_i32 m0, s9, 0x0
	v_lshl_add_u64 v[232:233], s[88:89], 0, v[162:163]
	global_load_lds_dwordx4 v[176:177], off
	s_add_i32 m0, s9, 0x2000
	v_lshl_add_u64 v[234:235], s[82:83], 0, v[160:161]
	global_load_lds_dwordx4 v[232:233], off
	s_add_i32 m0, s9, 0x14000
	v_lshl_add_u64 v[236:237], s[82:83], 0, v[162:163]
	global_load_lds_dwordx4 v[234:235], off
	s_add_i32 m0, s9, 0x16000
	s_add_u32 s88, s88, 0x80
	s_addc_u32 s89, s89, 0
	global_load_lds_dwordx4 v[236:237], off
	s_add_u32 s82, s82, 0x80
	s_addc_u32 s83, s83, 0
	s_mov_b32 s55, 0
.Lq_lout_2_k:
	v_lshl_add_u64 v[176:177], s[88:89], 0, v[160:161]
	s_add_i32 m0, s9, 0x8000
	v_lshl_add_u64 v[232:233], s[88:89], 0, v[162:163]
	global_load_lds_dwordx4 v[176:177], off
	s_add_i32 m0, s9, 0xa000
	v_lshl_add_u64 v[234:235], s[82:83], 0, v[160:161]
	global_load_lds_dwordx4 v[232:233], off
	s_add_i32 m0, s9, 0x1c000
	v_lshl_add_u64 v[236:237], s[82:83], 0, v[162:163]
	global_load_lds_dwordx4 v[234:235], off
	s_add_i32 m0, s9, 0x1e000
	s_add_u32 s88, s88, 0x80
	s_addc_u32 s89, s89, 0
	global_load_lds_dwordx4 v[236:237], off
	s_add_u32 s82, s82, 0x80
	s_addc_u32 s83, s83, 0
	v_add_u32_e32 v144, 0x10000, v178
	ds_read_b128 v[200:203], v190 offset:16384
	ds_read_b128 v[204:207], v190 offset:17408
	ds_read_b128 v[208:211], v190 offset:18432
	ds_read_b128 v[212:215], v190 offset:19456
	ds_read_b128 v[216:219], v190 offset:20480
	ds_read_b128 v[220:223], v190 offset:21504
	ds_read_b128 v[224:227], v190 offset:22528
	ds_read_b128 v[228:231], v190 offset:23552
	ds_read_b128 v[28:31], v144
	ds_read_b128 v[32:35], v144 offset:1024
	ds_read_b128 v[40:43], v144 offset:2048
	ds_read_b128 v[44:47], v144 offset:3072
	s_waitcnt vmcnt(8)
	s_waitcnt lgkmcnt(0)
	s_barrier
	s_setprio 1
	v_mfma_f32_16x16x32_bf16 v[76:79], v[28:31], v[200:203], v[76:79]
	v_mfma_f32_16x16x32_bf16 v[72:75], v[40:43], v[200:203], v[72:75]
	v_mfma_f32_16x16x32_bf16 v[60:63], v[28:31], v[208:211], v[60:63]
	v_mfma_f32_16x16x32_bf16 v[56:59], v[40:43], v[208:211], v[56:59]
	v_mfma_f32_16x16x32_bf16 v[36:39], v[28:31], v[216:219], v[36:39]
	v_mfma_f32_16x16x32_bf16 v[24:27], v[40:43], v[216:219], v[24:27]
	v_mfma_f32_16x16x32_bf16 v[12:15], v[28:31], v[224:227], v[12:15]
	v_mfma_f32_16x16x32_bf16 v[8:11], v[40:43], v[224:227], v[8:11]
	v_mfma_f32_16x16x32_bf16 v[76:79], v[32:35], v[204:207], v[76:79]
	v_mfma_f32_16x16x32_bf16 v[72:75], v[44:47], v[204:207], v[72:75]
	v_mfma_f32_16x16x32_bf16 v[60:63], v[32:35], v[212:215], v[60:63]
	v_mfma_f32_16x16x32_bf16 v[56:59], v[44:47], v[212:215], v[56:59]
	v_mfma_f32_16x16x32_bf16 v[36:39], v[32:35], v[220:223], v[36:39]
	v_mfma_f32_16x16x32_bf16 v[24:27], v[44:47], v[220:223], v[24:27]
	v_mfma_f32_16x16x32_bf16 v[12:15], v[32:35], v[228:231], v[12:15]
	v_mfma_f32_16x16x32_bf16 v[8:11], v[44:47], v[228:231], v[8:11]
	s_setprio 0
	s_barrier
	v_lshl_add_u64 v[176:177], s[88:89], 0, v[160:161]
	s_add_i32 m0, s9, 0x4000
	v_lshl_add_u64 v[232:233], s[88:89], 0, v[162:163]
	global_load_lds_dwordx4 v[176:177], off
	s_add_i32 m0, s9, 0x6000
	v_lshl_add_u64 v[234:235], s[82:83], 0, v[160:161]
	global_load_lds_dwordx4 v[232:233], off
	s_add_i32 m0, s9, 0x10000
	v_lshl_add_u64 v[236:237], s[82:83], 0, v[162:163]
	global_load_lds_dwordx4 v[234:235], off
	s_add_i32 m0, s9, 0x12000
	s_add_u32 s88, s88, 0x80
	s_addc_u32 s89, s89, 0
	global_load_lds_dwordx4 v[236:237], off
	s_add_u32 s82, s82, 0x80
	s_addc_u32 s83, s83, 0
	v_add_u32_e32 v144, 0x18000, v178
	ds_read_b128 v[200:203], v190 offset:49152
	ds_read_b128 v[204:207], v190 offset:50176
	ds_read_b128 v[208:211], v190 offset:51200
	ds_read_b128 v[212:215], v190 offset:52224
	ds_read_b128 v[216:219], v190 offset:53248
	ds_read_b128 v[220:223], v190 offset:54272
	ds_read_b128 v[224:227], v190 offset:55296
	ds_read_b128 v[228:231], v190 offset:56320
	ds_read_b128 v[28:31], v144
	ds_read_b128 v[32:35], v144 offset:1024
	ds_read_b128 v[40:43], v144 offset:2048
	ds_read_b128 v[44:47], v144 offset:3072
	s_waitcnt vmcnt(8)
	s_waitcnt lgkmcnt(0)
	s_barrier
	s_setprio 1
	v_mfma_f32_16x16x32_bf16 v[76:79], v[28:31], v[200:203], v[76:79]
	v_mfma_f32_16x16x32_bf16 v[72:75], v[40:43], v[200:203], v[72:75]
	v_mfma_f32_16x16x32_bf16 v[60:63], v[28:31], v[208:211], v[60:63]
	v_mfma_f32_16x16x32_bf16 v[56:59], v[40:43], v[208:211], v[56:59]
	v_mfma_f32_16x16x32_bf16 v[36:39], v[28:31], v[216:219], v[36:39]
	v_mfma_f32_16x16x32_bf16 v[24:27], v[40:43], v[216:219], v[24:27]
	v_mfma_f32_16x16x32_bf16 v[12:15], v[28:31], v[224:227], v[12:15]
	v_mfma_f32_16x16x32_bf16 v[8:11], v[40:43], v[224:227], v[8:11]
	v_mfma_f32_16x16x32_bf16 v[76:79], v[32:35], v[204:207], v[76:79]
	v_mfma_f32_16x16x32_bf16 v[72:75], v[44:47], v[204:207], v[72:75]
	v_mfma_f32_16x16x32_bf16 v[60:63], v[32:35], v[212:215], v[60:63]
	v_mfma_f32_16x16x32_bf16 v[56:59], v[44:47], v[212:215], v[56:59]
	v_mfma_f32_16x16x32_bf16 v[36:39], v[32:35], v[220:223], v[36:39]
	v_mfma_f32_16x16x32_bf16 v[24:27], v[44:47], v[220:223], v[24:27]
	v_mfma_f32_16x16x32_bf16 v[12:15], v[32:35], v[228:231], v[12:15]
	v_mfma_f32_16x16x32_bf16 v[8:11], v[44:47], v[228:231], v[8:11]
	s_setprio 0
	s_barrier
	v_lshl_add_u64 v[176:177], s[88:89], 0, v[160:161]
	s_add_i32 m0, s9, 0xc000
	v_lshl_add_u64 v[232:233], s[88:89], 0, v[162:163]
	global_load_lds_dwordx4 v[176:177], off
	s_add_i32 m0, s9, 0xe000
	v_lshl_add_u64 v[234:235], s[82:83], 0, v[160:161]
	global_load_lds_dwordx4 v[232:233], off
	s_add_i32 m0, s9, 0x18000
	v_lshl_add_u64 v[236:237], s[82:83], 0, v[162:163]
	global_load_lds_dwordx4 v[234:235], off
	s_add_i32 m0, s9, 0x1a000
	s_add_u32 s88, s88, 0x80
	s_addc_u32 s89, s89, 0
	global_load_lds_dwordx4 v[236:237], off
	s_add_u32 s82, s82, 0x80
	s_addc_u32 s83, s83, 0
	v_add_u32_e32 v144, 0x14000, v178
	ds_read_b128 v[200:203], v190 offset:0
	ds_read_b128 v[204:207], v190 offset:1024
	ds_read_b128 v[208:211], v190 offset:2048
	ds_read_b128 v[212:215], v190 offset:3072
	ds_read_b128 v[216:219], v190 offset:4096
	ds_read_b128 v[220:223], v190 offset:5120
	ds_read_b128 v[224:227], v190 offset:6144
	ds_read_b128 v[228:231], v190 offset:7168
	ds_read_b128 v[28:31], v144
	ds_read_b128 v[32:35], v144 offset:1024
	ds_read_b128 v[40:43], v144 offset:2048
	ds_read_b128 v[44:47], v144 offset:3072
	s_waitcnt vmcnt(8)
	s_waitcnt lgkmcnt(0)
	s_barrier
	s_setprio 1
	v_mfma_f32_16x16x32_bf16 v[76:79], v[28:31], v[200:203], v[76:79]
	v_mfma_f32_16x16x32_bf16 v[72:75], v[40:43], v[200:203], v[72:75]
	v_mfma_f32_16x16x32_bf16 v[60:63], v[28:31], v[208:211], v[60:63]
	v_mfma_f32_16x16x32_bf16 v[56:59], v[40:43], v[208:211], v[56:59]
	v_mfma_f32_16x16x32_bf16 v[36:39], v[28:31], v[216:219], v[36:39]
	v_mfma_f32_16x16x32_bf16 v[24:27], v[40:43], v[216:219], v[24:27]
	v_mfma_f32_16x16x32_bf16 v[12:15], v[28:31], v[224:227], v[12:15]
	v_mfma_f32_16x16x32_bf16 v[8:11], v[40:43], v[224:227], v[8:11]
	v_mfma_f32_16x16x32_bf16 v[76:79], v[32:35], v[204:207], v[76:79]
	v_mfma_f32_16x16x32_bf16 v[72:75], v[44:47], v[204:207], v[72:75]
	v_mfma_f32_16x16x32_bf16 v[60:63], v[32:35], v[212:215], v[60:63]
	v_mfma_f32_16x16x32_bf16 v[56:59], v[44:47], v[212:215], v[56:59]
	v_mfma_f32_16x16x32_bf16 v[36:39], v[32:35], v[220:223], v[36:39]
	v_mfma_f32_16x16x32_bf16 v[24:27], v[44:47], v[220:223], v[24:27]
	v_mfma_f32_16x16x32_bf16 v[12:15], v[32:35], v[228:231], v[12:15]
	v_mfma_f32_16x16x32_bf16 v[8:11], v[44:47], v[228:231], v[8:11]
	s_setprio 0
	s_barrier
	v_lshl_add_u64 v[176:177], s[88:89], 0, v[160:161]
	s_add_i32 m0, s9, 0x0
	v_lshl_add_u64 v[232:233], s[88:89], 0, v[162:163]
	global_load_lds_dwordx4 v[176:177], off
	s_add_i32 m0, s9, 0x2000
	v_lshl_add_u64 v[234:235], s[82:83], 0, v[160:161]
	global_load_lds_dwordx4 v[232:233], off
	s_add_i32 m0, s9, 0x14000
	v_lshl_add_u64 v[236:237], s[82:83], 0, v[162:163]
	global_load_lds_dwordx4 v[234:235], off
	s_add_i32 m0, s9, 0x16000
	s_add_u32 s88, s88, 0x80
	s_addc_u32 s89, s89, 0
	global_load_lds_dwordx4 v[236:237], off
	s_add_u32 s82, s82, 0x80
	s_addc_u32 s83, s83, 0
	v_add_u32_e32 v144, 0x1c000, v178
	ds_read_b128 v[200:203], v190 offset:32768
	ds_read_b128 v[204:207], v190 offset:33792
	ds_read_b128 v[208:211], v190 offset:34816
	ds_read_b128 v[212:215], v190 offset:35840
	ds_read_b128 v[216:219], v190 offset:36864
	ds_read_b128 v[220:223], v190 offset:37888
	ds_read_b128 v[224:227], v190 offset:38912
	ds_read_b128 v[228:231], v190 offset:39936
	ds_read_b128 v[28:31], v144
	ds_read_b128 v[32:35], v144 offset:1024
	ds_read_b128 v[40:43], v144 offset:2048
	ds_read_b128 v[44:47], v144 offset:3072
	s_waitcnt vmcnt(8)
	s_waitcnt lgkmcnt(0)
	s_barrier
	s_setprio 1
	v_mfma_f32_16x16x32_bf16 v[76:79], v[28:31], v[200:203], v[76:79]
	v_mfma_f32_16x16x32_bf16 v[72:75], v[40:43], v[200:203], v[72:75]
	v_mfma_f32_16x16x32_bf16 v[60:63], v[28:31], v[208:211], v[60:63]
	v_mfma_f32_16x16x32_bf16 v[56:59], v[40:43], v[208:211], v[56:59]
	v_mfma_f32_16x16x32_bf16 v[36:39], v[28:31], v[216:219], v[36:39]
	v_mfma_f32_16x16x32_bf16 v[24:27], v[40:43], v[216:219], v[24:27]
	v_mfma_f32_16x16x32_bf16 v[12:15], v[28:31], v[224:227], v[12:15]
	v_mfma_f32_16x16x32_bf16 v[8:11], v[40:43], v[224:227], v[8:11]
	v_mfma_f32_16x16x32_bf16 v[76:79], v[32:35], v[204:207], v[76:79]
	v_mfma_f32_16x16x32_bf16 v[72:75], v[44:47], v[204:207], v[72:75]
	v_mfma_f32_16x16x32_bf16 v[60:63], v[32:35], v[212:215], v[60:63]
	v_mfma_f32_16x16x32_bf16 v[56:59], v[44:47], v[212:215], v[56:59]
	v_mfma_f32_16x16x32_bf16 v[36:39], v[32:35], v[220:223], v[36:39]
	v_mfma_f32_16x16x32_bf16 v[24:27], v[44:47], v[220:223], v[24:27]
	v_mfma_f32_16x16x32_bf16 v[12:15], v[32:35], v[228:231], v[12:15]
	v_mfma_f32_16x16x32_bf16 v[8:11], v[44:47], v[228:231], v[8:11]
	s_setprio 0
	s_barrier
	s_add_i32 s55, s55, 1
	s_cmp_lt_u32 s55, 7
	s_cbranch_scc1 .Lq_lout_2_k
	v_lshl_add_u64 v[176:177], s[88:89], 0, v[160:161]
	s_add_i32 m0, s9, 0x8000
	v_lshl_add_u64 v[232:233], s[88:89], 0, v[162:163]
	global_load_lds_dwordx4 v[176:177], off
	s_add_i32 m0, s9, 0xa000
	v_lshl_add_u64 v[234:235], s[82:83], 0, v[160:161]
	global_load_lds_dwordx4 v[232:233], off
	s_add_i32 m0, s9, 0x1c000
	v_lshl_add_u64 v[236:237], s[82:83], 0, v[162:163]
	global_load_lds_dwordx4 v[234:235], off
	s_add_i32 m0, s9, 0x1e000
	s_add_u32 s88, s88, 0x80
	s_addc_u32 s89, s89, 0
	global_load_lds_dwordx4 v[236:237], off
	s_add_u32 s82, s82, 0x80
	s_addc_u32 s83, s83, 0
	v_add_u32_e32 v144, 0x10000, v178
	ds_read_b128 v[200:203], v190 offset:16384
	ds_read_b128 v[204:207], v190 offset:17408
	ds_read_b128 v[208:211], v190 offset:18432
	ds_read_b128 v[212:215], v190 offset:19456
	ds_read_b128 v[216:219], v190 offset:20480
	ds_read_b128 v[220:223], v190 offset:21504
	ds_read_b128 v[224:227], v190 offset:22528
	ds_read_b128 v[228:231], v190 offset:23552
	ds_read_b128 v[28:31], v144
	ds_read_b128 v[32:35], v144 offset:1024
	ds_read_b128 v[40:43], v144 offset:2048
	ds_read_b128 v[44:47], v144 offset:3072
	s_waitcnt vmcnt(8)
	s_waitcnt lgkmcnt(0)
	s_barrier
	s_setprio 1
	v_mfma_f32_16x16x32_bf16 v[76:79], v[28:31], v[200:203], v[76:79]
	v_mfma_f32_16x16x32_bf16 v[72:75], v[40:43], v[200:203], v[72:75]
	v_mfma_f32_16x16x32_bf16 v[60:63], v[28:31], v[208:211], v[60:63]
	v_mfma_f32_16x16x32_bf16 v[56:59], v[40:43], v[208:211], v[56:59]
	v_mfma_f32_16x16x32_bf16 v[36:39], v[28:31], v[216:219], v[36:39]
	v_mfma_f32_16x16x32_bf16 v[24:27], v[40:43], v[216:219], v[24:27]
	v_mfma_f32_16x16x32_bf16 v[12:15], v[28:31], v[224:227], v[12:15]
	v_mfma_f32_16x16x32_bf16 v[8:11], v[40:43], v[224:227], v[8:11]
	v_mfma_f32_16x16x32_bf16 v[76:79], v[32:35], v[204:207], v[76:79]
	v_mfma_f32_16x16x32_bf16 v[72:75], v[44:47], v[204:207], v[72:75]
	v_mfma_f32_16x16x32_bf16 v[60:63], v[32:35], v[212:215], v[60:63]
	v_mfma_f32_16x16x32_bf16 v[56:59], v[44:47], v[212:215], v[56:59]
	v_mfma_f32_16x16x32_bf16 v[36:39], v[32:35], v[220:223], v[36:39]
	v_mfma_f32_16x16x32_bf16 v[24:27], v[44:47], v[220:223], v[24:27]
	v_mfma_f32_16x16x32_bf16 v[12:15], v[32:35], v[228:231], v[12:15]
	v_mfma_f32_16x16x32_bf16 v[8:11], v[44:47], v[228:231], v[8:11]
	s_setprio 0
	s_barrier
	v_add_u32_e32 v144, 0x18000, v178
	ds_read_b128 v[200:203], v190 offset:49152
	ds_read_b128 v[204:207], v190 offset:50176
	ds_read_b128 v[208:211], v190 offset:51200
	ds_read_b128 v[212:215], v190 offset:52224
	ds_read_b128 v[216:219], v190 offset:53248
	ds_read_b128 v[220:223], v190 offset:54272
	ds_read_b128 v[224:227], v190 offset:55296
	ds_read_b128 v[228:231], v190 offset:56320
	ds_read_b128 v[28:31], v144
	ds_read_b128 v[32:35], v144 offset:1024
	ds_read_b128 v[40:43], v144 offset:2048
	ds_read_b128 v[44:47], v144 offset:3072
	s_waitcnt vmcnt(4)
	s_waitcnt lgkmcnt(0)
	s_barrier
	s_setprio 1
	v_mfma_f32_16x16x32_bf16 v[76:79], v[28:31], v[200:203], v[76:79]
	v_mfma_f32_16x16x32_bf16 v[72:75], v[40:43], v[200:203], v[72:75]
	v_mfma_f32_16x16x32_bf16 v[60:63], v[28:31], v[208:211], v[60:63]
	v_mfma_f32_16x16x32_bf16 v[56:59], v[40:43], v[208:211], v[56:59]
	v_mfma_f32_16x16x32_bf16 v[36:39], v[28:31], v[216:219], v[36:39]
	v_mfma_f32_16x16x32_bf16 v[24:27], v[40:43], v[216:219], v[24:27]
	v_mfma_f32_16x16x32_bf16 v[12:15], v[28:31], v[224:227], v[12:15]
	v_mfma_f32_16x16x32_bf16 v[8:11], v[40:43], v[224:227], v[8:11]
	v_mfma_f32_16x16x32_bf16 v[76:79], v[32:35], v[204:207], v[76:79]
	v_mfma_f32_16x16x32_bf16 v[72:75], v[44:47], v[204:207], v[72:75]
	v_mfma_f32_16x16x32_bf16 v[60:63], v[32:35], v[212:215], v[60:63]
	v_mfma_f32_16x16x32_bf16 v[56:59], v[44:47], v[212:215], v[56:59]
	v_mfma_f32_16x16x32_bf16 v[36:39], v[32:35], v[220:223], v[36:39]
	v_mfma_f32_16x16x32_bf16 v[24:27], v[44:47], v[220:223], v[24:27]
	v_mfma_f32_16x16x32_bf16 v[12:15], v[32:35], v[228:231], v[12:15]
	v_mfma_f32_16x16x32_bf16 v[8:11], v[44:47], v[228:231], v[8:11]
	s_setprio 0
	s_barrier
	v_add_u32_e32 v144, 0x14000, v178
	ds_read_b128 v[200:203], v190 offset:0
	ds_read_b128 v[204:207], v190 offset:1024
	ds_read_b128 v[208:211], v190 offset:2048
	ds_read_b128 v[212:215], v190 offset:3072
	ds_read_b128 v[216:219], v190 offset:4096
	ds_read_b128 v[220:223], v190 offset:5120
	ds_read_b128 v[224:227], v190 offset:6144
	ds_read_b128 v[228:231], v190 offset:7168
	ds_read_b128 v[28:31], v144
	ds_read_b128 v[32:35], v144 offset:1024
	ds_read_b128 v[40:43], v144 offset:2048
	ds_read_b128 v[44:47], v144 offset:3072
	s_waitcnt vmcnt(0)
	s_waitcnt lgkmcnt(0)
	s_barrier
	s_setprio 1
	v_mfma_f32_16x16x32_bf16 v[76:79], v[28:31], v[200:203], v[76:79]
	v_mfma_f32_16x16x32_bf16 v[72:75], v[40:43], v[200:203], v[72:75]
	v_mfma_f32_16x16x32_bf16 v[60:63], v[28:31], v[208:211], v[60:63]
	v_mfma_f32_16x16x32_bf16 v[56:59], v[40:43], v[208:211], v[56:59]
	v_mfma_f32_16x16x32_bf16 v[36:39], v[28:31], v[216:219], v[36:39]
	v_mfma_f32_16x16x32_bf16 v[24:27], v[40:43], v[216:219], v[24:27]
	v_mfma_f32_16x16x32_bf16 v[12:15], v[28:31], v[224:227], v[12:15]
	v_mfma_f32_16x16x32_bf16 v[8:11], v[40:43], v[224:227], v[8:11]
	v_mfma_f32_16x16x32_bf16 v[76:79], v[32:35], v[204:207], v[76:79]
	v_mfma_f32_16x16x32_bf16 v[72:75], v[44:47], v[204:207], v[72:75]
	v_mfma_f32_16x16x32_bf16 v[60:63], v[32:35], v[212:215], v[60:63]
	v_mfma_f32_16x16x32_bf16 v[56:59], v[44:47], v[212:215], v[56:59]
	v_mfma_f32_16x16x32_bf16 v[36:39], v[32:35], v[220:223], v[36:39]
	v_mfma_f32_16x16x32_bf16 v[24:27], v[44:47], v[220:223], v[24:27]
	v_mfma_f32_16x16x32_bf16 v[12:15], v[32:35], v[228:231], v[12:15]
	v_mfma_f32_16x16x32_bf16 v[8:11], v[44:47], v[228:231], v[8:11]
	s_setprio 0
	s_barrier
	v_add_u32_e32 v144, 0x1c000, v178
	ds_read_b128 v[200:203], v190 offset:32768
	ds_read_b128 v[204:207], v190 offset:33792
	ds_read_b128 v[208:211], v190 offset:34816
	ds_read_b128 v[212:215], v190 offset:35840
	ds_read_b128 v[216:219], v190 offset:36864
	ds_read_b128 v[220:223], v190 offset:37888
	ds_read_b128 v[224:227], v190 offset:38912
	ds_read_b128 v[228:231], v190 offset:39936
	ds_read_b128 v[28:31], v144
	ds_read_b128 v[32:35], v144 offset:1024
	ds_read_b128 v[40:43], v144 offset:2048
	ds_read_b128 v[44:47], v144 offset:3072
	s_waitcnt lgkmcnt(0)
	s_barrier
	s_setprio 1
	v_mfma_f32_16x16x32_bf16 v[76:79], v[28:31], v[200:203], v[76:79]
	v_mfma_f32_16x16x32_bf16 v[72:75], v[40:43], v[200:203], v[72:75]
	v_mfma_f32_16x16x32_bf16 v[60:63], v[28:31], v[208:211], v[60:63]
	v_mfma_f32_16x16x32_bf16 v[56:59], v[40:43], v[208:211], v[56:59]
	v_mfma_f32_16x16x32_bf16 v[36:39], v[28:31], v[216:219], v[36:39]
	v_mfma_f32_16x16x32_bf16 v[24:27], v[40:43], v[216:219], v[24:27]
	v_mfma_f32_16x16x32_bf16 v[12:15], v[28:31], v[224:227], v[12:15]
	v_mfma_f32_16x16x32_bf16 v[8:11], v[40:43], v[224:227], v[8:11]
	v_mfma_f32_16x16x32_bf16 v[76:79], v[32:35], v[204:207], v[76:79]
	v_mfma_f32_16x16x32_bf16 v[72:75], v[44:47], v[204:207], v[72:75]
	v_mfma_f32_16x16x32_bf16 v[60:63], v[32:35], v[212:215], v[60:63]
	v_mfma_f32_16x16x32_bf16 v[56:59], v[44:47], v[212:215], v[56:59]
	v_mfma_f32_16x16x32_bf16 v[36:39], v[32:35], v[220:223], v[36:39]
	v_mfma_f32_16x16x32_bf16 v[24:27], v[44:47], v[220:223], v[24:27]
	v_mfma_f32_16x16x32_bf16 v[12:15], v[32:35], v[228:231], v[12:15]
	v_mfma_f32_16x16x32_bf16 v[8:11], v[44:47], v[228:231], v[8:11]
	s_setprio 0
	s_barrier
	s_branch .Lq_lout_exit
.Lq_lout_3_loop:
	s_add_u32 s88, s88, 0x80080
	s_addc_u32 s89, s89, 0
	s_add_u32 s82, s82, 0x80100
	s_addc_u32 s83, s83, 0
	s_waitcnt vmcnt(0)
	s_barrier
	s_barrier
	v_lshl_add_u64 v[176:177], s[88:89], 0, v[160:161]
	s_add_i32 m0, s9, 0xc000
	v_lshl_add_u64 v[232:233], s[88:89], 0, v[162:163]
	global_load_lds_dwordx4 v[176:177], off
	s_add_i32 m0, s9, 0xe000
	s_add_u32 s88, s88, 0x80
	s_addc_u32 s89, s89, 0
	global_load_lds_dwordx4 v[232:233], off
	v_lshl_add_u64 v[176:177], s[88:89], 0, v[160:161]
	s_add_i32 m0, s9, 0x0
	v_lshl_add_u64 v[232:233], s[88:89], 0, v[162:163]
	global_load_lds_dwordx4 v[176:177], off
	s_add_i32 m0, s9, 0x2000
	v_lshl_add_u64 v[234:235], s[82:83], 0, v[160:161]
	global_load_lds_dwordx4 v[232:233], off
	s_add_i32 m0, s9, 0x10000
	v_lshl_add_u64 v[236:237], s[82:83], 0, v[162:163]
	global_load_lds_dwordx4 v[234:235], off
	s_add_i32 m0, s9, 0x12000
	s_add_u32 s88, s88, 0x80
	s_addc_u32 s89, s89, 0
	global_load_lds_dwordx4 v[236:237], off
	s_add_u32 s82, s82, 0x80
	s_addc_u32 s83, s83, 0
	s_mov_b32 s55, 0
.Lq_lout_3_k:
	v_lshl_add_u64 v[176:177], s[88:89], 0, v[160:161]
	s_add_i32 m0, s9, 0x8000
	v_lshl_add_u64 v[232:233], s[88:89], 0, v[162:163]
	global_load_lds_dwordx4 v[176:177], off
	s_add_i32 m0, s9, 0xa000
	v_lshl_add_u64 v[234:235], s[82:83], 0, v[160:161]
	global_load_lds_dwordx4 v[232:233], off
	s_add_i32 m0, s9, 0x18000
	v_lshl_add_u64 v[236:237], s[82:83], 0, v[162:163]
	global_load_lds_dwordx4 v[234:235], off
	s_add_i32 m0, s9, 0x1a000
	s_add_u32 s88, s88, 0x80
	s_addc_u32 s89, s89, 0
	global_load_lds_dwordx4 v[236:237], off
	s_add_u32 s82, s82, 0x80
	s_addc_u32 s83, s83, 0
	v_add_u32_e32 v144, 0x14000, v178
	ds_read_b128 v[200:203], v190 offset:16384
	ds_read_b128 v[204:207], v190 offset:17408
	ds_read_b128 v[208:211], v190 offset:18432
	ds_read_b128 v[212:215], v190 offset:19456
	ds_read_b128 v[216:219], v190 offset:20480
	ds_read_b128 v[220:223], v190 offset:21504
	ds_read_b128 v[224:227], v190 offset:22528
	ds_read_b128 v[228:231], v190 offset:23552
	ds_read_b128 v[168:171], v144
	ds_read_b128 v[172:175], v144 offset:1024
	ds_read_b128 v[192:195], v144 offset:2048
	ds_read_b128 v[196:199], v144 offset:3072
	s_waitcnt vmcnt(8)
	s_waitcnt lgkmcnt(0)
	s_barrier
	s_setprio 1
	v_mfma_f32_16x16x32_bf16 v[20:23], v[168:171], v[216:219], v[20:23]
	v_mfma_f32_16x16x32_bf16 v[16:19], v[192:195], v[216:219], v[16:19]
	v_mfma_f32_16x16x32_bf16 v[4:7], v[168:171], v[224:227], v[4:7]
	v_mfma_f32_16x16x32_bf16 v[0:3], v[192:195], v[224:227], v[0:3]
	v_mfma_f32_16x16x32_bf16 v[68:71], v[168:171], v[200:203], v[68:71]
	v_mfma_f32_16x16x32_bf16 v[64:67], v[192:195], v[200:203], v[64:67]
	v_mfma_f32_16x16x32_bf16 v[52:55], v[168:171], v[208:211], v[52:55]
	v_mfma_f32_16x16x32_bf16 v[48:51], v[192:195], v[208:211], v[48:51]
	v_mfma_f32_16x16x32_bf16 v[20:23], v[172:175], v[220:223], v[20:23]
	v_mfma_f32_16x16x32_bf16 v[16:19], v[196:199], v[220:223], v[16:19]
	v_mfma_f32_16x16x32_bf16 v[4:7], v[172:175], v[228:231], v[4:7]
	v_mfma_f32_16x16x32_bf16 v[0:3], v[196:199], v[228:231], v[0:3]
	v_mfma_f32_16x16x32_bf16 v[68:71], v[172:175], v[204:207], v[68:71]
	v_mfma_f32_16x16x32_bf16 v[64:67], v[196:199], v[204:207], v[64:67]
	v_mfma_f32_16x16x32_bf16 v[52:55], v[172:175], v[212:215], v[52:55]
	v_mfma_f32_16x16x32_bf16 v[48:51], v[196:199], v[212:215], v[48:51]
	s_setprio 0
	s_barrier
	v_lshl_add_u64 v[176:177], s[88:89], 0, v[160:161]
	s_add_i32 m0, s9, 0x4000
	v_lshl_add_u64 v[232:233], s[88:89], 0, v[162:163]
	global_load_lds_dwordx4 v[176:177], off
	s_add_i32 m0, s9, 0x6000
	v_lshl_add_u64 v[234:235], s[82:83], 0, v[160:161]
	global_load_lds_dwordx4 v[232:233], off
	s_add_i32 m0, s9, 0x14000
	v_lshl_add_u64 v[236:237], s[82:83], 0, v[162:163]
	global_load_lds_dwordx4 v[234:235], off
	s_add_i32 m0, s9, 0x16000
	s_add_u32 s88, s88, 0x80
	s_addc_u32 s89, s89, 0
	global_load_lds_dwordx4 v[236:237], off
	s_add_u32 s82, s82, 0x80
	s_addc_u32 s83, s83, 0
	v_add_u32_e32 v144, 0x1c000, v178
	ds_read_b128 v[200:203], v190 offset:49152
	ds_read_b128 v[204:207], v190 offset:50176
	ds_read_b128 v[208:211], v190 offset:51200
	ds_read_b128 v[212:215], v190 offset:52224
	ds_read_b128 v[216:219], v190 offset:53248
	ds_read_b128 v[220:223], v190 offset:54272
	ds_read_b128 v[224:227], v190 offset:55296
	ds_read_b128 v[228:231], v190 offset:56320
	ds_read_b128 v[168:171], v144
	ds_read_b128 v[172:175], v144 offset:1024
	ds_read_b128 v[192:195], v144 offset:2048
	ds_read_b128 v[196:199], v144 offset:3072
	s_waitcnt vmcnt(8)
	s_waitcnt lgkmcnt(0)
	s_barrier
	s_setprio 1
	v_mfma_f32_16x16x32_bf16 v[20:23], v[168:171], v[216:219], v[20:23]
	v_mfma_f32_16x16x32_bf16 v[16:19], v[192:195], v[216:219], v[16:19]
	v_mfma_f32_16x16x32_bf16 v[4:7], v[168:171], v[224:227], v[4:7]
	v_mfma_f32_16x16x32_bf16 v[0:3], v[192:195], v[224:227], v[0:3]
	v_mfma_f32_16x16x32_bf16 v[68:71], v[168:171], v[200:203], v[68:71]
	v_mfma_f32_16x16x32_bf16 v[64:67], v[192:195], v[200:203], v[64:67]
	v_mfma_f32_16x16x32_bf16 v[52:55], v[168:171], v[208:211], v[52:55]
	v_mfma_f32_16x16x32_bf16 v[48:51], v[192:195], v[208:211], v[48:51]
	v_mfma_f32_16x16x32_bf16 v[20:23], v[172:175], v[220:223], v[20:23]
	v_mfma_f32_16x16x32_bf16 v[16:19], v[196:199], v[220:223], v[16:19]
	v_mfma_f32_16x16x32_bf16 v[4:7], v[172:175], v[228:231], v[4:7]
	v_mfma_f32_16x16x32_bf16 v[0:3], v[196:199], v[228:231], v[0:3]
	v_mfma_f32_16x16x32_bf16 v[68:71], v[172:175], v[204:207], v[68:71]
	v_mfma_f32_16x16x32_bf16 v[64:67], v[196:199], v[204:207], v[64:67]
	v_mfma_f32_16x16x32_bf16 v[52:55], v[172:175], v[212:215], v[52:55]
	v_mfma_f32_16x16x32_bf16 v[48:51], v[196:199], v[212:215], v[48:51]
	s_setprio 0
	s_barrier
	v_lshl_add_u64 v[176:177], s[88:89], 0, v[160:161]
	s_add_i32 m0, s9, 0xc000
	v_lshl_add_u64 v[232:233], s[88:89], 0, v[162:163]
	global_load_lds_dwordx4 v[176:177], off
	s_add_i32 m0, s9, 0xe000
	v_lshl_add_u64 v[234:235], s[82:83], 0, v[160:161]
	global_load_lds_dwordx4 v[232:233], off
	s_add_i32 m0, s9, 0x1c000
	v_lshl_add_u64 v[236:237], s[82:83], 0, v[162:163]
	global_load_lds_dwordx4 v[234:235], off
	s_add_i32 m0, s9, 0x1e000
	s_add_u32 s88, s88, 0x80
	s_addc_u32 s89, s89, 0
	global_load_lds_dwordx4 v[236:237], off
	s_add_u32 s82, s82, 0x80
	s_addc_u32 s83, s83, 0
	v_add_u32_e32 v144, 0x10000, v178
	ds_read_b128 v[200:203], v190 offset:0
	ds_read_b128 v[204:207], v190 offset:1024
	ds_read_b128 v[208:211], v190 offset:2048
	ds_read_b128 v[212:215], v190 offset:3072
	ds_read_b128 v[216:219], v190 offset:4096
	ds_read_b128 v[220:223], v190 offset:5120
	ds_read_b128 v[224:227], v190 offset:6144
	ds_read_b128 v[228:231], v190 offset:7168
	ds_read_b128 v[168:171], v144
	ds_read_b128 v[172:175], v144 offset:1024
	ds_read_b128 v[192:195], v144 offset:2048
	ds_read_b128 v[196:199], v144 offset:3072
	s_waitcnt vmcnt(8)
	s_waitcnt lgkmcnt(0)
	s_barrier
	s_setprio 1
	v_mfma_f32_16x16x32_bf16 v[20:23], v[168:171], v[216:219], v[20:23]
	v_mfma_f32_16x16x32_bf16 v[16:19], v[192:195], v[216:219], v[16:19]
	v_mfma_f32_16x16x32_bf16 v[4:7], v[168:171], v[224:227], v[4:7]
	v_mfma_f32_16x16x32_bf16 v[0:3], v[192:195], v[224:227], v[0:3]
	v_mfma_f32_16x16x32_bf16 v[68:71], v[168:171], v[200:203], v[68:71]
	v_mfma_f32_16x16x32_bf16 v[64:67], v[192:195], v[200:203], v[64:67]
	v_mfma_f32_16x16x32_bf16 v[52:55], v[168:171], v[208:211], v[52:55]
	v_mfma_f32_16x16x32_bf16 v[48:51], v[192:195], v[208:211], v[48:51]
	v_mfma_f32_16x16x32_bf16 v[20:23], v[172:175], v[220:223], v[20:23]
	v_mfma_f32_16x16x32_bf16 v[16:19], v[196:199], v[220:223], v[16:19]
	v_mfma_f32_16x16x32_bf16 v[4:7], v[172:175], v[228:231], v[4:7]
	v_mfma_f32_16x16x32_bf16 v[0:3], v[196:199], v[228:231], v[0:3]
	v_mfma_f32_16x16x32_bf16 v[68:71], v[172:175], v[204:207], v[68:71]
	v_mfma_f32_16x16x32_bf16 v[64:67], v[196:199], v[204:207], v[64:67]
	v_mfma_f32_16x16x32_bf16 v[52:55], v[172:175], v[212:215], v[52:55]
	v_mfma_f32_16x16x32_bf16 v[48:51], v[196:199], v[212:215], v[48:51]
	s_setprio 0
	s_barrier
	v_lshl_add_u64 v[176:177], s[88:89], 0, v[160:161]
	s_add_i32 m0, s9, 0x0
	v_lshl_add_u64 v[232:233], s[88:89], 0, v[162:163]
	global_load_lds_dwordx4 v[176:177], off
	s_add_i32 m0, s9, 0x2000
	v_lshl_add_u64 v[234:235], s[82:83], 0, v[160:161]
	global_load_lds_dwordx4 v[232:233], off
	s_add_i32 m0, s9, 0x10000
	v_lshl_add_u64 v[236:237], s[82:83], 0, v[162:163]
	global_load_lds_dwordx4 v[234:235], off
	s_add_i32 m0, s9, 0x12000
	s_add_u32 s88, s88, 0x80
	s_addc_u32 s89, s89, 0
	global_load_lds_dwordx4 v[236:237], off
	s_add_u32 s82, s82, 0x80
	s_addc_u32 s83, s83, 0
	v_add_u32_e32 v144, 0x18000, v178
	ds_read_b128 v[200:203], v190 offset:32768
	ds_read_b128 v[204:207], v190 offset:33792
	ds_read_b128 v[208:211], v190 offset:34816
	ds_read_b128 v[212:215], v190 offset:35840
	ds_read_b128 v[216:219], v190 offset:36864
	ds_read_b128 v[220:223], v190 offset:37888
	ds_read_b128 v[224:227], v190 offset:38912
	ds_read_b128 v[228:231], v190 offset:39936
	ds_read_b128 v[168:171], v144
	ds_read_b128 v[172:175], v144 offset:1024
	ds_read_b128 v[192:195], v144 offset:2048
	ds_read_b128 v[196:199], v144 offset:3072
	s_waitcnt vmcnt(8)
	s_waitcnt lgkmcnt(0)
	s_barrier
	s_setprio 1
	v_mfma_f32_16x16x32_bf16 v[20:23], v[168:171], v[216:219], v[20:23]
	v_mfma_f32_16x16x32_bf16 v[16:19], v[192:195], v[216:219], v[16:19]
	v_mfma_f32_16x16x32_bf16 v[4:7], v[168:171], v[224:227], v[4:7]
	v_mfma_f32_16x16x32_bf16 v[0:3], v[192:195], v[224:227], v[0:3]
	v_mfma_f32_16x16x32_bf16 v[68:71], v[168:171], v[200:203], v[68:71]
	v_mfma_f32_16x16x32_bf16 v[64:67], v[192:195], v[200:203], v[64:67]
	v_mfma_f32_16x16x32_bf16 v[52:55], v[168:171], v[208:211], v[52:55]
	v_mfma_f32_16x16x32_bf16 v[48:51], v[192:195], v[208:211], v[48:51]
	v_mfma_f32_16x16x32_bf16 v[20:23], v[172:175], v[220:223], v[20:23]
	v_mfma_f32_16x16x32_bf16 v[16:19], v[196:199], v[220:223], v[16:19]
	v_mfma_f32_16x16x32_bf16 v[4:7], v[172:175], v[228:231], v[4:7]
	v_mfma_f32_16x16x32_bf16 v[0:3], v[196:199], v[228:231], v[0:3]
	v_mfma_f32_16x16x32_bf16 v[68:71], v[172:175], v[204:207], v[68:71]
	v_mfma_f32_16x16x32_bf16 v[64:67], v[196:199], v[204:207], v[64:67]
	v_mfma_f32_16x16x32_bf16 v[52:55], v[172:175], v[212:215], v[52:55]
	v_mfma_f32_16x16x32_bf16 v[48:51], v[196:199], v[212:215], v[48:51]
	s_setprio 0
	s_barrier
	s_add_i32 s55, s55, 1
	s_cmp_lt_u32 s55, 7
	s_cbranch_scc1 .Lq_lout_3_k
	v_lshl_add_u64 v[176:177], s[88:89], 0, v[160:161]
	s_add_i32 m0, s9, 0x8000
	v_lshl_add_u64 v[232:233], s[88:89], 0, v[162:163]
	global_load_lds_dwordx4 v[176:177], off
	s_add_i32 m0, s9, 0xa000
	v_lshl_add_u64 v[234:235], s[82:83], 0, v[160:161]
	global_load_lds_dwordx4 v[232:233], off
	s_add_i32 m0, s9, 0x18000
	v_lshl_add_u64 v[236:237], s[82:83], 0, v[162:163]
	global_load_lds_dwordx4 v[234:235], off
	s_add_i32 m0, s9, 0x1a000
	s_add_u32 s88, s88, 0x80
	s_addc_u32 s89, s89, 0
	global_load_lds_dwordx4 v[236:237], off
	s_add_u32 s82, s82, 0x80
	s_addc_u32 s83, s83, 0
	v_add_u32_e32 v144, 0x14000, v178
	ds_read_b128 v[200:203], v190 offset:16384
	ds_read_b128 v[204:207], v190 offset:17408
	ds_read_b128 v[208:211], v190 offset:18432
	ds_read_b128 v[212:215], v190 offset:19456
	ds_read_b128 v[216:219], v190 offset:20480
	ds_read_b128 v[220:223], v190 offset:21504
	ds_read_b128 v[224:227], v190 offset:22528
	ds_read_b128 v[228:231], v190 offset:23552
	ds_read_b128 v[168:171], v144
	ds_read_b128 v[172:175], v144 offset:1024
	ds_read_b128 v[192:195], v144 offset:2048
	ds_read_b128 v[196:199], v144 offset:3072
	s_waitcnt vmcnt(8)
	s_waitcnt lgkmcnt(0)
	s_barrier
	s_setprio 1
	v_mfma_f32_16x16x32_bf16 v[20:23], v[168:171], v[216:219], v[20:23]
	v_mfma_f32_16x16x32_bf16 v[16:19], v[192:195], v[216:219], v[16:19]
	v_mfma_f32_16x16x32_bf16 v[4:7], v[168:171], v[224:227], v[4:7]
	v_mfma_f32_16x16x32_bf16 v[0:3], v[192:195], v[224:227], v[0:3]
	v_mfma_f32_16x16x32_bf16 v[68:71], v[168:171], v[200:203], v[68:71]
	v_mfma_f32_16x16x32_bf16 v[64:67], v[192:195], v[200:203], v[64:67]
	v_mfma_f32_16x16x32_bf16 v[52:55], v[168:171], v[208:211], v[52:55]
	v_mfma_f32_16x16x32_bf16 v[48:51], v[192:195], v[208:211], v[48:51]
	v_mfma_f32_16x16x32_bf16 v[20:23], v[172:175], v[220:223], v[20:23]
	v_mfma_f32_16x16x32_bf16 v[16:19], v[196:199], v[220:223], v[16:19]
	v_mfma_f32_16x16x32_bf16 v[4:7], v[172:175], v[228:231], v[4:7]
	v_mfma_f32_16x16x32_bf16 v[0:3], v[196:199], v[228:231], v[0:3]
	v_mfma_f32_16x16x32_bf16 v[68:71], v[172:175], v[204:207], v[68:71]
	v_mfma_f32_16x16x32_bf16 v[64:67], v[196:199], v[204:207], v[64:67]
	v_mfma_f32_16x16x32_bf16 v[52:55], v[172:175], v[212:215], v[52:55]
	v_mfma_f32_16x16x32_bf16 v[48:51], v[196:199], v[212:215], v[48:51]
	s_setprio 0
	s_barrier
	v_add_u32_e32 v144, 0x1c000, v178
	ds_read_b128 v[200:203], v190 offset:49152
	ds_read_b128 v[204:207], v190 offset:50176
	ds_read_b128 v[208:211], v190 offset:51200
	ds_read_b128 v[212:215], v190 offset:52224
	ds_read_b128 v[216:219], v190 offset:53248
	ds_read_b128 v[220:223], v190 offset:54272
	ds_read_b128 v[224:227], v190 offset:55296
	ds_read_b128 v[228:231], v190 offset:56320
	ds_read_b128 v[168:171], v144
	ds_read_b128 v[172:175], v144 offset:1024
	ds_read_b128 v[192:195], v144 offset:2048
	ds_read_b128 v[196:199], v144 offset:3072
	s_waitcnt vmcnt(4)
	s_waitcnt lgkmcnt(0)
	s_barrier
	s_setprio 1
	v_mfma_f32_16x16x32_bf16 v[20:23], v[168:171], v[216:219], v[20:23]
	v_mfma_f32_16x16x32_bf16 v[16:19], v[192:195], v[216:219], v[16:19]
	v_mfma_f32_16x16x32_bf16 v[4:7], v[168:171], v[224:227], v[4:7]
	v_mfma_f32_16x16x32_bf16 v[0:3], v[192:195], v[224:227], v[0:3]
	v_mfma_f32_16x16x32_bf16 v[68:71], v[168:171], v[200:203], v[68:71]
	v_mfma_f32_16x16x32_bf16 v[64:67], v[192:195], v[200:203], v[64:67]
	v_mfma_f32_16x16x32_bf16 v[52:55], v[168:171], v[208:211], v[52:55]
	v_mfma_f32_16x16x32_bf16 v[48:51], v[192:195], v[208:211], v[48:51]
	v_mfma_f32_16x16x32_bf16 v[20:23], v[172:175], v[220:223], v[20:23]
	v_mfma_f32_16x16x32_bf16 v[16:19], v[196:199], v[220:223], v[16:19]
	v_mfma_f32_16x16x32_bf16 v[4:7], v[172:175], v[228:231], v[4:7]
	v_mfma_f32_16x16x32_bf16 v[0:3], v[196:199], v[228:231], v[0:3]
	v_mfma_f32_16x16x32_bf16 v[68:71], v[172:175], v[204:207], v[68:71]
	v_mfma_f32_16x16x32_bf16 v[64:67], v[196:199], v[204:207], v[64:67]
	v_mfma_f32_16x16x32_bf16 v[52:55], v[172:175], v[212:215], v[52:55]
	v_mfma_f32_16x16x32_bf16 v[48:51], v[196:199], v[212:215], v[48:51]
	s_setprio 0
	s_barrier
	v_add_u32_e32 v144, 0x10000, v178
	ds_read_b128 v[200:203], v190 offset:0
	ds_read_b128 v[204:207], v190 offset:1024
	ds_read_b128 v[208:211], v190 offset:2048
	ds_read_b128 v[212:215], v190 offset:3072
	ds_read_b128 v[216:219], v190 offset:4096
	ds_read_b128 v[220:223], v190 offset:5120
	ds_read_b128 v[224:227], v190 offset:6144
	ds_read_b128 v[228:231], v190 offset:7168
	ds_read_b128 v[168:171], v144
	ds_read_b128 v[172:175], v144 offset:1024
	ds_read_b128 v[192:195], v144 offset:2048
	ds_read_b128 v[196:199], v144 offset:3072
	s_waitcnt vmcnt(0)
	s_waitcnt lgkmcnt(0)
	s_barrier
	s_setprio 1
	v_mfma_f32_16x16x32_bf16 v[20:23], v[168:171], v[216:219], v[20:23]
	v_mfma_f32_16x16x32_bf16 v[16:19], v[192:195], v[216:219], v[16:19]
	v_mfma_f32_16x16x32_bf16 v[4:7], v[168:171], v[224:227], v[4:7]
	v_mfma_f32_16x16x32_bf16 v[0:3], v[192:195], v[224:227], v[0:3]
	v_mfma_f32_16x16x32_bf16 v[68:71], v[168:171], v[200:203], v[68:71]
	v_mfma_f32_16x16x32_bf16 v[64:67], v[192:195], v[200:203], v[64:67]
	v_mfma_f32_16x16x32_bf16 v[52:55], v[168:171], v[208:211], v[52:55]
	v_mfma_f32_16x16x32_bf16 v[48:51], v[192:195], v[208:211], v[48:51]
	v_mfma_f32_16x16x32_bf16 v[20:23], v[172:175], v[220:223], v[20:23]
	v_mfma_f32_16x16x32_bf16 v[16:19], v[196:199], v[220:223], v[16:19]
	v_mfma_f32_16x16x32_bf16 v[4:7], v[172:175], v[228:231], v[4:7]
	v_mfma_f32_16x16x32_bf16 v[0:3], v[196:199], v[228:231], v[0:3]
	v_mfma_f32_16x16x32_bf16 v[68:71], v[172:175], v[204:207], v[68:71]
	v_mfma_f32_16x16x32_bf16 v[64:67], v[196:199], v[204:207], v[64:67]
	v_mfma_f32_16x16x32_bf16 v[52:55], v[172:175], v[212:215], v[52:55]
	v_mfma_f32_16x16x32_bf16 v[48:51], v[196:199], v[212:215], v[48:51]
	s_setprio 0
	s_barrier
	v_add_u32_e32 v144, 0x18000, v178
	ds_read_b128 v[200:203], v190 offset:32768
	ds_read_b128 v[204:207], v190 offset:33792
	ds_read_b128 v[208:211], v190 offset:34816
	ds_read_b128 v[212:215], v190 offset:35840
	ds_read_b128 v[216:219], v190 offset:36864
	ds_read_b128 v[220:223], v190 offset:37888
	ds_read_b128 v[224:227], v190 offset:38912
	ds_read_b128 v[228:231], v190 offset:39936
	ds_read_b128 v[168:171], v144
	ds_read_b128 v[172:175], v144 offset:1024
	ds_read_b128 v[192:195], v144 offset:2048
	ds_read_b128 v[196:199], v144 offset:3072
	s_waitcnt lgkmcnt(0)
	s_barrier
	s_setprio 1
	v_mfma_f32_16x16x32_bf16 v[20:23], v[168:171], v[216:219], v[20:23]
	v_mfma_f32_16x16x32_bf16 v[16:19], v[192:195], v[216:219], v[16:19]
	v_mfma_f32_16x16x32_bf16 v[4:7], v[168:171], v[224:227], v[4:7]
	v_mfma_f32_16x16x32_bf16 v[0:3], v[192:195], v[224:227], v[0:3]
	v_mfma_f32_16x16x32_bf16 v[68:71], v[168:171], v[200:203], v[68:71]
	v_mfma_f32_16x16x32_bf16 v[64:67], v[192:195], v[200:203], v[64:67]
	v_mfma_f32_16x16x32_bf16 v[52:55], v[168:171], v[208:211], v[52:55]
	v_mfma_f32_16x16x32_bf16 v[48:51], v[192:195], v[208:211], v[48:51]
	v_mfma_f32_16x16x32_bf16 v[20:23], v[172:175], v[220:223], v[20:23]
	v_mfma_f32_16x16x32_bf16 v[16:19], v[196:199], v[220:223], v[16:19]
	v_mfma_f32_16x16x32_bf16 v[4:7], v[172:175], v[228:231], v[4:7]
	v_mfma_f32_16x16x32_bf16 v[0:3], v[196:199], v[228:231], v[0:3]
	v_mfma_f32_16x16x32_bf16 v[68:71], v[172:175], v[204:207], v[68:71]
	v_mfma_f32_16x16x32_bf16 v[64:67], v[196:199], v[204:207], v[64:67]
	v_mfma_f32_16x16x32_bf16 v[52:55], v[172:175], v[212:215], v[52:55]
	v_mfma_f32_16x16x32_bf16 v[48:51], v[196:199], v[212:215], v[48:51]
	s_setprio 0
	s_barrier
	s_branch .Lq_lout_exit
.Lq_lout_exit:
	s_and_b64 vcc, exec, s[52:53]
	s_cbranch_vccz .LBB0_393
	s_barrier
.LBB0_393:
	v_lshl_or_b32 v168, s4, 8, v179
	s_andn2_b64 vcc, exec, s[20:21]
	v_ashrrev_i32_e32 v169, 31, v168
	s_cbranch_vccnz .LBB0_395
	v_lshl_add_u64 v[28:29], v[168:169], 2, s[34:35]
	global_load_dwordx4 v[44:47], v[28:29], off
	global_load_dwordx4 v[40:43], v[28:29], off offset:64
	global_load_dwordx4 v[32:35], v[28:29], off offset:512
	s_nop 0
	global_load_dwordx4 v[28:31], v[28:29], off offset:576
.LBB0_395:
	v_lshl_add_u32 v170, s72, 8, v146
	v_cmp_lt_i32_e32 vcc, s70, v170
	s_and_saveexec_b64 s[4:5], vcc
	s_xor_b64 s[4:5], exec, s[4:5]
	v_add_u32_e32 v144, 0xffffe000, v170
	v_lshlrev_b64 v[172:173], 13, v[144:145]
	v_mov_b32_e32 v171, v145
	v_lshl_add_u64 v[174:175], s[30:31], 0, v[172:173]
	v_lshlrev_b64 v[176:177], 11, v[170:171]
	s_andn2_saveexec_b64 s[4:5], s[4:5]
	v_ashrrev_i32_e32 v171, 31, v170
	v_lshlrev_b64 v[172:173], 13, v[170:171]
	v_lshlrev_b64 v[176:177], 11, v[170:171]
	v_lshl_add_u64 v[174:175], s[26:27], 0, v[172:173]
	s_or_b64 exec, exec, s[4:5]
	v_lshlrev_b64 v[172:173], 2, v[168:169]
	v_lshl_add_u64 v[174:175], v[174:175], 0, v[172:173]
	v_lshl_add_u64 v[176:177], v[176:177], 2, s[26:27]
	s_mov_b64 s[4:5], -1
	s_and_b64 vcc, exec, s[18:19]
	v_lshl_add_u64 v[176:177], v[176:177], 0, v[172:173]
	s_waitcnt vmcnt(0) lgkmcnt(0)
	s_bitcmp1_b32 s98, 0
	s_cbranch_scc0 .Lqs_lout_0
	global_store_dwordx4 v[176:177], v[140:143], off
.Lqs_lout_0:
	s_cbranch_vccz .LBB0_401
	s_mov_b64 s[4:5], 0
	s_waitcnt lgkmcnt(0)
	s_bitcmp1_b32 s98, 0
	s_cbranch_scc0 .Lqs_lout_1
	global_store_dwordx4 v[176:177], v[136:139], off offset:64
.Lqs_lout_1:
	s_waitcnt lgkmcnt(0)
	s_bitcmp1_b32 s98, 1
	s_cbranch_scc0 .Lqs_lout_2
	global_store_dwordx4 v[176:177], v[132:135], off offset:512
.Lqs_lout_2:
	s_waitcnt lgkmcnt(0)
	s_bitcmp1_b32 s98, 1
	s_cbranch_scc0 .Lqs_lout_3
	global_store_dwordx4 v[176:177], v[128:131], off offset:576
.Lqs_lout_3:
.LBB0_401:
	s_andn2_b64 vcc, exec, s[4:5]
	s_cbranch_vccnz .LBB0_405
	v_mul_f32_e32 v144, v141, v141
	v_fmac_f32_e32 v144, v140, v140
	v_mul_f32_e32 v191, v143, v143
	v_mul_f32_e32 v140, v44, v140
	v_mul_f32_e32 v141, v45, v141
	v_fmac_f32_e32 v191, v142, v142
	v_cvt_pk_bf16_f32 v140, v140, v141
	v_mul_f32_e32 v141, v46, v142
	v_mul_f32_e32 v142, v47, v143
	v_cvt_pk_bf16_f32 v141, v141, v142
	v_lshlrev_b64 v[142:143], 12, v[170:171]
	v_lshl_add_u64 v[142:143], s[28:29], 0, v[142:143]
	v_lshl_add_u64 v[192:193], v[168:169], 1, v[142:143]
	s_bitcmp1_b32 s98, 0
	s_cbranch_scc0 .Lqs_lout_4
	global_store_dwordx2 v[192:193], v[140:141], off
.Lqs_lout_4:
	v_add_f32_e32 v144, v144, v191
	s_waitcnt lgkmcnt(0)
	v_mul_f32_e32 v140, v137, v137
	s_bitcmp1_b32 s98, 0
	s_cbranch_scc0 .Lqs_lout_5
	global_store_dwordx4 v[176:177], v[136:139], off offset:64
.Lqs_lout_5:
	v_fmac_f32_e32 v140, v136, v136
	v_mul_f32_e32 v141, v139, v139
	v_mul_f32_e32 v136, v40, v136
	v_mul_f32_e32 v137, v41, v137
	v_cvt_pk_bf16_f32 v136, v136, v137
	v_mul_f32_e32 v137, v42, v138
	v_fmac_f32_e32 v141, v138, v138
	v_mul_f32_e32 v138, v43, v139
	v_cvt_pk_bf16_f32 v137, v137, v138
	s_bitcmp1_b32 s98, 0
	s_cbranch_scc0 .Lqs_lout_6
	global_store_dwordx2 v[192:193], v[136:137], off offset:32
.Lqs_lout_6:
	v_add_f32_e32 v140, v140, v141
	v_add_f32_e32 v140, v144, v140
	s_waitcnt lgkmcnt(0)
	v_mul_f32_e32 v136, v133, v133
	s_bitcmp1_b32 s98, 1
	s_cbranch_scc0 .Lqs_lout_7
	global_store_dwordx4 v[176:177], v[132:135], off offset:512
.Lqs_lout_7:
	v_fmac_f32_e32 v136, v132, v132
	v_mul_f32_e32 v137, v135, v135
	v_mul_f32_e32 v132, v32, v132
	v_mul_f32_e32 v133, v33, v133
	v_cvt_pk_bf16_f32 v132, v132, v133
	v_mul_f32_e32 v133, v34, v134
	v_fmac_f32_e32 v137, v134, v134
	v_mul_f32_e32 v134, v35, v135
	v_cvt_pk_bf16_f32 v133, v133, v134
	s_bitcmp1_b32 s98, 1
	s_cbranch_scc0 .Lqs_lout_8
	global_store_dwordx2 v[192:193], v[132:133], off offset:256
.Lqs_lout_8:
	v_add_f32_e32 v136, v136, v137
	v_add_f32_e32 v136, v140, v136
	s_waitcnt lgkmcnt(0)
	s_bitcmp1_b32 s98, 1
	s_cbranch_scc0 .Lqs_lout_9
	global_store_dwordx4 v[176:177], v[128:131], off offset:576
.Lqs_lout_9:
	v_mul_f32_e32 v133, v29, v129
	v_mul_f32_e32 v132, v28, v128
	v_mul_f32_e32 v129, v129, v129
	v_fmac_f32_e32 v129, v128, v128
	v_mul_f32_e32 v128, v131, v131
	v_cvt_pk_bf16_f32 v132, v132, v133
	v_mul_f32_e32 v133, v30, v130
	v_fmac_f32_e32 v128, v130, v130
	v_and_b32_e32 v130, 64, v182
	v_add_f32_e32 v128, v129, v128
	v_xor_b32_e32 v129, 16, v182
	v_add_u32_e32 v130, 64, v130
	v_cmp_lt_i32_e32 vcc, v129, v130
	v_add_f32_e32 v128, v136, v128
	v_mul_f32_e32 v134, v31, v131
	v_cndmask_b32_e32 v129, v182, v129, vcc
	v_lshlrev_b32_e32 v129, 2, v129
	ds_bpermute_b32 v129, v129, v128
	v_cvt_pk_bf16_f32 v133, v133, v134
	s_bitcmp1_b32 s98, 1
	s_cbranch_scc0 .Lqs_lout_10
	global_store_dwordx2 v[192:193], v[132:133], off offset:288
.Lqs_lout_10:
	s_waitcnt lgkmcnt(0)
	v_add_f32_e32 v128, v128, v129
	v_xor_b32_e32 v129, 32, v182
	v_cmp_lt_i32_e32 vcc, v129, v130
	s_nop 1
	v_cndmask_b32_e32 v129, v182, v129, vcc
	v_lshlrev_b32_e32 v129, 2, v129
	ds_bpermute_b32 v129, v129, v128
	s_and_saveexec_b64 s[4:5], s[36:37]
	s_cbranch_execz .LBB0_404
	v_lshl_add_u64 v[130:131], v[170:171], 2, s[40:41]
	s_waitcnt lgkmcnt(0)
	v_add_f32_e32 v128, v128, v129
	global_atomic_add_f32 v[130:131], v128, off

.LBB0_405:
	s_waitcnt lgkmcnt(0)
	v_or_b32_e32 v128, 16, v170
	v_cmp_lt_i32_e32 vcc, s70, v128
	s_and_saveexec_b64 s[4:5], vcc
	s_xor_b64 s[4:5], exec, s[4:5]
	v_add_u32_e32 v144, 0xffffe010, v170
	v_lshlrev_b64 v[130:131], 13, v[144:145]
	v_mov_b32_e32 v129, v145
	v_lshl_add_u64 v[130:131], s[30:31], 0, v[130:131]
	v_lshlrev_b64 v[132:133], 11, v[128:129]
	s_andn2_saveexec_b64 s[4:5], s[4:5]
	v_ashrrev_i32_e32 v129, 31, v128
	v_lshlrev_b64 v[130:131], 13, v[128:129]
	v_lshlrev_b64 v[132:133], 11, v[128:129]
	v_lshl_add_u64 v[130:131], s[26:27], 0, v[130:131]
	s_or_b64 exec, exec, s[4:5]
	v_lshl_add_u64 v[130:131], v[130:131], 0, v[172:173]
	v_lshl_add_u64 v[132:133], v[132:133], 2, s[26:27]
	s_mov_b64 s[4:5], -1
	s_and_b64 vcc, exec, s[18:19]
	v_lshl_add_u64 v[132:133], v[132:133], 0, v[172:173]
	s_waitcnt lgkmcnt(0)
	s_bitcmp1_b32 s98, 0
	s_cbranch_scc0 .Lqs_lout_11
	global_store_dwordx4 v[132:133], v[124:127], off
.Lqs_lout_11:
	s_cbranch_vccz .LBB0_411
	s_mov_b64 s[4:5], 0
	s_waitcnt lgkmcnt(0)
	s_bitcmp1_b32 s98, 0
	s_cbranch_scc0 .Lqs_lout_12
	global_store_dwordx4 v[132:133], v[120:123], off offset:64
.Lqs_lout_12:
	s_waitcnt lgkmcnt(0)
	s_bitcmp1_b32 s98, 1
	s_cbranch_scc0 .Lqs_lout_13
	global_store_dwordx4 v[132:133], v[116:119], off offset:512
.Lqs_lout_13:
	s_waitcnt lgkmcnt(0)
	s_bitcmp1_b32 s98, 1
	s_cbranch_scc0 .Lqs_lout_14
	global_store_dwordx4 v[132:133], v[112:115], off offset:576
.Lqs_lout_14:
.LBB0_411:
	s_andn2_b64 vcc, exec, s[4:5]
	s_cbranch_vccnz .LBB0_415
	v_mul_f32_e32 v134, v125, v125
	v_fmac_f32_e32 v134, v124, v124
	v_mul_f32_e32 v135, v127, v127
	v_mul_f32_e32 v124, v44, v124
	v_mul_f32_e32 v125, v45, v125
	v_fmac_f32_e32 v135, v126, v126
	v_cvt_pk_bf16_f32 v124, v124, v125
	v_mul_f32_e32 v125, v46, v126
	v_mul_f32_e32 v126, v47, v127
	v_cvt_pk_bf16_f32 v125, v125, v126
	v_lshlrev_b64 v[126:127], 12, v[128:129]
	v_lshl_add_u64 v[126:127], s[28:29], 0, v[126:127]
	v_add_f32_e32 v136, v134, v135
	v_lshl_add_u64 v[134:135], v[168:169], 1, v[126:127]
	s_bitcmp1_b32 s98, 0
	s_cbranch_scc0 .Lqs_lout_15
	global_store_dwordx2 v[134:135], v[124:125], off
.Lqs_lout_15:
	s_waitcnt lgkmcnt(0)
	v_mul_f32_e32 v124, v121, v121
	s_bitcmp1_b32 s98, 0
	s_cbranch_scc0 .Lqs_lout_16
	global_store_dwordx4 v[132:133], v[120:123], off offset:64
.Lqs_lout_16:
	v_fmac_f32_e32 v124, v120, v120
	v_mul_f32_e32 v125, v123, v123
	v_mul_f32_e32 v120, v40, v120
	v_mul_f32_e32 v121, v41, v121
	v_cvt_pk_bf16_f32 v120, v120, v121
	v_mul_f32_e32 v121, v42, v122
	v_fmac_f32_e32 v125, v122, v122
	v_mul_f32_e32 v122, v43, v123
	v_cvt_pk_bf16_f32 v121, v121, v122
	s_bitcmp1_b32 s98, 0
	s_cbranch_scc0 .Lqs_lout_17
	global_store_dwordx2 v[134:135], v[120:121], off offset:32
.Lqs_lout_17:
	v_add_f32_e32 v124, v124, v125
	v_add_f32_e32 v124, v136, v124
	s_waitcnt lgkmcnt(0)
	v_mul_f32_e32 v120, v117, v117
	s_bitcmp1_b32 s98, 1
	s_cbranch_scc0 .Lqs_lout_18
	global_store_dwordx4 v[132:133], v[116:119], off offset:512
.Lqs_lout_18:
	v_fmac_f32_e32 v120, v116, v116
	v_mul_f32_e32 v121, v119, v119
	v_mul_f32_e32 v116, v32, v116
	v_mul_f32_e32 v117, v33, v117
	v_cvt_pk_bf16_f32 v116, v116, v117
	v_mul_f32_e32 v117, v34, v118
	v_fmac_f32_e32 v121, v118, v118
	v_mul_f32_e32 v118, v35, v119
	v_cvt_pk_bf16_f32 v117, v117, v118
	s_bitcmp1_b32 s98, 1
	s_cbranch_scc0 .Lqs_lout_19
	global_store_dwordx2 v[134:135], v[116:117], off offset:256
.Lqs_lout_19:
	v_add_f32_e32 v120, v120, v121
	v_add_f32_e32 v120, v124, v120
	s_waitcnt lgkmcnt(0)
	s_bitcmp1_b32 s98, 1
	s_cbranch_scc0 .Lqs_lout_20
	global_store_dwordx4 v[132:133], v[112:115], off offset:576
.Lqs_lout_20:
	v_mul_f32_e32 v117, v29, v113
	v_mul_f32_e32 v116, v28, v112
	v_mul_f32_e32 v113, v113, v113
	v_fmac_f32_e32 v113, v112, v112
	v_mul_f32_e32 v112, v115, v115
	v_cvt_pk_bf16_f32 v116, v116, v117
	v_mul_f32_e32 v117, v30, v114
	v_fmac_f32_e32 v112, v114, v114
	v_and_b32_e32 v114, 64, v182
	v_add_f32_e32 v112, v113, v112
	v_xor_b32_e32 v113, 16, v182
	v_add_u32_e32 v114, 64, v114
	v_cmp_lt_i32_e32 vcc, v113, v114
	v_add_f32_e32 v112, v120, v112
	v_mul_f32_e32 v118, v31, v115
	v_cndmask_b32_e32 v113, v182, v113, vcc
	v_lshlrev_b32_e32 v113, 2, v113
	ds_bpermute_b32 v113, v113, v112
	v_cvt_pk_bf16_f32 v117, v117, v118
	s_bitcmp1_b32 s98, 1
	s_cbranch_scc0 .Lqs_lout_21
	global_store_dwordx2 v[134:135], v[116:117], off offset:288
.Lqs_lout_21:
	s_waitcnt lgkmcnt(0)
	v_add_f32_e32 v112, v112, v113
	v_xor_b32_e32 v113, 32, v182
	v_cmp_lt_i32_e32 vcc, v113, v114
	s_nop 1
	v_cndmask_b32_e32 v113, v182, v113, vcc
	v_lshlrev_b32_e32 v113, 2, v113
	ds_bpermute_b32 v113, v113, v112
	s_and_saveexec_b64 s[4:5], s[36:37]
	s_cbranch_execz .LBB0_414
	v_lshl_add_u64 v[114:115], v[128:129], 2, s[40:41]
	s_waitcnt lgkmcnt(0)
	v_add_f32_e32 v112, v112, v113
	global_atomic_add_f32 v[114:115], v112, off

.LBB0_415:
	s_waitcnt lgkmcnt(0)
	v_or_b32_e32 v112, 32, v170
	v_cmp_lt_i32_e32 vcc, s70, v112
	s_and_saveexec_b64 s[4:5], vcc
	s_xor_b64 s[4:5], exec, s[4:5]
	v_add_u32_e32 v144, 0xffffe020, v170
	v_lshlrev_b64 v[114:115], 13, v[144:145]
	v_mov_b32_e32 v113, v145
	v_lshl_add_u64 v[114:115], s[30:31], 0, v[114:115]
	v_lshlrev_b64 v[116:117], 11, v[112:113]
	s_andn2_saveexec_b64 s[4:5], s[4:5]
	v_ashrrev_i32_e32 v113, 31, v112
	v_lshlrev_b64 v[114:115], 13, v[112:113]
	v_lshlrev_b64 v[116:117], 11, v[112:113]
	v_lshl_add_u64 v[114:115], s[26:27], 0, v[114:115]
	s_or_b64 exec, exec, s[4:5]
	v_lshl_add_u64 v[114:115], v[114:115], 0, v[172:173]
	v_lshl_add_u64 v[116:117], v[116:117], 2, s[26:27]
	s_mov_b64 s[4:5], -1
	s_and_b64 vcc, exec, s[18:19]
	v_lshl_add_u64 v[116:117], v[116:117], 0, v[172:173]
	s_waitcnt lgkmcnt(0)
	s_bitcmp1_b32 s98, 0
	s_cbranch_scc0 .Lqs_lout_22
	global_store_dwordx4 v[116:117], v[108:111], off
.Lqs_lout_22:
	s_cbranch_vccz .LBB0_421
	s_mov_b64 s[4:5], 0
	s_waitcnt lgkmcnt(0)
	s_bitcmp1_b32 s98, 0
	s_cbranch_scc0 .Lqs_lout_23
	global_store_dwordx4 v[116:117], v[104:107], off offset:64
.Lqs_lout_23:
	s_waitcnt lgkmcnt(0)
	s_bitcmp1_b32 s98, 1
	s_cbranch_scc0 .Lqs_lout_24
	global_store_dwordx4 v[116:117], v[100:103], off offset:512
.Lqs_lout_24:
	s_waitcnt lgkmcnt(0)
	s_bitcmp1_b32 s98, 1
	s_cbranch_scc0 .Lqs_lout_25
	global_store_dwordx4 v[116:117], v[96:99], off offset:576
.Lqs_lout_25:
.LBB0_421:
	s_andn2_b64 vcc, exec, s[4:5]
	s_cbranch_vccnz .LBB0_425
	v_mul_f32_e32 v118, v109, v109
	v_fmac_f32_e32 v118, v108, v108
	v_mul_f32_e32 v119, v111, v111
	v_mul_f32_e32 v108, v44, v108
	v_mul_f32_e32 v109, v45, v109
	v_fmac_f32_e32 v119, v110, v110
	v_cvt_pk_bf16_f32 v108, v108, v109
	v_mul_f32_e32 v109, v46, v110
	v_mul_f32_e32 v110, v47, v111
	v_cvt_pk_bf16_f32 v109, v109, v110
	v_lshlrev_b64 v[110:111], 12, v[112:113]
	v_lshl_add_u64 v[110:111], s[28:29], 0, v[110:111]
	v_add_f32_e32 v120, v118, v119
	v_lshl_add_u64 v[118:119], v[168:169], 1, v[110:111]
	s_bitcmp1_b32 s98, 0
	s_cbranch_scc0 .Lqs_lout_26
	global_store_dwordx2 v[118:119], v[108:109], off
.Lqs_lout_26:
	s_waitcnt lgkmcnt(0)
	v_mul_f32_e32 v108, v105, v105
	s_bitcmp1_b32 s98, 0
	s_cbranch_scc0 .Lqs_lout_27
	global_store_dwordx4 v[116:117], v[104:107], off offset:64
.Lqs_lout_27:
	v_fmac_f32_e32 v108, v104, v104
	v_mul_f32_e32 v109, v107, v107
	v_mul_f32_e32 v104, v40, v104
	v_mul_f32_e32 v105, v41, v105
	v_cvt_pk_bf16_f32 v104, v104, v105
	v_mul_f32_e32 v105, v42, v106
	v_fmac_f32_e32 v109, v106, v106
	v_mul_f32_e32 v106, v43, v107
	v_cvt_pk_bf16_f32 v105, v105, v106
	s_bitcmp1_b32 s98, 0
	s_cbranch_scc0 .Lqs_lout_28
	global_store_dwordx2 v[118:119], v[104:105], off offset:32
.Lqs_lout_28:
	v_add_f32_e32 v108, v108, v109
	v_add_f32_e32 v108, v120, v108
	s_waitcnt lgkmcnt(0)
	v_mul_f32_e32 v104, v101, v101
	s_bitcmp1_b32 s98, 1
	s_cbranch_scc0 .Lqs_lout_29
	global_store_dwordx4 v[116:117], v[100:103], off offset:512
.Lqs_lout_29:
	v_fmac_f32_e32 v104, v100, v100
	v_mul_f32_e32 v105, v103, v103
	v_mul_f32_e32 v100, v32, v100
	v_mul_f32_e32 v101, v33, v101
	v_cvt_pk_bf16_f32 v100, v100, v101
	v_mul_f32_e32 v101, v34, v102
	v_fmac_f32_e32 v105, v102, v102
	v_mul_f32_e32 v102, v35, v103
	v_cvt_pk_bf16_f32 v101, v101, v102
	s_bitcmp1_b32 s98, 1
	s_cbranch_scc0 .Lqs_lout_30
	global_store_dwordx2 v[118:119], v[100:101], off offset:256
.Lqs_lout_30:
	v_add_f32_e32 v104, v104, v105
	v_add_f32_e32 v104, v108, v104
	s_waitcnt lgkmcnt(0)
	s_bitcmp1_b32 s98, 1
	s_cbranch_scc0 .Lqs_lout_31
	global_store_dwordx4 v[116:117], v[96:99], off offset:576
.Lqs_lout_31:
	v_mul_f32_e32 v101, v29, v97
	v_mul_f32_e32 v100, v28, v96
	v_mul_f32_e32 v97, v97, v97
	v_fmac_f32_e32 v97, v96, v96
	v_mul_f32_e32 v96, v99, v99
	v_cvt_pk_bf16_f32 v100, v100, v101
	v_mul_f32_e32 v101, v30, v98
	v_fmac_f32_e32 v96, v98, v98
	v_and_b32_e32 v98, 64, v182
	v_add_f32_e32 v96, v97, v96
	v_xor_b32_e32 v97, 16, v182
	v_add_u32_e32 v98, 64, v98
	v_cmp_lt_i32_e32 vcc, v97, v98
	v_add_f32_e32 v96, v104, v96
	v_mul_f32_e32 v102, v31, v99
	v_cndmask_b32_e32 v97, v182, v97, vcc
	v_lshlrev_b32_e32 v97, 2, v97
	ds_bpermute_b32 v97, v97, v96
	v_cvt_pk_bf16_f32 v101, v101, v102
	s_bitcmp1_b32 s98, 1
	s_cbranch_scc0 .Lqs_lout_32
	global_store_dwordx2 v[118:119], v[100:101], off offset:288
.Lqs_lout_32:
	s_waitcnt lgkmcnt(0)
	v_add_f32_e32 v96, v96, v97
	v_xor_b32_e32 v97, 32, v182
	v_cmp_lt_i32_e32 vcc, v97, v98
	s_nop 1
	v_cndmask_b32_e32 v97, v182, v97, vcc
	v_lshlrev_b32_e32 v97, 2, v97
	ds_bpermute_b32 v97, v97, v96
	s_and_saveexec_b64 s[4:5], s[36:37]
	s_cbranch_execz .LBB0_424
	v_lshl_add_u64 v[98:99], v[112:113], 2, s[40:41]
	s_waitcnt lgkmcnt(0)
	v_add_f32_e32 v96, v96, v97
	global_atomic_add_f32 v[98:99], v96, off

.LBB0_425:
	s_waitcnt lgkmcnt(0)
	v_or_b32_e32 v96, 48, v170
	v_cmp_lt_i32_e32 vcc, s70, v96
	s_and_saveexec_b64 s[4:5], vcc
	s_xor_b64 s[4:5], exec, s[4:5]
	v_add_u32_e32 v144, 0xffffe030, v170
	v_lshlrev_b64 v[98:99], 13, v[144:145]
	v_mov_b32_e32 v97, v145
	v_lshl_add_u64 v[98:99], s[30:31], 0, v[98:99]
	v_lshlrev_b64 v[100:101], 11, v[96:97]
	s_andn2_saveexec_b64 s[4:5], s[4:5]
	v_ashrrev_i32_e32 v97, 31, v96
	v_lshlrev_b64 v[98:99], 13, v[96:97]
	v_lshlrev_b64 v[100:101], 11, v[96:97]
	v_lshl_add_u64 v[98:99], s[26:27], 0, v[98:99]
	s_or_b64 exec, exec, s[4:5]
	v_lshl_add_u64 v[98:99], v[98:99], 0, v[172:173]
	v_lshl_add_u64 v[100:101], v[100:101], 2, s[26:27]
	s_mov_b64 s[4:5], -1
	s_and_b64 vcc, exec, s[18:19]
	v_lshl_add_u64 v[100:101], v[100:101], 0, v[172:173]
	s_waitcnt lgkmcnt(0)
	s_bitcmp1_b32 s98, 0
	s_cbranch_scc0 .Lqs_lout_33
	global_store_dwordx4 v[100:101], v[92:95], off
.Lqs_lout_33:
	s_cbranch_vccz .LBB0_431
	s_mov_b64 s[4:5], 0
	s_waitcnt lgkmcnt(0)
	s_bitcmp1_b32 s98, 0
	s_cbranch_scc0 .Lqs_lout_34
	global_store_dwordx4 v[100:101], v[88:91], off offset:64
.Lqs_lout_34:
	s_waitcnt lgkmcnt(0)
	s_bitcmp1_b32 s98, 1
	s_cbranch_scc0 .Lqs_lout_35
	global_store_dwordx4 v[100:101], v[84:87], off offset:512
.Lqs_lout_35:
	s_waitcnt lgkmcnt(0)
	s_bitcmp1_b32 s98, 1
	s_cbranch_scc0 .Lqs_lout_36
	global_store_dwordx4 v[100:101], v[80:83], off offset:576
.Lqs_lout_36:
.LBB0_431:
	s_andn2_b64 vcc, exec, s[4:5]
	s_cbranch_vccnz .LBB0_435
	v_mul_f32_e32 v102, v93, v93
	v_fmac_f32_e32 v102, v92, v92
	v_mul_f32_e32 v103, v95, v95
	v_mul_f32_e32 v92, v44, v92
	v_mul_f32_e32 v93, v45, v93
	v_fmac_f32_e32 v103, v94, v94
	v_cvt_pk_bf16_f32 v92, v92, v93
	v_mul_f32_e32 v93, v46, v94
	v_mul_f32_e32 v94, v47, v95
	v_cvt_pk_bf16_f32 v93, v93, v94
	v_lshlrev_b64 v[94:95], 12, v[96:97]
	v_lshl_add_u64 v[94:95], s[28:29], 0, v[94:95]
	v_add_f32_e32 v104, v102, v103
	v_lshl_add_u64 v[102:103], v[168:169], 1, v[94:95]
	s_bitcmp1_b32 s98, 0
	s_cbranch_scc0 .Lqs_lout_37
	global_store_dwordx2 v[102:103], v[92:93], off
.Lqs_lout_37:
	s_waitcnt lgkmcnt(0)
	v_mul_f32_e32 v92, v89, v89
	s_bitcmp1_b32 s98, 0
	s_cbranch_scc0 .Lqs_lout_38
	global_store_dwordx4 v[100:101], v[88:91], off offset:64
.Lqs_lout_38:
	v_fmac_f32_e32 v92, v88, v88
	v_mul_f32_e32 v93, v91, v91
	v_mul_f32_e32 v88, v40, v88
	v_mul_f32_e32 v89, v41, v89
	v_cvt_pk_bf16_f32 v88, v88, v89
	v_mul_f32_e32 v89, v42, v90
	v_fmac_f32_e32 v93, v90, v90
	v_mul_f32_e32 v90, v43, v91
	v_cvt_pk_bf16_f32 v89, v89, v90
	s_bitcmp1_b32 s98, 0
	s_cbranch_scc0 .Lqs_lout_39
	global_store_dwordx2 v[102:103], v[88:89], off offset:32
.Lqs_lout_39:
	v_add_f32_e32 v92, v92, v93
	v_add_f32_e32 v92, v104, v92
	s_waitcnt lgkmcnt(0)
	v_mul_f32_e32 v88, v85, v85
	s_bitcmp1_b32 s98, 1
	s_cbranch_scc0 .Lqs_lout_40
	global_store_dwordx4 v[100:101], v[84:87], off offset:512
.Lqs_lout_40:
	v_fmac_f32_e32 v88, v84, v84
	v_mul_f32_e32 v89, v87, v87
	v_mul_f32_e32 v84, v32, v84
	v_mul_f32_e32 v85, v33, v85
	v_cvt_pk_bf16_f32 v84, v84, v85
	v_mul_f32_e32 v85, v34, v86
	v_fmac_f32_e32 v89, v86, v86
	v_mul_f32_e32 v86, v35, v87
	v_cvt_pk_bf16_f32 v85, v85, v86
	s_bitcmp1_b32 s98, 1
	s_cbranch_scc0 .Lqs_lout_41
	global_store_dwordx2 v[102:103], v[84:85], off offset:256
.Lqs_lout_41:
	v_add_f32_e32 v88, v88, v89
	v_add_f32_e32 v88, v92, v88
	s_waitcnt lgkmcnt(0)
	s_bitcmp1_b32 s98, 1
	s_cbranch_scc0 .Lqs_lout_42
	global_store_dwordx4 v[100:101], v[80:83], off offset:576
.Lqs_lout_42:
	v_mul_f32_e32 v85, v29, v81
	v_mul_f32_e32 v84, v28, v80
	v_mul_f32_e32 v81, v81, v81
	v_fmac_f32_e32 v81, v80, v80
	v_mul_f32_e32 v80, v83, v83
	v_cvt_pk_bf16_f32 v84, v84, v85
	v_mul_f32_e32 v85, v30, v82
	v_fmac_f32_e32 v80, v82, v82
	v_and_b32_e32 v82, 64, v182
	v_add_f32_e32 v80, v81, v80
	v_xor_b32_e32 v81, 16, v182
	v_add_u32_e32 v82, 64, v82
	v_cmp_lt_i32_e32 vcc, v81, v82
	v_add_f32_e32 v80, v88, v80
	v_mul_f32_e32 v86, v31, v83
	v_cndmask_b32_e32 v81, v182, v81, vcc
	v_lshlrev_b32_e32 v81, 2, v81
	ds_bpermute_b32 v81, v81, v80
	v_cvt_pk_bf16_f32 v85, v85, v86
	s_bitcmp1_b32 s98, 1
	s_cbranch_scc0 .Lqs_lout_43
	global_store_dwordx2 v[102:103], v[84:85], off offset:288
.Lqs_lout_43:
	s_waitcnt lgkmcnt(0)
	v_add_f32_e32 v80, v80, v81
	v_xor_b32_e32 v81, 32, v182
	v_cmp_lt_i32_e32 vcc, v81, v82
	s_nop 1
	v_cndmask_b32_e32 v81, v182, v81, vcc
	v_lshlrev_b32_e32 v81, 2, v81
	ds_bpermute_b32 v81, v81, v80
	s_and_saveexec_b64 s[4:5], s[36:37]
	s_cbranch_execz .LBB0_434
	v_lshl_add_u64 v[82:83], v[96:97], 2, s[40:41]
	s_waitcnt lgkmcnt(0)
	v_add_f32_e32 v80, v80, v81
	global_atomic_add_f32 v[82:83], v80, off

.LBB0_435:
	s_movk_i32 s4, 0x1f7f
	s_waitcnt lgkmcnt(0)
	v_add_u32_e32 v80, 0x80, v170
	v_cmp_lt_i32_e32 vcc, s4, v170
	s_and_saveexec_b64 s[4:5], vcc
	s_xor_b64 s[4:5], exec, s[4:5]
	v_add_u32_e32 v144, 0xffffe080, v170
	v_lshlrev_b64 v[82:83], 13, v[144:145]
	v_mov_b32_e32 v81, v145
	v_lshl_add_u64 v[82:83], s[30:31], 0, v[82:83]
	v_lshlrev_b64 v[84:85], 11, v[80:81]
	s_andn2_saveexec_b64 s[4:5], s[4:5]
	v_ashrrev_i32_e32 v81, 31, v80
	v_lshlrev_b64 v[82:83], 13, v[80:81]
	v_lshlrev_b64 v[84:85], 11, v[80:81]
	v_lshl_add_u64 v[82:83], s[26:27], 0, v[82:83]
	s_or_b64 exec, exec, s[4:5]
	v_lshl_add_u64 v[82:83], v[82:83], 0, v[172:173]
	v_lshl_add_u64 v[84:85], v[84:85], 2, s[26:27]
	s_mov_b64 s[4:5], -1
	s_and_b64 vcc, exec, s[18:19]
	v_lshl_add_u64 v[84:85], v[84:85], 0, v[172:173]
	s_waitcnt lgkmcnt(0)
	s_bitcmp1_b32 s98, 2
	s_cbranch_scc0 .Lqs_lout_44
	global_store_dwordx4 v[84:85], v[76:79], off
.Lqs_lout_44:
	s_cbranch_vccz .LBB0_441
	s_mov_b64 s[4:5], 0
	s_waitcnt lgkmcnt(0)
	s_bitcmp1_b32 s98, 2
	s_cbranch_scc0 .Lqs_lout_45
	global_store_dwordx4 v[84:85], v[72:75], off offset:64
.Lqs_lout_45:
	s_waitcnt lgkmcnt(0)
	s_bitcmp1_b32 s98, 3
	s_cbranch_scc0 .Lqs_lout_46
	global_store_dwordx4 v[84:85], v[68:71], off offset:512
.Lqs_lout_46:
	s_waitcnt lgkmcnt(0)
	s_bitcmp1_b32 s98, 3
	s_cbranch_scc0 .Lqs_lout_47
	global_store_dwordx4 v[84:85], v[64:67], off offset:576
.Lqs_lout_47:
.LBB0_441:
	s_andn2_b64 vcc, exec, s[4:5]
	s_cbranch_vccnz .LBB0_445
	v_mul_f32_e32 v86, v77, v77
	v_fmac_f32_e32 v86, v76, v76
	v_mul_f32_e32 v87, v79, v79
	v_mul_f32_e32 v76, v44, v76
	v_mul_f32_e32 v77, v45, v77
	v_fmac_f32_e32 v87, v78, v78
	v_cvt_pk_bf16_f32 v76, v76, v77
	v_mul_f32_e32 v77, v46, v78
	v_mul_f32_e32 v78, v47, v79
	v_cvt_pk_bf16_f32 v77, v77, v78
	v_lshlrev_b64 v[78:79], 12, v[80:81]
	v_lshl_add_u64 v[78:79], s[28:29], 0, v[78:79]
	v_add_f32_e32 v88, v86, v87
	v_lshl_add_u64 v[86:87], v[168:169], 1, v[78:79]
	s_bitcmp1_b32 s98, 2
	s_cbranch_scc0 .Lqs_lout_48
	global_store_dwordx2 v[86:87], v[76:77], off
.Lqs_lout_48:
	s_waitcnt lgkmcnt(0)
	v_mul_f32_e32 v76, v73, v73
	s_bitcmp1_b32 s98, 2
	s_cbranch_scc0 .Lqs_lout_49
	global_store_dwordx4 v[84:85], v[72:75], off offset:64
.Lqs_lout_49:
	v_fmac_f32_e32 v76, v72, v72
	v_mul_f32_e32 v77, v75, v75
	v_mul_f32_e32 v72, v40, v72
	v_mul_f32_e32 v73, v41, v73
	v_cvt_pk_bf16_f32 v72, v72, v73
	v_mul_f32_e32 v73, v42, v74
	v_fmac_f32_e32 v77, v74, v74
	v_mul_f32_e32 v74, v43, v75
	v_cvt_pk_bf16_f32 v73, v73, v74
	s_bitcmp1_b32 s98, 2
	s_cbranch_scc0 .Lqs_lout_50
	global_store_dwordx2 v[86:87], v[72:73], off offset:32
.Lqs_lout_50:
	v_add_f32_e32 v76, v76, v77
	v_add_f32_e32 v76, v88, v76
	s_waitcnt lgkmcnt(0)
	v_mul_f32_e32 v72, v69, v69
	s_bitcmp1_b32 s98, 3
	s_cbranch_scc0 .Lqs_lout_51
	global_store_dwordx4 v[84:85], v[68:71], off offset:512
.Lqs_lout_51:
	v_fmac_f32_e32 v72, v68, v68
	v_mul_f32_e32 v73, v71, v71
	v_mul_f32_e32 v68, v32, v68
	v_mul_f32_e32 v69, v33, v69
	v_cvt_pk_bf16_f32 v68, v68, v69
	v_mul_f32_e32 v69, v34, v70
	v_fmac_f32_e32 v73, v70, v70
	v_mul_f32_e32 v70, v35, v71
	v_cvt_pk_bf16_f32 v69, v69, v70
	s_bitcmp1_b32 s98, 3
	s_cbranch_scc0 .Lqs_lout_52
	global_store_dwordx2 v[86:87], v[68:69], off offset:256
.Lqs_lout_52:
	v_add_f32_e32 v72, v72, v73
	v_add_f32_e32 v72, v76, v72
	s_waitcnt lgkmcnt(0)
	s_bitcmp1_b32 s98, 3
	s_cbranch_scc0 .Lqs_lout_53
	global_store_dwordx4 v[84:85], v[64:67], off offset:576
.Lqs_lout_53:
	v_mul_f32_e32 v69, v29, v65
	v_mul_f32_e32 v68, v28, v64
	v_mul_f32_e32 v65, v65, v65
	v_fmac_f32_e32 v65, v64, v64
	v_mul_f32_e32 v64, v67, v67
	v_cvt_pk_bf16_f32 v68, v68, v69
	v_mul_f32_e32 v69, v30, v66
	v_fmac_f32_e32 v64, v66, v66
	v_and_b32_e32 v66, 64, v182
	v_add_f32_e32 v64, v65, v64
	v_xor_b32_e32 v65, 16, v182
	v_add_u32_e32 v66, 64, v66
	v_cmp_lt_i32_e32 vcc, v65, v66
	v_add_f32_e32 v64, v72, v64
	v_mul_f32_e32 v70, v31, v67
	v_cndmask_b32_e32 v65, v182, v65, vcc
	v_lshlrev_b32_e32 v65, 2, v65
	ds_bpermute_b32 v65, v65, v64
	v_cvt_pk_bf16_f32 v69, v69, v70
	s_bitcmp1_b32 s98, 3
	s_cbranch_scc0 .Lqs_lout_54
	global_store_dwordx2 v[86:87], v[68:69], off offset:288
.Lqs_lout_54:
	s_waitcnt lgkmcnt(0)
	v_add_f32_e32 v64, v64, v65
	v_xor_b32_e32 v65, 32, v182
	v_cmp_lt_i32_e32 vcc, v65, v66
	s_nop 1
	v_cndmask_b32_e32 v65, v182, v65, vcc
	v_lshlrev_b32_e32 v65, 2, v65
	ds_bpermute_b32 v65, v65, v64
	s_and_saveexec_b64 s[4:5], s[36:37]
	s_cbranch_execz .LBB0_444
	v_lshl_add_u64 v[66:67], v[80:81], 2, s[40:41]
	s_waitcnt lgkmcnt(0)
	v_add_f32_e32 v64, v64, v65
	global_atomic_add_f32 v[66:67], v64, off

.LBB0_445:
	s_movk_i32 s4, 0x1f6f
	s_waitcnt lgkmcnt(0)
	v_add_u32_e32 v64, 0x90, v170
	v_cmp_lt_i32_e32 vcc, s4, v170
	s_and_saveexec_b64 s[4:5], vcc
	s_xor_b64 s[4:5], exec, s[4:5]
	v_add_u32_e32 v144, 0xffffe090, v170
	v_lshlrev_b64 v[66:67], 13, v[144:145]
	v_mov_b32_e32 v65, v145
	v_lshl_add_u64 v[66:67], s[30:31], 0, v[66:67]
	v_lshlrev_b64 v[68:69], 11, v[64:65]
	s_andn2_saveexec_b64 s[4:5], s[4:5]
	v_ashrrev_i32_e32 v65, 31, v64
	v_lshlrev_b64 v[66:67], 13, v[64:65]
	v_lshlrev_b64 v[68:69], 11, v[64:65]
	v_lshl_add_u64 v[66:67], s[26:27], 0, v[66:67]
	s_or_b64 exec, exec, s[4:5]
	v_lshl_add_u64 v[66:67], v[66:67], 0, v[172:173]
	v_lshl_add_u64 v[68:69], v[68:69], 2, s[26:27]
	s_mov_b64 s[4:5], -1
	s_and_b64 vcc, exec, s[18:19]
	v_lshl_add_u64 v[68:69], v[68:69], 0, v[172:173]
	s_waitcnt lgkmcnt(0)
	s_bitcmp1_b32 s98, 2
	s_cbranch_scc0 .Lqs_lout_55
	global_store_dwordx4 v[68:69], v[60:63], off
.Lqs_lout_55:
	s_cbranch_vccz .LBB0_451
	s_mov_b64 s[4:5], 0
	s_waitcnt lgkmcnt(0)
	s_bitcmp1_b32 s98, 2
	s_cbranch_scc0 .Lqs_lout_56
	global_store_dwordx4 v[68:69], v[56:59], off offset:64
.Lqs_lout_56:
	s_waitcnt lgkmcnt(0)
	s_bitcmp1_b32 s98, 3
	s_cbranch_scc0 .Lqs_lout_57
	global_store_dwordx4 v[68:69], v[52:55], off offset:512
.Lqs_lout_57:
	s_waitcnt lgkmcnt(0)
	s_bitcmp1_b32 s98, 3
	s_cbranch_scc0 .Lqs_lout_58
	global_store_dwordx4 v[68:69], v[48:51], off offset:576
.Lqs_lout_58:
.LBB0_451:
	s_andn2_b64 vcc, exec, s[4:5]
	s_cbranch_vccnz .LBB0_455
	v_mul_f32_e32 v70, v61, v61
	v_fmac_f32_e32 v70, v60, v60
	v_mul_f32_e32 v71, v63, v63
	v_mul_f32_e32 v60, v44, v60
	v_mul_f32_e32 v61, v45, v61
	v_fmac_f32_e32 v71, v62, v62
	v_cvt_pk_bf16_f32 v60, v60, v61
	v_mul_f32_e32 v61, v46, v62
	v_mul_f32_e32 v62, v47, v63
	v_cvt_pk_bf16_f32 v61, v61, v62
	v_lshlrev_b64 v[62:63], 12, v[64:65]
	v_lshl_add_u64 v[62:63], s[28:29], 0, v[62:63]
	v_add_f32_e32 v72, v70, v71
	v_lshl_add_u64 v[70:71], v[168:169], 1, v[62:63]
	s_bitcmp1_b32 s98, 2
	s_cbranch_scc0 .Lqs_lout_59
	global_store_dwordx2 v[70:71], v[60:61], off
.Lqs_lout_59:
	s_waitcnt lgkmcnt(0)
	v_mul_f32_e32 v60, v57, v57
	s_bitcmp1_b32 s98, 2
	s_cbranch_scc0 .Lqs_lout_60
	global_store_dwordx4 v[68:69], v[56:59], off offset:64
.Lqs_lout_60:
	v_fmac_f32_e32 v60, v56, v56
	v_mul_f32_e32 v61, v59, v59
	v_mul_f32_e32 v56, v40, v56
	v_mul_f32_e32 v57, v41, v57
	v_cvt_pk_bf16_f32 v56, v56, v57
	v_mul_f32_e32 v57, v42, v58
	v_fmac_f32_e32 v61, v58, v58
	v_mul_f32_e32 v58, v43, v59
	v_cvt_pk_bf16_f32 v57, v57, v58
	s_bitcmp1_b32 s98, 2
	s_cbranch_scc0 .Lqs_lout_61
	global_store_dwordx2 v[70:71], v[56:57], off offset:32
.Lqs_lout_61:
	v_add_f32_e32 v60, v60, v61
	v_add_f32_e32 v60, v72, v60
	s_waitcnt lgkmcnt(0)
	v_mul_f32_e32 v56, v53, v53
	s_bitcmp1_b32 s98, 3
	s_cbranch_scc0 .Lqs_lout_62
	global_store_dwordx4 v[68:69], v[52:55], off offset:512
.Lqs_lout_62:
	v_fmac_f32_e32 v56, v52, v52
	v_mul_f32_e32 v57, v55, v55
	v_mul_f32_e32 v52, v32, v52
	v_mul_f32_e32 v53, v33, v53
	v_cvt_pk_bf16_f32 v52, v52, v53
	v_mul_f32_e32 v53, v34, v54
	v_fmac_f32_e32 v57, v54, v54
	v_mul_f32_e32 v54, v35, v55
	v_cvt_pk_bf16_f32 v53, v53, v54
	s_bitcmp1_b32 s98, 3
	s_cbranch_scc0 .Lqs_lout_63
	global_store_dwordx2 v[70:71], v[52:53], off offset:256
.Lqs_lout_63:
	v_add_f32_e32 v56, v56, v57
	v_add_f32_e32 v56, v60, v56
	s_waitcnt lgkmcnt(0)
	s_bitcmp1_b32 s98, 3
	s_cbranch_scc0 .Lqs_lout_64
	global_store_dwordx4 v[68:69], v[48:51], off offset:576
.Lqs_lout_64:
	v_mul_f32_e32 v53, v29, v49
	v_mul_f32_e32 v52, v28, v48
	v_mul_f32_e32 v49, v49, v49
	v_fmac_f32_e32 v49, v48, v48
	v_mul_f32_e32 v48, v51, v51
	v_cvt_pk_bf16_f32 v52, v52, v53
	v_mul_f32_e32 v53, v30, v50
	v_fmac_f32_e32 v48, v50, v50
	v_and_b32_e32 v50, 64, v182
	v_add_f32_e32 v48, v49, v48
	v_xor_b32_e32 v49, 16, v182
	v_add_u32_e32 v50, 64, v50
	v_cmp_lt_i32_e32 vcc, v49, v50
	v_add_f32_e32 v48, v56, v48
	v_mul_f32_e32 v54, v31, v51
	v_cndmask_b32_e32 v49, v182, v49, vcc
	v_lshlrev_b32_e32 v49, 2, v49
	ds_bpermute_b32 v49, v49, v48
	v_cvt_pk_bf16_f32 v53, v53, v54
	s_bitcmp1_b32 s98, 3
	s_cbranch_scc0 .Lqs_lout_65
	global_store_dwordx2 v[70:71], v[52:53], off offset:288
.Lqs_lout_65:
	s_waitcnt lgkmcnt(0)
	v_add_f32_e32 v48, v48, v49
	v_xor_b32_e32 v49, 32, v182
	v_cmp_lt_i32_e32 vcc, v49, v50
	s_nop 1
	v_cndmask_b32_e32 v49, v182, v49, vcc
	v_lshlrev_b32_e32 v49, 2, v49
	ds_bpermute_b32 v49, v49, v48
	s_and_saveexec_b64 s[4:5], s[36:37]
	s_cbranch_execz .LBB0_454
	v_lshl_add_u64 v[50:51], v[64:65], 2, s[40:41]
	s_waitcnt lgkmcnt(0)
	v_add_f32_e32 v48, v48, v49
	global_atomic_add_f32 v[50:51], v48, off

.LBB0_455:
	s_movk_i32 s4, 0x1f5f
	s_waitcnt lgkmcnt(0)
	v_add_u32_e32 v48, 0xa0, v170
	v_cmp_lt_i32_e32 vcc, s4, v170
	s_and_saveexec_b64 s[4:5], vcc
	s_xor_b64 s[4:5], exec, s[4:5]
	v_add_u32_e32 v144, 0xffffe0a0, v170
	v_lshlrev_b64 v[50:51], 13, v[144:145]
	v_mov_b32_e32 v49, v145
	v_lshl_add_u64 v[50:51], s[30:31], 0, v[50:51]
	v_lshlrev_b64 v[52:53], 11, v[48:49]
	s_andn2_saveexec_b64 s[4:5], s[4:5]
	v_ashrrev_i32_e32 v49, 31, v48
	v_lshlrev_b64 v[50:51], 13, v[48:49]
	v_lshlrev_b64 v[52:53], 11, v[48:49]
	v_lshl_add_u64 v[50:51], s[26:27], 0, v[50:51]
	s_or_b64 exec, exec, s[4:5]
	v_lshl_add_u64 v[50:51], v[50:51], 0, v[172:173]
	v_lshl_add_u64 v[52:53], v[52:53], 2, s[26:27]
	s_mov_b64 s[4:5], -1
	s_and_b64 vcc, exec, s[18:19]
	v_lshl_add_u64 v[52:53], v[52:53], 0, v[172:173]
	s_waitcnt lgkmcnt(0)
	s_bitcmp1_b32 s98, 2
	s_cbranch_scc0 .Lqs_lout_66
	global_store_dwordx4 v[52:53], v[36:39], off
.Lqs_lout_66:
	s_cbranch_vccz .LBB0_461
	s_mov_b64 s[4:5], 0
	s_waitcnt lgkmcnt(0)
	s_bitcmp1_b32 s98, 2
	s_cbranch_scc0 .Lqs_lout_67
	global_store_dwordx4 v[52:53], v[24:27], off offset:64
.Lqs_lout_67:
	s_waitcnt lgkmcnt(0)
	s_bitcmp1_b32 s98, 3
	s_cbranch_scc0 .Lqs_lout_68
	global_store_dwordx4 v[52:53], v[20:23], off offset:512
.Lqs_lout_68:
	s_waitcnt lgkmcnt(0)
	s_bitcmp1_b32 s98, 3
	s_cbranch_scc0 .Lqs_lout_69
	global_store_dwordx4 v[52:53], v[16:19], off offset:576
.Lqs_lout_69:
.LBB0_461:
	s_andn2_b64 vcc, exec, s[4:5]
	s_cbranch_vccnz .LBB0_465
	v_mul_f32_e32 v54, v37, v37
	v_fmac_f32_e32 v54, v36, v36
	v_mul_f32_e32 v55, v39, v39
	v_mul_f32_e32 v36, v44, v36
	v_mul_f32_e32 v37, v45, v37
	v_fmac_f32_e32 v55, v38, v38
	v_cvt_pk_bf16_f32 v36, v36, v37
	v_mul_f32_e32 v37, v46, v38
	v_mul_f32_e32 v38, v47, v39
	v_cvt_pk_bf16_f32 v37, v37, v38
	v_lshlrev_b64 v[38:39], 12, v[48:49]
	v_lshl_add_u64 v[38:39], s[28:29], 0, v[38:39]
	v_add_f32_e32 v56, v54, v55
	v_lshl_add_u64 v[54:55], v[168:169], 1, v[38:39]
	s_bitcmp1_b32 s98, 2
	s_cbranch_scc0 .Lqs_lout_70
	global_store_dwordx2 v[54:55], v[36:37], off
.Lqs_lout_70:
	s_waitcnt lgkmcnt(0)
	v_mul_f32_e32 v36, v25, v25
	s_bitcmp1_b32 s98, 2
	s_cbranch_scc0 .Lqs_lout_71
	global_store_dwordx4 v[52:53], v[24:27], off offset:64
.Lqs_lout_71:
	v_fmac_f32_e32 v36, v24, v24
	v_mul_f32_e32 v37, v27, v27
	v_mul_f32_e32 v24, v40, v24
	v_mul_f32_e32 v25, v41, v25
	v_cvt_pk_bf16_f32 v24, v24, v25
	v_mul_f32_e32 v25, v42, v26
	v_fmac_f32_e32 v37, v26, v26
	v_mul_f32_e32 v26, v43, v27
	v_cvt_pk_bf16_f32 v25, v25, v26
	s_bitcmp1_b32 s98, 2
	s_cbranch_scc0 .Lqs_lout_72
	global_store_dwordx2 v[54:55], v[24:25], off offset:32
.Lqs_lout_72:
	v_add_f32_e32 v36, v36, v37
	v_add_f32_e32 v36, v56, v36
	s_waitcnt lgkmcnt(0)
	v_mul_f32_e32 v24, v21, v21
	s_bitcmp1_b32 s98, 3
	s_cbranch_scc0 .Lqs_lout_73
	global_store_dwordx4 v[52:53], v[20:23], off offset:512
.Lqs_lout_73:
	v_fmac_f32_e32 v24, v20, v20
	v_mul_f32_e32 v25, v23, v23
	v_mul_f32_e32 v20, v32, v20
	v_mul_f32_e32 v21, v33, v21
	v_cvt_pk_bf16_f32 v20, v20, v21
	v_mul_f32_e32 v21, v34, v22
	v_fmac_f32_e32 v25, v22, v22
	v_mul_f32_e32 v22, v35, v23
	v_cvt_pk_bf16_f32 v21, v21, v22
	s_bitcmp1_b32 s98, 3
	s_cbranch_scc0 .Lqs_lout_74
	global_store_dwordx2 v[54:55], v[20:21], off offset:256
.Lqs_lout_74:
	v_add_f32_e32 v24, v24, v25
	v_add_f32_e32 v24, v36, v24
	s_waitcnt lgkmcnt(0)
	s_bitcmp1_b32 s98, 3
	s_cbranch_scc0 .Lqs_lout_75
	global_store_dwordx4 v[52:53], v[16:19], off offset:576
.Lqs_lout_75:
	v_mul_f32_e32 v21, v29, v17
	v_mul_f32_e32 v20, v28, v16
	v_mul_f32_e32 v17, v17, v17
	v_fmac_f32_e32 v17, v16, v16
	v_mul_f32_e32 v16, v19, v19
	v_cvt_pk_bf16_f32 v20, v20, v21
	v_mul_f32_e32 v21, v30, v18
	v_fmac_f32_e32 v16, v18, v18
	v_and_b32_e32 v18, 64, v182
	v_add_f32_e32 v16, v17, v16
	v_xor_b32_e32 v17, 16, v182
	v_add_u32_e32 v18, 64, v18
	v_cmp_lt_i32_e32 vcc, v17, v18
	v_add_f32_e32 v16, v24, v16
	v_mul_f32_e32 v22, v31, v19
	v_cndmask_b32_e32 v17, v182, v17, vcc
	v_lshlrev_b32_e32 v17, 2, v17
	ds_bpermute_b32 v17, v17, v16
	v_cvt_pk_bf16_f32 v21, v21, v22
	s_bitcmp1_b32 s98, 3
	s_cbranch_scc0 .Lqs_lout_76
	global_store_dwordx2 v[54:55], v[20:21], off offset:288
.Lqs_lout_76:
	s_waitcnt lgkmcnt(0)
	v_add_f32_e32 v16, v16, v17
	v_xor_b32_e32 v17, 32, v182
	v_cmp_lt_i32_e32 vcc, v17, v18
	s_nop 1
	v_cndmask_b32_e32 v17, v182, v17, vcc
	v_lshlrev_b32_e32 v17, 2, v17
	ds_bpermute_b32 v17, v17, v16
	s_and_saveexec_b64 s[4:5], s[36:37]
	s_cbranch_execz .LBB0_464
	v_lshl_add_u64 v[18:19], v[48:49], 2, s[40:41]
	s_waitcnt lgkmcnt(0)
	v_add_f32_e32 v16, v16, v17
	global_atomic_add_f32 v[18:19], v16, off

.LBB0_465:
	s_movk_i32 s4, 0x1f4f
	s_waitcnt lgkmcnt(0)
	v_add_u32_e32 v16, 0xb0, v170
	v_cmp_lt_i32_e32 vcc, s4, v170
	s_and_saveexec_b64 s[4:5], vcc
	s_xor_b64 s[4:5], exec, s[4:5]
	v_add_u32_e32 v144, 0xffffe0b0, v170
	v_lshlrev_b64 v[18:19], 13, v[144:145]
	v_mov_b32_e32 v17, v145
	v_lshl_add_u64 v[18:19], s[30:31], 0, v[18:19]
	v_lshlrev_b64 v[22:23], 11, v[16:17]
	s_andn2_saveexec_b64 s[4:5], s[4:5]
	v_ashrrev_i32_e32 v17, 31, v16
	v_lshlrev_b64 v[18:19], 13, v[16:17]
	v_lshlrev_b64 v[22:23], 11, v[16:17]
	v_lshl_add_u64 v[18:19], s[26:27], 0, v[18:19]
	s_or_b64 exec, exec, s[4:5]
	v_lshl_add_u64 v[20:21], v[18:19], 0, v[172:173]
	v_lshl_add_u64 v[18:19], v[22:23], 2, s[26:27]
	v_lshl_add_u64 v[18:19], v[18:19], 0, v[172:173]
	s_mov_b64 s[4:5], -1
	s_and_b64 vcc, exec, s[18:19]
	s_waitcnt lgkmcnt(0)
	s_bitcmp1_b32 s98, 2
	s_cbranch_scc0 .Lqs_lout_77
	global_store_dwordx4 v[18:19], v[12:15], off
.Lqs_lout_77:
	s_cbranch_vccnz .LBB0_472
	s_andn2_b64 vcc, exec, s[4:5]
	s_cbranch_vccz .LBB0_473

.LBB0_472:
	s_waitcnt lgkmcnt(0)
	s_bitcmp1_b32 s98, 2
	s_cbranch_scc0 .Lqs_lout_78
	global_store_dwordx4 v[18:19], v[8:11], off offset:64
.Lqs_lout_78:
	s_waitcnt lgkmcnt(0)
	s_bitcmp1_b32 s98, 3
	s_cbranch_scc0 .Lqs_lout_79
	global_store_dwordx4 v[18:19], v[4:7], off offset:512
.Lqs_lout_79:
	s_waitcnt lgkmcnt(0)
	s_bitcmp1_b32 s98, 3
	s_cbranch_scc0 .Lqs_lout_80
	global_store_dwordx4 v[18:19], v[0:3], off offset:576

.LBB0_473:
	s_nop 0
	v_mul_f32_e32 v22, v13, v13
	v_fmac_f32_e32 v22, v12, v12
	v_mul_f32_e32 v23, v15, v15
	v_mul_f32_e32 v12, v44, v12
	v_mul_f32_e32 v13, v45, v13
	v_fmac_f32_e32 v23, v14, v14
	v_cvt_pk_bf16_f32 v12, v12, v13
	v_mul_f32_e32 v13, v46, v14
	v_mul_f32_e32 v14, v47, v15
	v_cvt_pk_bf16_f32 v13, v13, v14
	v_lshlrev_b64 v[14:15], 12, v[16:17]
	v_lshl_add_u64 v[14:15], s[28:29], 0, v[14:15]
	v_add_f32_e32 v24, v22, v23
	v_lshl_add_u64 v[22:23], v[168:169], 1, v[14:15]
	s_bitcmp1_b32 s98, 2
	s_cbranch_scc0 .Lqs_lout_81
	global_store_dwordx2 v[22:23], v[12:13], off
.Lqs_lout_81:
	s_waitcnt lgkmcnt(0)
	v_mul_f32_e32 v12, v9, v9
	s_bitcmp1_b32 s98, 2
	s_cbranch_scc0 .Lqs_lout_82
	global_store_dwordx4 v[18:19], v[8:11], off offset:64
.Lqs_lout_82:
	v_fmac_f32_e32 v12, v8, v8
	v_mul_f32_e32 v13, v11, v11
	v_mul_f32_e32 v8, v40, v8
	v_mul_f32_e32 v9, v41, v9
	v_cvt_pk_bf16_f32 v8, v8, v9
	v_mul_f32_e32 v9, v42, v10
	v_fmac_f32_e32 v13, v10, v10
	v_mul_f32_e32 v10, v43, v11
	v_cvt_pk_bf16_f32 v9, v9, v10
	s_bitcmp1_b32 s98, 2
	s_cbranch_scc0 .Lqs_lout_83
	global_store_dwordx2 v[22:23], v[8:9], off offset:32
.Lqs_lout_83:
	v_add_f32_e32 v12, v12, v13
	v_add_f32_e32 v12, v24, v12
	s_waitcnt lgkmcnt(0)
	v_mul_f32_e32 v8, v5, v5
	s_bitcmp1_b32 s98, 3
	s_cbranch_scc0 .Lqs_lout_84
	global_store_dwordx4 v[18:19], v[4:7], off offset:512
.Lqs_lout_84:
	v_fmac_f32_e32 v8, v4, v4
	v_mul_f32_e32 v9, v7, v7
	v_mul_f32_e32 v4, v32, v4
	v_mul_f32_e32 v5, v33, v5
	v_cvt_pk_bf16_f32 v4, v4, v5
	v_mul_f32_e32 v5, v34, v6
	v_fmac_f32_e32 v9, v6, v6
	v_mul_f32_e32 v6, v35, v7
	v_cvt_pk_bf16_f32 v5, v5, v6
	s_bitcmp1_b32 s98, 3
	s_cbranch_scc0 .Lqs_lout_85
	global_store_dwordx2 v[22:23], v[4:5], off offset:256
.Lqs_lout_85:
	v_add_f32_e32 v8, v8, v9
	v_add_f32_e32 v8, v12, v8
	s_waitcnt lgkmcnt(0)
	s_bitcmp1_b32 s98, 3
	s_cbranch_scc0 .Lqs_lout_86
	global_store_dwordx4 v[18:19], v[0:3], off offset:576
.Lqs_lout_86:
	v_mul_f32_e32 v5, v29, v1
	v_mul_f32_e32 v4, v28, v0
	v_mul_f32_e32 v1, v1, v1
	v_fmac_f32_e32 v1, v0, v0
	v_mul_f32_e32 v0, v3, v3
	v_cvt_pk_bf16_f32 v4, v4, v5
	v_mul_f32_e32 v5, v30, v2
	v_fmac_f32_e32 v0, v2, v2
	v_and_b32_e32 v2, 64, v182
	v_add_f32_e32 v0, v1, v0
	v_xor_b32_e32 v1, 16, v182
	v_add_u32_e32 v2, 64, v2
	v_cmp_lt_i32_e32 vcc, v1, v2
	v_add_f32_e32 v0, v8, v0
	v_mul_f32_e32 v6, v31, v3
	v_cndmask_b32_e32 v1, v182, v1, vcc
	v_lshlrev_b32_e32 v1, 2, v1
	ds_bpermute_b32 v1, v1, v0
	v_cvt_pk_bf16_f32 v5, v5, v6
	s_bitcmp1_b32 s98, 3
	s_cbranch_scc0 .Lqs_lout_87
	flat_store_dwordx2 v[22:23], v[4:5] offset:288
.Lqs_lout_87:
	s_waitcnt lgkmcnt(0)
	v_add_f32_e32 v0, v0, v1
	v_xor_b32_e32 v1, 32, v182
	v_cmp_lt_i32_e32 vcc, v1, v2
	s_nop 1
	v_cndmask_b32_e32 v1, v182, v1, vcc
	v_lshlrev_b32_e32 v1, 2, v1
	ds_bpermute_b32 v1, v1, v0
	s_and_saveexec_b64 s[4:5], s[36:37]
	s_cbranch_execz .LBB0_475
	v_lshl_add_u64 v[2:3], v[16:17], 2, s[40:41]
	s_waitcnt lgkmcnt(0)
	v_add_f32_e32 v0, v0, v1
	flat_atomic_add_f32 v[2:3], v0
